# w13+w2+res gemm LDS-DMA loops, rcp sigmoid, scan_unit prefetched pk loop, permlane swaps
# speedup vs baseline: 1.0312x; 1.0312x over previous
.LBB0_62:
	s_ashr_i32 s22, s1, 31
	s_lshr_b32 s22, s22, 27
	s_add_i32 s22, s1, s22
	s_and_b32 s23, s22, 0xffffe0
	s_sub_i32 s23, s1, s23
	s_lshl_b32 s40, s23, 8
	s_lshl_b32 s22, s22, 2
	s_ashr_i32 s41, s40, 31
	s_and_b32 s44, s22, 0xffffff80
	v_readlane_b32 s4, v254, 0
	s_ashr_i32 s45, s44, 31
	s_lshl_b64 s[22:23], s[40:41], 11
	v_readlane_b32 s6, v254, 2
	v_readlane_b32 s7, v254, 3
	s_add_u32 s22, s6, s22
	s_addc_u32 s23, s7, s23
	s_lshl_b64 s[4:5], s[44:45], 11
	s_add_u32 s4, s20, s4
	s_addc_u32 s5, s21, s5
	s_waitcnt lgkmcnt(0)
	v_lshrrev_b32_e32 v132, 3, v196
	v_lshrrev_b32_e32 v133, 4, v196
	v_xor_b32_e32 v133, v133, v196
	v_and_b32_e32 v133, 7, v133
	v_lshlrev_b32_e32 v133, 4, v133
	v_lshl_or_b32 v82, v132, 11, v133
	v_add_u32_e32 v83, 0x20000, v82
	v_add_u32_e32 v84, 0x40000, v82
	v_add_u32_e32 v85, 0x60000, v82
	v_add_u32_e32 v132, 0, v140
	v_xor_b32_e32 v132, v132, v141
	v_lshlrev_b32_e32 v132, 4, v132
	v_add3_u32 v86, v150, v132, 0
	v_add3_u32 v128, v151, v132, 0
	v_add_u32_e32 v132, 2, v140
	v_xor_b32_e32 v132, v132, v141
	v_lshlrev_b32_e32 v132, 4, v132
	v_add3_u32 v87, v150, v132, 0
	v_add3_u32 v129, v151, v132, 0
	v_add_u32_e32 v132, 4, v140
	v_xor_b32_e32 v132, v132, v141
	v_lshlrev_b32_e32 v132, 4, v132
	v_add3_u32 v88, v150, v132, 0
	v_add3_u32 v130, v151, v132, 0
	v_add_u32_e32 v132, 6, v140
	v_xor_b32_e32 v132, v132, v141
	v_lshlrev_b32_e32 v132, 4, v132
	v_add3_u32 v89, v150, v132, 0
	v_add3_u32 v131, v151, v132, 0
	v_lshrrev_b32_e32 v132, 6, v196
	v_mov_b64_e32 v[2:3], 0
	v_mov_b64_e32 v[4:5], 0
	v_mov_b64_e32 v[6:7], 0
	v_mov_b64_e32 v[8:9], 0
	v_mov_b64_e32 v[10:11], 0
	v_mov_b64_e32 v[12:13], 0
	v_mov_b64_e32 v[14:15], 0
	v_mov_b64_e32 v[16:17], 0
	v_mov_b64_e32 v[18:19], 0
	v_mov_b64_e32 v[20:21], 0
	v_mov_b64_e32 v[22:23], 0
	v_mov_b64_e32 v[24:25], 0
	v_mov_b64_e32 v[26:27], 0
	v_mov_b64_e32 v[28:29], 0
	v_mov_b64_e32 v[30:31], 0
	v_mov_b64_e32 v[32:33], 0
	v_mov_b64_e32 v[34:35], 0
	v_mov_b64_e32 v[36:37], 0
	v_mov_b64_e32 v[38:39], 0
	v_mov_b64_e32 v[40:41], 0
	v_mov_b64_e32 v[42:43], 0
	v_mov_b64_e32 v[44:45], 0
	v_mov_b64_e32 v[46:47], 0
	v_mov_b64_e32 v[48:49], 0
	v_mov_b64_e32 v[50:51], 0
	v_mov_b64_e32 v[52:53], 0
	v_mov_b64_e32 v[54:55], 0
	v_mov_b64_e32 v[56:57], 0
	v_mov_b64_e32 v[58:59], 0
	v_mov_b64_e32 v[60:61], 0
	v_mov_b64_e32 v[62:63], 0
	v_mov_b64_e32 v[64:65], 0
	v_readfirstlane_b32 s10, v132
	s_lshl_b32 s10, s10, 10
	s_add_i32 s10, s10, 16
	s_add_i32 vcc_hi, s10, 0xc000
	s_mov_b32 m0, s10
	s_nop 0
	global_load_lds_dwordx4 v82, s[22:23]
	s_add_u32 m0, m0, 0x2000
	s_nop 0
	global_load_lds_dwordx4 v83, s[22:23]
	s_add_u32 m0, m0, 0x2000
	s_nop 0
	global_load_lds_dwordx4 v84, s[22:23]
	s_add_u32 m0, m0, 0x2000
	s_nop 0
	global_load_lds_dwordx4 v85, s[22:23]
	s_add_u32 m0, m0, 0x2000
	s_nop 0
	global_load_lds_dwordx4 v82, s[4:5]
	s_add_u32 m0, m0, 0x2000
	s_nop 0
	global_load_lds_dwordx4 v83, s[4:5]
	s_add_u32 s22, s22, 0x80
	s_addc_u32 s23, s23, 0
	s_add_u32 s4, s4, 0x80
	s_addc_u32 s5, s5, 0
	s_mov_b32 m0, vcc_hi
	s_nop 0
	global_load_lds_dwordx4 v82, s[22:23]
	s_add_u32 m0, m0, 0x2000
	s_nop 0
	global_load_lds_dwordx4 v83, s[22:23]
	s_add_u32 m0, m0, 0x2000
	s_nop 0
	global_load_lds_dwordx4 v84, s[22:23]
	s_add_u32 m0, m0, 0x2000
	s_nop 0
	global_load_lds_dwordx4 v85, s[22:23]
	s_add_u32 m0, m0, 0x2000
	s_nop 0
	global_load_lds_dwordx4 v82, s[4:5]
	s_add_u32 m0, m0, 0x2000
	s_nop 0
	global_load_lds_dwordx4 v83, s[4:5]
	s_add_u32 s22, s22, 0x80
	s_addc_u32 s23, s23, 0
	s_add_u32 s4, s4, 0x80
	s_addc_u32 s5, s5, 0
	s_mov_b32 s9, 0
	s_movk_i32 s8, 15
.Lres_loop:
	s_waitcnt vmcnt(6)
	s_barrier
	ds_read_b128 v[154:157], v86
	ds_read_b128 v[158:161], v86 offset:4096
	ds_read_b128 v[162:165], v128 offset:32768
	ds_read_b128 v[166:169], v128 offset:36864
	s_cmp_lt_u32 s8, 2
	s_cbranch_scc1 .Lres_skipdma
	s_add_i32 vcc_hi, s9, 2
	s_cmp_ge_u32 vcc_hi, 3
	s_cselect_b32 vcc_lo, 3, 0
	s_sub_i32 vcc_hi, vcc_hi, vcc_lo
	s_mul_i32 vcc_hi, vcc_hi, 0xc000
	s_add_i32 vcc_hi, vcc_hi, s10
	s_mov_b32 m0, vcc_hi
	s_nop 0
	global_load_lds_dwordx4 v82, s[22:23]
	s_add_u32 m0, m0, 0x2000
	s_nop 0
	global_load_lds_dwordx4 v83, s[22:23]
	s_add_u32 m0, m0, 0x2000
	s_nop 0
	global_load_lds_dwordx4 v84, s[22:23]
	s_add_u32 m0, m0, 0x2000
	s_nop 0
	global_load_lds_dwordx4 v85, s[22:23]
	s_add_u32 m0, m0, 0x2000
	s_nop 0
	global_load_lds_dwordx4 v82, s[4:5]
	s_add_u32 m0, m0, 0x2000
	s_nop 0
	global_load_lds_dwordx4 v83, s[4:5]
	s_add_u32 s22, s22, 0x80
	s_addc_u32 s23, s23, 0
	s_add_u32 s4, s4, 0x80
	s_addc_u32 s5, s5, 0
.Lres_skipdma:
	ds_read_b128 v[66:69], v87
	ds_read_b128 v[70:73], v87 offset:4096
	ds_read_b128 v[74:77], v129 offset:32768
	ds_read_b128 v[78:81], v129 offset:36864
	s_waitcnt lgkmcnt(4)
	s_setprio 1
	v_mfma_f32_32x32x16_bf16 v[50:65], v[154:157], v[162:165], v[50:65]
	v_mfma_f32_32x32x16_bf16 v[18:33], v[158:161], v[162:165], v[18:33]
	v_mfma_f32_32x32x16_bf16 v[34:49], v[154:157], v[166:169], v[34:49]
	v_mfma_f32_32x32x16_bf16 v[2:17], v[158:161], v[166:169], v[2:17]
	s_setprio 0
	ds_read_b128 v[154:157], v88
	ds_read_b128 v[158:161], v88 offset:4096
	ds_read_b128 v[162:165], v130 offset:32768
	ds_read_b128 v[166:169], v130 offset:36864
	s_waitcnt lgkmcnt(4)
	s_setprio 1
	v_mfma_f32_32x32x16_bf16 v[50:65], v[66:69], v[74:77], v[50:65]
	v_mfma_f32_32x32x16_bf16 v[18:33], v[70:73], v[74:77], v[18:33]
	v_mfma_f32_32x32x16_bf16 v[34:49], v[66:69], v[78:81], v[34:49]
	v_mfma_f32_32x32x16_bf16 v[2:17], v[70:73], v[78:81], v[2:17]
	s_setprio 0
	ds_read_b128 v[66:69], v89
	ds_read_b128 v[70:73], v89 offset:4096
	ds_read_b128 v[74:77], v131 offset:32768
	ds_read_b128 v[78:81], v131 offset:36864
	s_waitcnt lgkmcnt(4)
	s_setprio 1
	v_mfma_f32_32x32x16_bf16 v[50:65], v[154:157], v[162:165], v[50:65]
	v_mfma_f32_32x32x16_bf16 v[18:33], v[158:161], v[162:165], v[18:33]
	v_mfma_f32_32x32x16_bf16 v[34:49], v[154:157], v[166:169], v[34:49]
	v_mfma_f32_32x32x16_bf16 v[2:17], v[158:161], v[166:169], v[2:17]
	s_setprio 0
	s_waitcnt lgkmcnt(0)
	s_setprio 1
	v_mfma_f32_32x32x16_bf16 v[50:65], v[66:69], v[74:77], v[50:65]
	v_mfma_f32_32x32x16_bf16 v[18:33], v[70:73], v[74:77], v[18:33]
	v_mfma_f32_32x32x16_bf16 v[34:49], v[66:69], v[78:81], v[34:49]
	v_mfma_f32_32x32x16_bf16 v[2:17], v[70:73], v[78:81], v[2:17]
	s_setprio 0
	s_add_i32 s9, s9, 1
	s_cmp_eq_u32 s9, 3
	s_cselect_b32 vcc_lo, 0xfffdc000, 0
	s_cselect_b32 s9, 0, s9
	s_add_i32 vcc_lo, vcc_lo, 0xc000
	v_add_u32_e32 v86, vcc_lo, v86
	v_add_u32_e32 v128, vcc_lo, v128
	v_add_u32_e32 v87, vcc_lo, v87
	v_add_u32_e32 v129, vcc_lo, v129
	v_add_u32_e32 v88, vcc_lo, v88
	v_add_u32_e32 v130, vcc_lo, v130
	v_add_u32_e32 v89, vcc_lo, v89
	v_add_u32_e32 v131, vcc_lo, v131
	s_add_i32 s8, s8, -1
	s_cmp_lg_u32 s8, 0
	s_cbranch_scc1 .Lres_loop
	s_waitcnt vmcnt(0)
	s_barrier
	ds_read_b128 v[154:157], v86
	ds_read_b128 v[158:161], v86 offset:4096
	ds_read_b128 v[162:165], v128 offset:32768
	ds_read_b128 v[166:169], v128 offset:36864
	ds_read_b128 v[66:69], v87
	ds_read_b128 v[70:73], v87 offset:4096
	ds_read_b128 v[74:77], v129 offset:32768
	ds_read_b128 v[78:81], v129 offset:36864
	s_waitcnt lgkmcnt(4)
	s_setprio 1
	v_mfma_f32_32x32x16_bf16 v[50:65], v[154:157], v[162:165], v[50:65]
	v_mfma_f32_32x32x16_bf16 v[18:33], v[158:161], v[162:165], v[18:33]
	v_mfma_f32_32x32x16_bf16 v[34:49], v[154:157], v[166:169], v[34:49]
	v_mfma_f32_32x32x16_bf16 v[2:17], v[158:161], v[166:169], v[2:17]
	s_setprio 0
	ds_read_b128 v[154:157], v88
	ds_read_b128 v[158:161], v88 offset:4096
	ds_read_b128 v[162:165], v130 offset:32768
	ds_read_b128 v[166:169], v130 offset:36864
	s_waitcnt lgkmcnt(4)
	s_setprio 1
	v_mfma_f32_32x32x16_bf16 v[50:65], v[66:69], v[74:77], v[50:65]
	v_mfma_f32_32x32x16_bf16 v[18:33], v[70:73], v[74:77], v[18:33]
	v_mfma_f32_32x32x16_bf16 v[34:49], v[66:69], v[78:81], v[34:49]
	v_mfma_f32_32x32x16_bf16 v[2:17], v[70:73], v[78:81], v[2:17]
	s_setprio 0
	ds_read_b128 v[66:69], v89
	ds_read_b128 v[70:73], v89 offset:4096
	ds_read_b128 v[74:77], v131 offset:32768
	ds_read_b128 v[78:81], v131 offset:36864
	s_waitcnt lgkmcnt(4)
	s_setprio 1
	v_mfma_f32_32x32x16_bf16 v[50:65], v[154:157], v[162:165], v[50:65]
	v_mfma_f32_32x32x16_bf16 v[18:33], v[158:161], v[162:165], v[18:33]
	v_mfma_f32_32x32x16_bf16 v[34:49], v[154:157], v[166:169], v[34:49]
	v_mfma_f32_32x32x16_bf16 v[2:17], v[158:161], v[166:169], v[2:17]
	s_setprio 0
	s_waitcnt lgkmcnt(0)
	s_setprio 1
	v_mfma_f32_32x32x16_bf16 v[50:65], v[66:69], v[74:77], v[50:65]
	v_mfma_f32_32x32x16_bf16 v[18:33], v[70:73], v[74:77], v[18:33]
	v_mfma_f32_32x32x16_bf16 v[34:49], v[66:69], v[78:81], v[34:49]
	v_mfma_f32_32x32x16_bf16 v[2:17], v[70:73], v[78:81], v[2:17]
	s_setprio 0
	s_barrier
	v_readlane_b32 s4, v254, 0
	v_readlane_b32 s5, v254, 1
	v_readlane_b32 s8, v254, 4
	v_readlane_b32 s9, v254, 5
	v_readlane_b32 s10, v254, 6
	v_readlane_b32 s11, v254, 7
	v_readlane_b32 s12, v254, 8
	v_readlane_b32 s13, v254, 9
	v_readlane_b32 s14, v254, 10
	v_readlane_b32 s15, v254, 11
	v_readlane_b32 s16, v254, 12
	v_readlane_b32 s17, v254, 13
	v_readlane_b32 s18, v254, 14
	v_readlane_b32 s19, v254, 15
	s_nop 7
	v_add_u32_e32 v70, s40, v142
	v_add_u32_e32 v66, 0xfffff000, v70
	v_lshrrev_b32_e32 v66, 11, v66
	s_movk_i32 s4, 0x1800
	v_mad_u32_u24 v76, v66, s4, s4
	s_movk_i32 s4, 0xfff
	v_cmp_lt_i32_e32 vcc, s4, v70
	v_or_b32_e32 v68, s44, v143
	s_nop 0
	v_cndmask_b32_e32 v78, 0, v76, vcc
	v_add_u32_e32 v66, v78, v68
	v_ashrrev_i32_e32 v67, 31, v66
	v_lshl_add_u64 v[66:67], v[66:67], 2, s[28:29]
	s_barrier
	global_load_dword v79, v[66:67], off
	v_readlane_b32 s4, v252, 14
	v_ashrrev_i32_e32 v69, 31, v68
	v_readlane_b32 s5, v252, 15
	v_lshl_add_u64 v[66:67], v[68:69], 2, s[42:43]
	v_mov_b32_e32 v77, 0
	s_and_b64 vcc, exec, s[4:5]
	v_mov_b32_e32 v80, 0
	s_cbranch_vccz .LBB0_96
	global_load_dword v80, v[66:67], off

.LBB0_507:
	ds_read_b128 v[2:5], v14
	ds_read_b128 v[6:9], v14 offset:32
	v_add_u32_e32 v173, s30, v129
	s_waitcnt lgkmcnt(1)
	v_mfma_f32_32x32x16_bf16 v[80:95], v[2:5], v[96:99], 0
	v_mov_b32_e32 v3, v133
	v_max_f32_e32 v4, v3, v3
	s_waitcnt lgkmcnt(0)
	v_mfma_f32_32x32x16_bf16 v[80:95], v[6:9], v[100:103], v[80:95]
	s_nop 11
	v_max_f32_e32 v0, v81, v81
	v_max_f32_e32 v2, v80, v80
	v_max_f32_e32 v0, v2, v0
	v_max3_f32 v0, v0, v82, v83
	v_max3_f32 v0, v0, v84, v85
	v_max3_f32 v0, v0, v86, v87
	v_max3_f32 v0, v0, v88, v89
	v_max3_f32 v0, v0, v90, v91
	v_max3_f32 v0, v0, v92, v93
	v_max3_f32 v0, v0, v94, v95
	v_mov_b32_e32 v2, v0
	s_nop 1
	v_permlane32_swap_b32_e32 v0, v2
	s_waitcnt lgkmcnt(0)
	v_max_f32_e32 v2, v2, v2
	v_max_f32_e32 v0, v0, v2
	v_mul_f32_e32 v0, 0x3e8293ee, v0
	v_max_f32_e32 v133, v4, v0
	v_sub_f32_e32 v0, v3, v133
	v_exp_f32_e32 v0, v0
	ds_read2_b64 v[2:5], v173 offset1:2
	ds_read2_b64 v[6:9], v173 offset0:4 offset1:6
	v_cmp_neq_f32_e32 vcc, 1.0, v0
	s_cmp_lg_u64 vcc, 0
	s_cselect_b64 s[20:21], -1, 0
	s_cbranch_vccz .LBB0_509
	v_pk_mul_f32 v[62:63], v[62:63], v[0:1] op_sel_hi:[1,0]
	v_pk_mul_f32 v[60:61], v[60:61], v[0:1] op_sel_hi:[1,0]
	v_pk_mul_f32 v[58:59], v[58:59], v[0:1] op_sel_hi:[1,0]
	v_pk_mul_f32 v[56:57], v[56:57], v[0:1] op_sel_hi:[1,0]
	v_pk_mul_f32 v[54:55], v[54:55], v[0:1] op_sel_hi:[1,0]
	v_pk_mul_f32 v[52:53], v[52:53], v[0:1] op_sel_hi:[1,0]
	v_pk_mul_f32 v[50:51], v[50:51], v[0:1] op_sel_hi:[1,0]
	v_pk_mul_f32 v[48:49], v[48:49], v[0:1] op_sel_hi:[1,0]

.LBB0_515:
	v_mov_b32_e32 v0, v2
	s_nop 1
	v_permlane32_swap_b32_e32 v2, v0
	s_waitcnt lgkmcnt(0)
	s_barrier
	v_add_f32_e32 v0, v2, v0
	v_div_scale_f32 v2, s[20:21], v0, v0, 1.0
	v_rcp_f32_e32 v3, v2
	v_div_scale_f32 v4, vcc, 1.0, v0, 1.0
	v_fma_f32 v5, -v2, v3, 1.0
	v_fmac_f32_e32 v3, v5, v3
	v_mul_f32_e32 v5, v4, v3
	v_fma_f32 v6, -v2, v5, v4
	v_fmac_f32_e32 v5, v6, v3
	v_fma_f32 v2, -v2, v5, v4
	v_div_fmas_f32 v2, v2, v3, v5
	v_div_fixup_f32 v0, v2, v0, 1.0
	v_cndmask_b32_e64 v2, 0, 1, s[0:1]
	v_cmp_ne_u32_e64 s[40:41], 1, v2
	s_andn2_b64 vcc, exec, s[0:1]
	s_mov_b64 s[0:1], -1
	s_cbranch_vccnz .LBB0_517
	v_mov_b32_e32 v133, v132
	v_pk_mul_f32 v[2:3], v[132:133], v[50:51]
	v_pk_mul_f32 v[4:5], v[132:133], v[52:53]
	v_pk_mul_f32 v[6:7], v[132:133], v[54:55]
	v_pk_mul_f32 v[8:9], v[132:133], v[56:57]
	v_pk_mul_f32 v[10:11], v[132:133], v[58:59]
	v_pk_mul_f32 v[12:13], v[132:133], v[60:61]
	v_pk_mul_f32 v[14:15], v[132:133], v[62:63]
	v_pk_mul_f32 v[80:81], v[146:147], v[48:49]
	s_waitcnt vmcnt(4)
	v_pk_fma_f32 v[110:111], v[14:15], v[0:1], v[30:31] op_sel_hi:[1,0,1] neg_lo:[1,0,0] neg_hi:[1,0,0]
	v_pk_fma_f32 v[96:97], v[80:81], v[0:1], v[16:17] op_sel_hi:[1,0,1] neg_lo:[1,0,0] neg_hi:[1,0,0]
	v_pk_fma_f32 v[108:109], v[12:13], v[0:1], v[28:29] op_sel_hi:[1,0,1] neg_lo:[1,0,0] neg_hi:[1,0,0]
	v_pk_fma_f32 v[106:107], v[10:11], v[0:1], v[26:27] op_sel_hi:[1,0,1] neg_lo:[1,0,0] neg_hi:[1,0,0]
	v_pk_fma_f32 v[104:105], v[8:9], v[0:1], v[24:25] op_sel_hi:[1,0,1] neg_lo:[1,0,0] neg_hi:[1,0,0]
	v_pk_fma_f32 v[102:103], v[6:7], v[0:1], v[22:23] op_sel_hi:[1,0,1] neg_lo:[1,0,0] neg_hi:[1,0,0]
	v_pk_fma_f32 v[100:101], v[4:5], v[0:1], v[20:21] op_sel_hi:[1,0,1] neg_lo:[1,0,0] neg_hi:[1,0,0]
	v_pk_fma_f32 v[98:99], v[2:3], v[0:1], v[18:19] op_sel_hi:[1,0,1] neg_lo:[1,0,0] neg_hi:[1,0,0]
	v_pk_mul_f32 v[2:3], v[132:133], v[66:67]
	v_pk_mul_f32 v[4:5], v[132:133], v[68:69]
	v_pk_mul_f32 v[6:7], v[132:133], v[70:71]
	v_pk_mul_f32 v[8:9], v[132:133], v[72:73]
	v_pk_mul_f32 v[10:11], v[132:133], v[74:75]
	v_pk_mul_f32 v[12:13], v[132:133], v[76:77]
	v_pk_mul_f32 v[14:15], v[132:133], v[78:79]
	v_pk_mul_f32 v[80:81], v[146:147], v[64:65]
	v_pk_fma_f32 v[94:95], v[14:15], v[0:1], v[46:47] op_sel_hi:[1,0,1] neg_lo:[1,0,0] neg_hi:[1,0,0]
	v_pk_fma_f32 v[80:81], v[80:81], v[0:1], v[32:33] op_sel_hi:[1,0,1] neg_lo:[1,0,0] neg_hi:[1,0,0]
	v_pk_fma_f32 v[92:93], v[12:13], v[0:1], v[44:45] op_sel_hi:[1,0,1] neg_lo:[1,0,0] neg_hi:[1,0,0]
	v_pk_fma_f32 v[90:91], v[10:11], v[0:1], v[42:43] op_sel_hi:[1,0,1] neg_lo:[1,0,0] neg_hi:[1,0,0]
	v_pk_fma_f32 v[88:89], v[8:9], v[0:1], v[40:41] op_sel_hi:[1,0,1] neg_lo:[1,0,0] neg_hi:[1,0,0]
	v_pk_fma_f32 v[86:87], v[6:7], v[0:1], v[38:39] op_sel_hi:[1,0,1] neg_lo:[1,0,0] neg_hi:[1,0,0]
	v_pk_fma_f32 v[84:85], v[4:5], v[0:1], v[36:37] op_sel_hi:[1,0,1] neg_lo:[1,0,0] neg_hi:[1,0,0]
	v_pk_fma_f32 v[82:83], v[2:3], v[0:1], v[34:35] op_sel_hi:[1,0,1] neg_lo:[1,0,0] neg_hi:[1,0,0]
	s_cbranch_execnz .LBB0_502
	s_branch .LBB0_518

.LBB0_519:
	v_readlane_b32 s20, v255, 26
	v_readlane_b32 s21, v255, 27
	v_mul_f32_e32 v0, v80, v80
	v_mul_f32_e32 v16, v81, v81
	v_mul_f32_e32 v17, v82, v82
	v_fmac_f32_e32 v0, v96, v96
	v_fmac_f32_e32 v16, v97, v97
	global_load_dwordx4 v[2:5], v128, s[20:21]
	v_mul_f32_e32 v18, v83, v83
	v_fmac_f32_e32 v17, v98, v98
	v_add_f32_e32 v0, v0, v16
	v_mul_f32_e32 v19, v84, v84
	v_fmac_f32_e32 v18, v99, v99
	v_add_f32_e32 v0, v17, v0
	v_mul_f32_e32 v20, v85, v85
	v_fmac_f32_e32 v19, v100, v100
	v_add_f32_e32 v0, v18, v0
	v_pk_mul_f32 v[6:7], v[86:87], v[86:87]
	v_fmac_f32_e32 v20, v101, v101
	v_add_f32_e32 v0, v19, v0
	v_pk_fma_f32 v[6:7], v[102:103], v[102:103], v[6:7]
	v_add_f32_e32 v0, v20, v0
	v_pk_mul_f32 v[8:9], v[88:89], v[88:89]
	v_add_f32_e32 v0, v6, v0
	s_waitcnt vmcnt(6)
	v_pk_fma_f32 v[8:9], v[104:105], v[104:105], v[8:9]
	v_add_f32_e32 v0, v7, v0
	v_pk_mul_f32 v[10:11], v[90:91], v[90:91]
	v_add_f32_e32 v0, v8, v0
	v_pk_fma_f32 v[10:11], v[106:107], v[106:107], v[10:11]
	v_add_f32_e32 v0, v9, v0
	v_pk_mul_f32 v[12:13], v[92:93], v[92:93]
	v_add_f32_e32 v0, v10, v0
	s_waitcnt vmcnt(5)
	v_pk_fma_f32 v[12:13], v[108:109], v[108:109], v[12:13]
	v_add_f32_e32 v0, v11, v0
	v_pk_mul_f32 v[14:15], v[94:95], v[94:95]
	v_add_f32_e32 v0, v12, v0
	v_pk_fma_f32 v[14:15], v[110:111], v[110:111], v[14:15]
	v_add_f32_e32 v0, v13, v0
	v_add_f32_e32 v0, v14, v0
	v_add_f32_e32 v8, v15, v0
	v_mov_b32_e32 v9, v8
	s_nop 1
	v_permlane32_swap_b32_e32 v8, v9
	s_lshl_b32 s0, s29, 11
	s_addk_i32 s0, 0x1000
	v_or3_b32 v0, v161, s0, v160
	v_lshlrev_b64 v[6:7], 11, v[0:1]
	s_waitcnt lgkmcnt(0)
	v_add_f32_e32 v0, v8, v9
	v_mov_b32_e32 v8, 0x3727c5ac
	v_fmamk_f32 v0, v0, 0x3c800000, v8
	s_mov_b32 s0, 0x800000
	v_mul_f32_e32 v8, 0x4b800000, v0
	v_cmp_gt_f32_e32 vcc, s0, v0
	v_readlane_b32 s4, v254, 0
	v_readlane_b32 s6, v254, 2
	v_cndmask_b32_e32 v0, v0, v8, vcc
	v_rsq_f32_e32 v0, v0
	v_readlane_b32 s7, v254, 3
	s_lshl_b32 s30, s28, 7
	v_mov_b32_e32 v131, v1
	v_mul_f32_e32 v8, 0x45800000, v0
	v_cndmask_b32_e32 v0, v0, v8, vcc
	v_mul_f32_e32 v0, v159, v0
	v_lshl_add_u64 v[6:7], s[6:7], 0, v[6:7]
	v_pk_mul_f32 v[8:9], v[96:97], v[0:1] op_sel_hi:[1,0]
	v_pk_mul_f32 v[10:11], v[98:99], v[0:1] op_sel_hi:[1,0]
	v_lshl_add_u64 v[6:7], v[6:7], 0, s[30:31]
	v_lshl_add_u64 v[6:7], v[6:7], 0, v[130:131]
	v_readlane_b32 s5, v254, 1
	v_readlane_b32 s8, v254, 4
	v_readlane_b32 s9, v254, 5
	v_readlane_b32 s10, v254, 6
	v_readlane_b32 s11, v254, 7
	v_readlane_b32 s12, v254, 8
	v_readlane_b32 s13, v254, 9
	v_readlane_b32 s14, v254, 10
	v_readlane_b32 s15, v254, 11
	v_readlane_b32 s16, v254, 12
	v_readlane_b32 s17, v254, 13
	v_readlane_b32 s18, v254, 14
	v_readlane_b32 s19, v254, 15
	s_mov_b64 s[0:1], 0
	s_waitcnt vmcnt(0)
	v_pk_mul_f32 v[2:3], v[2:3], v[8:9]
	v_pk_mul_f32 v[4:5], v[4:5], v[10:11]
	v_cvt_pk_bf16_f32 v2, v2, v3
	v_cvt_pk_bf16_f32 v3, v4, v5
	global_store_dwordx2 v[6:7], v[2:3], off
	global_load_dwordx4 v[2:5], v128, s[20:21] offset:32
	v_pk_mul_f32 v[8:9], v[100:101], v[0:1] op_sel_hi:[1,0]
	v_pk_mul_f32 v[10:11], v[102:103], v[0:1] op_sel_hi:[1,0]
	s_waitcnt vmcnt(0)
	v_pk_mul_f32 v[2:3], v[2:3], v[8:9]
	v_pk_mul_f32 v[4:5], v[4:5], v[10:11]
	v_cvt_pk_bf16_f32 v2, v2, v3
	v_cvt_pk_bf16_f32 v3, v4, v5
	global_store_dwordx2 v[6:7], v[2:3], off offset:16
	global_load_dwordx4 v[2:5], v128, s[20:21] offset:64
	v_pk_mul_f32 v[8:9], v[104:105], v[0:1] op_sel_hi:[1,0]
	v_pk_mul_f32 v[10:11], v[106:107], v[0:1] op_sel_hi:[1,0]
	s_waitcnt vmcnt(0)
	v_pk_mul_f32 v[2:3], v[8:9], v[2:3]
	v_pk_mul_f32 v[4:5], v[10:11], v[4:5]
	v_cvt_pk_bf16_f32 v2, v2, v3
	v_cvt_pk_bf16_f32 v3, v4, v5
	global_store_dwordx2 v[6:7], v[2:3], off offset:32
	global_load_dwordx4 v[2:5], v128, s[20:21] offset:96
	v_pk_mul_f32 v[8:9], v[108:109], v[0:1] op_sel_hi:[1,0]
	v_pk_mul_f32 v[10:11], v[110:111], v[0:1] op_sel_hi:[1,0]
	s_waitcnt vmcnt(0)
	v_pk_mul_f32 v[2:3], v[8:9], v[2:3]
	v_pk_mul_f32 v[4:5], v[10:11], v[4:5]
	v_cvt_pk_bf16_f32 v2, v2, v3
	v_cvt_pk_bf16_f32 v3, v4, v5
	global_store_dwordx2 v[6:7], v[2:3], off offset:48
	global_load_dwordx4 v[2:5], v128, s[20:21] offset:128
	v_pk_mul_f32 v[8:9], v[80:81], v[0:1] op_sel_hi:[1,0]
	v_pk_mul_f32 v[10:11], v[82:83], v[0:1] op_sel_hi:[1,0]
	s_waitcnt vmcnt(0)
	v_pk_mul_f32 v[2:3], v[8:9], v[2:3]
	v_pk_mul_f32 v[4:5], v[10:11], v[4:5]
	v_cvt_pk_bf16_f32 v2, v2, v3
	v_cvt_pk_bf16_f32 v3, v4, v5
	global_store_dwordx2 v[6:7], v[2:3], off offset:64
	global_load_dwordx4 v[2:5], v128, s[20:21] offset:160
	v_pk_mul_f32 v[8:9], v[84:85], v[0:1] op_sel_hi:[1,0]
	v_pk_mul_f32 v[10:11], v[86:87], v[0:1] op_sel_hi:[1,0]
	s_waitcnt vmcnt(0)
	v_pk_mul_f32 v[2:3], v[8:9], v[2:3]
	v_pk_mul_f32 v[4:5], v[10:11], v[4:5]
	v_cvt_pk_bf16_f32 v2, v2, v3
	v_cvt_pk_bf16_f32 v3, v4, v5
	global_store_dwordx2 v[6:7], v[2:3], off offset:80
	global_load_dwordx4 v[2:5], v128, s[20:21] offset:192
	v_pk_mul_f32 v[8:9], v[88:89], v[0:1] op_sel_hi:[1,0]
	v_pk_mul_f32 v[10:11], v[90:91], v[0:1] op_sel_hi:[1,0]
	s_waitcnt vmcnt(0)
	v_pk_mul_f32 v[2:3], v[8:9], v[2:3]
	v_pk_mul_f32 v[4:5], v[10:11], v[4:5]
	v_cvt_pk_bf16_f32 v2, v2, v3
	v_cvt_pk_bf16_f32 v3, v4, v5
	global_store_dwordx2 v[6:7], v[2:3], off offset:96
	global_load_dwordx4 v[2:5], v128, s[20:21] offset:224
	v_pk_mul_f32 v[8:9], v[92:93], v[0:1] op_sel_hi:[1,0]
	v_pk_mul_f32 v[10:11], v[94:95], v[0:1] op_sel_hi:[1,0]
	s_waitcnt vmcnt(0)
	v_pk_mul_f32 v[2:3], v[8:9], v[2:3]
	v_pk_mul_f32 v[4:5], v[10:11], v[4:5]
	v_cvt_pk_bf16_f32 v2, v2, v3
	v_cvt_pk_bf16_f32 v3, v4, v5
	global_store_dwordx2 v[6:7], v[2:3], off offset:112

.LBB0_524:
	ds_read_b128 v[66:69], v157
	ds_read_b128 v[114:117], v157 offset:32
	v_add_u32_e32 v177, s30, v123
	s_waitcnt lgkmcnt(1)
	v_mfma_f32_32x32x16_bf16 v[66:81], v[66:69], v[82:85], 0
	s_waitcnt lgkmcnt(0)
	v_mfma_f32_32x32x16_bf16 v[66:81], v[114:117], v[86:89], v[66:81]
	v_mov_b32_e32 v116, v127
	v_max_f32_e32 v117, v116, v116
	s_nop 9
	v_max_f32_e32 v114, v67, v67
	v_max_f32_e32 v115, v66, v66
	v_max_f32_e32 v114, v115, v114
	v_max3_f32 v114, v114, v68, v69
	v_max3_f32 v114, v114, v70, v71
	v_max3_f32 v114, v114, v72, v73
	v_max3_f32 v114, v114, v74, v75
	v_max3_f32 v114, v114, v76, v77
	v_max3_f32 v114, v114, v78, v79
	v_max3_f32 v114, v114, v80, v81
	v_mov_b32_e32 v115, v114
	s_nop 1
	v_permlane32_swap_b32_e32 v114, v115
	s_waitcnt lgkmcnt(0)
	v_max_f32_e32 v115, v115, v115
	v_max_f32_e32 v114, v114, v115
	v_mul_f32_e32 v114, 0x3e8293ee, v114
	v_max_f32_e32 v127, v117, v114
	v_sub_f32_e32 v114, v116, v127
	v_exp_f32_e32 v146, v114
	ds_read2_b64 v[114:117], v177 offset1:2
	ds_read2_b64 v[118:121], v177 offset0:4 offset1:6
	v_cmp_neq_f32_e32 vcc, 1.0, v146
	s_cmp_lg_u64 vcc, 0
	s_cselect_b64 s[0:1], -1, 0
	s_cbranch_vccz .LBB0_526
	v_pk_mul_f32 v[48:49], v[48:49], v[146:147] op_sel_hi:[1,0]
	v_pk_mul_f32 v[46:47], v[46:47], v[146:147] op_sel_hi:[1,0]
	v_pk_mul_f32 v[44:45], v[44:45], v[146:147] op_sel_hi:[1,0]
	v_pk_mul_f32 v[42:43], v[42:43], v[146:147] op_sel_hi:[1,0]
	v_pk_mul_f32 v[40:41], v[40:41], v[146:147] op_sel_hi:[1,0]
	v_pk_mul_f32 v[38:39], v[38:39], v[146:147] op_sel_hi:[1,0]
	v_pk_mul_f32 v[36:37], v[36:37], v[146:147] op_sel_hi:[1,0]
	v_pk_mul_f32 v[34:35], v[34:35], v[146:147] op_sel_hi:[1,0]

.LBB0_531:
	ds_read_b128 v[66:69], v99
	ds_read_b128 v[90:93], v99 offset:32
	v_add_u32_e32 v117, s30, v123
	s_waitcnt lgkmcnt(1)
	v_mfma_f32_32x32x16_bf16 v[66:81], v[66:69], v[82:85], 0
	s_waitcnt lgkmcnt(0)
	v_mfma_f32_32x32x16_bf16 v[66:81], v[90:93], v[86:89], v[66:81]
	v_mov_b32_e32 v92, v127
	v_max_f32_e32 v93, v92, v92
	s_nop 9
	v_max_f32_e32 v90, v67, v67
	v_max_f32_e32 v91, v66, v66
	v_max_f32_e32 v90, v91, v90
	v_max3_f32 v90, v90, v68, v69
	v_max3_f32 v90, v90, v70, v71
	v_max3_f32 v90, v90, v72, v73
	v_max3_f32 v90, v90, v74, v75
	v_max3_f32 v90, v90, v76, v77
	v_max3_f32 v90, v90, v78, v79
	v_max3_f32 v90, v90, v80, v81
	v_mov_b32_e32 v91, v90
	s_nop 1
	v_permlane32_swap_b32_e32 v90, v91
	s_waitcnt lgkmcnt(0)
	v_max_f32_e32 v91, v91, v91
	v_max_f32_e32 v90, v90, v91
	v_mul_f32_e32 v90, 0x3e8293ee, v90
	v_max_f32_e32 v127, v93, v90
	v_sub_f32_e32 v90, v92, v127
	v_exp_f32_e32 v98, v90
	ds_read2_b64 v[90:93], v117 offset1:2
	ds_read2_b64 v[94:97], v117 offset0:4 offset1:6
	v_cmp_neq_f32_e32 vcc, 1.0, v98
	s_cmp_lg_u64 vcc, 0
	s_cselect_b64 s[0:1], -1, 0
	s_cbranch_vccz .LBB0_533
	v_pk_mul_f32 v[48:49], v[48:49], v[98:99] op_sel_hi:[1,0]
	v_pk_mul_f32 v[46:47], v[46:47], v[98:99] op_sel_hi:[1,0]
	v_pk_mul_f32 v[44:45], v[44:45], v[98:99] op_sel_hi:[1,0]
	v_pk_mul_f32 v[42:43], v[42:43], v[98:99] op_sel_hi:[1,0]
	v_pk_mul_f32 v[40:41], v[40:41], v[98:99] op_sel_hi:[1,0]
	v_pk_mul_f32 v[38:39], v[38:39], v[98:99] op_sel_hi:[1,0]
	v_pk_mul_f32 v[36:37], v[36:37], v[98:99] op_sel_hi:[1,0]
	v_pk_mul_f32 v[34:35], v[34:35], v[98:99] op_sel_hi:[1,0]

.LBB0_537:
	v_mov_b32_e32 v67, v66
	s_nop 1
	v_permlane32_swap_b32_e32 v66, v67
	s_waitcnt lgkmcnt(0)
	s_barrier
	v_add_f32_e32 v66, v66, v67
	v_div_scale_f32 v67, s[0:1], v66, v66, 1.0
	v_rcp_f32_e32 v68, v67
	v_div_scale_f32 v69, vcc, 1.0, v66, 1.0
	s_mov_b64 s[0:1], -1
	v_fma_f32 v70, -v67, v68, 1.0
	v_fmac_f32_e32 v68, v70, v68
	v_mul_f32_e32 v70, v69, v68
	v_fma_f32 v71, -v67, v70, v69
	v_fmac_f32_e32 v70, v71, v68
	v_fma_f32 v67, -v67, v70, v69
	v_div_fmas_f32 v67, v67, v68, v70
	v_div_fixup_f32 v98, v67, v66, 1.0
	v_cndmask_b32_e64 v66, 0, 1, s[28:29]
	v_cmp_ne_u32_e64 s[40:41], 1, v66
	s_andn2_b64 vcc, exec, s[28:29]
	s_cbranch_vccnz .LBB0_539
	v_mov_b32_e32 v127, v126
	v_pk_mul_f32 v[66:67], v[126:127], v[36:37]
	v_pk_mul_f32 v[68:69], v[126:127], v[38:39]
	v_pk_mul_f32 v[70:71], v[126:127], v[40:41]
	v_pk_mul_f32 v[72:73], v[126:127], v[42:43]
	v_pk_mul_f32 v[74:75], v[126:127], v[44:45]
	v_pk_mul_f32 v[76:77], v[126:127], v[46:47]
	v_pk_mul_f32 v[78:79], v[126:127], v[48:49]
	v_pk_mul_f32 v[80:81], v[142:143], v[34:35]
	v_pk_fma_f32 v[96:97], v[78:79], v[98:99], v[16:17] op_sel_hi:[1,0,1] neg_lo:[1,0,0] neg_hi:[1,0,0]
	v_pk_fma_f32 v[82:83], v[80:81], v[98:99], v[2:3] op_sel_hi:[1,0,1] neg_lo:[1,0,0] neg_hi:[1,0,0]
	v_pk_fma_f32 v[94:95], v[76:77], v[98:99], v[14:15] op_sel_hi:[1,0,1] neg_lo:[1,0,0] neg_hi:[1,0,0]
	v_pk_fma_f32 v[92:93], v[74:75], v[98:99], v[12:13] op_sel_hi:[1,0,1] neg_lo:[1,0,0] neg_hi:[1,0,0]
	v_pk_fma_f32 v[90:91], v[72:73], v[98:99], v[10:11] op_sel_hi:[1,0,1] neg_lo:[1,0,0] neg_hi:[1,0,0]
	v_pk_fma_f32 v[88:89], v[70:71], v[98:99], v[8:9] op_sel_hi:[1,0,1] neg_lo:[1,0,0] neg_hi:[1,0,0]
	v_pk_fma_f32 v[86:87], v[68:69], v[98:99], v[6:7] op_sel_hi:[1,0,1] neg_lo:[1,0,0] neg_hi:[1,0,0]
	v_pk_fma_f32 v[84:85], v[66:67], v[98:99], v[4:5] op_sel_hi:[1,0,1] neg_lo:[1,0,0] neg_hi:[1,0,0]
	v_pk_mul_f32 v[68:69], v[126:127], v[52:53]
	v_pk_mul_f32 v[70:71], v[126:127], v[54:55]
	v_pk_mul_f32 v[72:73], v[126:127], v[56:57]
	v_pk_mul_f32 v[74:75], v[126:127], v[58:59]
	v_pk_mul_f32 v[76:77], v[126:127], v[60:61]
	v_pk_mul_f32 v[78:79], v[126:127], v[62:63]
	v_pk_mul_f32 v[80:81], v[126:127], v[64:65]
	v_pk_mul_f32 v[66:67], v[142:143], v[50:51]
	v_pk_fma_f32 v[80:81], v[80:81], v[98:99], v[32:33] op_sel_hi:[1,0,1] neg_lo:[1,0,0] neg_hi:[1,0,0]
	v_pk_fma_f32 v[66:67], v[66:67], v[98:99], v[18:19] op_sel_hi:[1,0,1] neg_lo:[1,0,0] neg_hi:[1,0,0]
	v_pk_fma_f32 v[78:79], v[78:79], v[98:99], v[30:31] op_sel_hi:[1,0,1] neg_lo:[1,0,0] neg_hi:[1,0,0]
	v_pk_fma_f32 v[76:77], v[76:77], v[98:99], v[28:29] op_sel_hi:[1,0,1] neg_lo:[1,0,0] neg_hi:[1,0,0]
	v_pk_fma_f32 v[74:75], v[74:75], v[98:99], v[26:27] op_sel_hi:[1,0,1] neg_lo:[1,0,0] neg_hi:[1,0,0]
	v_pk_fma_f32 v[72:73], v[72:73], v[98:99], v[24:25] op_sel_hi:[1,0,1] neg_lo:[1,0,0] neg_hi:[1,0,0]
	v_pk_fma_f32 v[70:71], v[70:71], v[98:99], v[22:23] op_sel_hi:[1,0,1] neg_lo:[1,0,0] neg_hi:[1,0,0]
	v_pk_fma_f32 v[68:69], v[68:69], v[98:99], v[20:21] op_sel_hi:[1,0,1] neg_lo:[1,0,0] neg_hi:[1,0,0]
	s_cbranch_execnz .LBB0_522
	s_branch .LBB0_540

.LBB0_541:
	v_readlane_b32 s20, v255, 26
	v_readlane_b32 s21, v255, 27
	v_mul_f32_e32 v0, v66, v66
	v_mul_f32_e32 v16, v67, v67
	v_mul_f32_e32 v17, v68, v68
	v_fmac_f32_e32 v0, v82, v82
	v_fmac_f32_e32 v16, v83, v83
	global_load_dwordx4 v[2:5], v122, s[20:21]
	v_mul_f32_e32 v18, v69, v69
	v_fmac_f32_e32 v17, v84, v84
	v_add_f32_e32 v0, v0, v16
	v_mul_f32_e32 v19, v70, v70
	v_fmac_f32_e32 v18, v85, v85
	v_add_f32_e32 v0, v17, v0
	v_mul_f32_e32 v20, v71, v71
	v_fmac_f32_e32 v19, v86, v86
	v_add_f32_e32 v0, v18, v0
	v_pk_mul_f32 v[6:7], v[72:73], v[72:73]
	v_fmac_f32_e32 v20, v87, v87
	v_add_f32_e32 v0, v19, v0
	v_pk_fma_f32 v[6:7], v[88:89], v[88:89], v[6:7]
	v_add_f32_e32 v0, v20, v0
	v_pk_mul_f32 v[8:9], v[74:75], v[74:75]
	v_add_f32_e32 v0, v6, v0
	v_pk_fma_f32 v[8:9], v[90:91], v[90:91], v[8:9]
	v_add_f32_e32 v0, v7, v0
	v_pk_mul_f32 v[10:11], v[76:77], v[76:77]
	v_add_f32_e32 v0, v8, v0
	v_pk_fma_f32 v[10:11], v[92:93], v[92:93], v[10:11]
	v_add_f32_e32 v0, v9, v0
	v_pk_mul_f32 v[12:13], v[78:79], v[78:79]
	v_add_f32_e32 v0, v10, v0
	v_pk_fma_f32 v[12:13], v[94:95], v[94:95], v[12:13]
	v_add_f32_e32 v0, v11, v0
	v_pk_mul_f32 v[14:15], v[80:81], v[80:81]
	v_add_f32_e32 v0, v12, v0
	v_pk_fma_f32 v[14:15], v[96:97], v[96:97], v[14:15]
	v_add_f32_e32 v0, v13, v0
	v_add_f32_e32 v0, v14, v0
	v_add_f32_e32 v8, v15, v0
	v_mov_b32_e32 v9, v8
	s_nop 1
	v_permlane32_swap_b32_e32 v8, v9
	s_lshl_b32 s0, s44, 8
	v_or3_b32 v0, v148, s0, v147
	v_lshlrev_b64 v[6:7], 11, v[0:1]
	s_mov_b32 s0, 0x800000
	s_waitcnt lgkmcnt(0)
	v_add_f32_e32 v0, v8, v9
	v_mov_b32_e32 v8, 0x3727c5ac
	v_fmamk_f32 v0, v0, 0x3c800000, v8
	v_mul_f32_e32 v8, 0x4b800000, v0
	v_cmp_gt_f32_e32 vcc, s0, v0
	v_readlane_b32 s4, v254, 0
	v_readlane_b32 s6, v254, 2
	v_cndmask_b32_e32 v0, v0, v8, vcc
	v_rsq_f32_e32 v0, v0
	v_readlane_b32 s7, v254, 3
	s_lshl_b32 s30, s43, 7
	v_mov_b32_e32 v125, v1
	v_mul_f32_e32 v8, 0x45800000, v0
	v_cndmask_b32_e32 v0, v0, v8, vcc
	v_mul_f32_e32 v0, v159, v0
	v_lshl_add_u64 v[6:7], s[6:7], 0, v[6:7]
	v_pk_mul_f32 v[8:9], v[82:83], v[0:1] op_sel_hi:[1,0]
	v_pk_mul_f32 v[10:11], v[84:85], v[0:1] op_sel_hi:[1,0]
	v_lshl_add_u64 v[6:7], v[6:7], 0, s[30:31]
	v_lshl_add_u64 v[6:7], v[6:7], 0, v[124:125]
	s_mov_b32 s23, s45
	v_readlane_b32 s5, v254, 1
	v_readlane_b32 s8, v254, 4
	v_readlane_b32 s9, v254, 5
	v_readlane_b32 s10, v254, 6
	v_readlane_b32 s11, v254, 7
	v_readlane_b32 s12, v254, 8
	v_readlane_b32 s13, v254, 9
	v_readlane_b32 s14, v254, 10
	v_readlane_b32 s15, v254, 11
	v_readlane_b32 s16, v254, 12
	v_readlane_b32 s17, v254, 13
	v_readlane_b32 s18, v254, 14
	v_readlane_b32 s19, v254, 15
	s_waitcnt vmcnt(0)
	v_pk_mul_f32 v[2:3], v[2:3], v[8:9]
	v_pk_mul_f32 v[4:5], v[4:5], v[10:11]
	v_cvt_pk_bf16_f32 v2, v2, v3
	v_cvt_pk_bf16_f32 v3, v4, v5
	global_store_dwordx2 v[6:7], v[2:3], off
	global_load_dwordx4 v[2:5], v122, s[20:21] offset:32
	v_pk_mul_f32 v[8:9], v[86:87], v[0:1] op_sel_hi:[1,0]
	v_pk_mul_f32 v[10:11], v[88:89], v[0:1] op_sel_hi:[1,0]
	s_waitcnt vmcnt(0)
	v_pk_mul_f32 v[2:3], v[2:3], v[8:9]
	v_pk_mul_f32 v[4:5], v[4:5], v[10:11]
	v_cvt_pk_bf16_f32 v2, v2, v3
	v_cvt_pk_bf16_f32 v3, v4, v5
	global_store_dwordx2 v[6:7], v[2:3], off offset:16
	global_load_dwordx4 v[2:5], v122, s[20:21] offset:64
	v_pk_mul_f32 v[8:9], v[90:91], v[0:1] op_sel_hi:[1,0]
	v_pk_mul_f32 v[10:11], v[92:93], v[0:1] op_sel_hi:[1,0]
	s_waitcnt vmcnt(0)
	v_pk_mul_f32 v[2:3], v[8:9], v[2:3]
	v_pk_mul_f32 v[4:5], v[10:11], v[4:5]
	v_cvt_pk_bf16_f32 v2, v2, v3
	v_cvt_pk_bf16_f32 v3, v4, v5
	global_store_dwordx2 v[6:7], v[2:3], off offset:32
	global_load_dwordx4 v[2:5], v122, s[20:21] offset:96
	v_pk_mul_f32 v[8:9], v[94:95], v[0:1] op_sel_hi:[1,0]
	v_pk_mul_f32 v[10:11], v[96:97], v[0:1] op_sel_hi:[1,0]
	s_waitcnt vmcnt(0)
	v_pk_mul_f32 v[2:3], v[8:9], v[2:3]
	v_pk_mul_f32 v[4:5], v[10:11], v[4:5]
	v_cvt_pk_bf16_f32 v2, v2, v3
	v_cvt_pk_bf16_f32 v3, v4, v5
	global_store_dwordx2 v[6:7], v[2:3], off offset:48
	global_load_dwordx4 v[2:5], v122, s[20:21] offset:128
	v_pk_mul_f32 v[8:9], v[66:67], v[0:1] op_sel_hi:[1,0]
	v_pk_mul_f32 v[10:11], v[68:69], v[0:1] op_sel_hi:[1,0]
	s_waitcnt vmcnt(0)
	v_pk_mul_f32 v[2:3], v[8:9], v[2:3]
	v_pk_mul_f32 v[4:5], v[10:11], v[4:5]
	v_cvt_pk_bf16_f32 v2, v2, v3
	v_cvt_pk_bf16_f32 v3, v4, v5
	global_store_dwordx2 v[6:7], v[2:3], off offset:64
	global_load_dwordx4 v[2:5], v122, s[20:21] offset:160
	v_pk_mul_f32 v[8:9], v[70:71], v[0:1] op_sel_hi:[1,0]
	v_pk_mul_f32 v[10:11], v[72:73], v[0:1] op_sel_hi:[1,0]
	s_waitcnt vmcnt(0)
	v_pk_mul_f32 v[2:3], v[8:9], v[2:3]
	v_pk_mul_f32 v[4:5], v[10:11], v[4:5]
	v_cvt_pk_bf16_f32 v2, v2, v3
	v_cvt_pk_bf16_f32 v3, v4, v5
	global_store_dwordx2 v[6:7], v[2:3], off offset:80
	global_load_dwordx4 v[2:5], v122, s[20:21] offset:192
	v_pk_mul_f32 v[8:9], v[74:75], v[0:1] op_sel_hi:[1,0]
	v_pk_mul_f32 v[10:11], v[76:77], v[0:1] op_sel_hi:[1,0]
	s_waitcnt vmcnt(0)
	v_pk_mul_f32 v[2:3], v[8:9], v[2:3]
	v_pk_mul_f32 v[4:5], v[10:11], v[4:5]
	v_cvt_pk_bf16_f32 v2, v2, v3
	v_cvt_pk_bf16_f32 v3, v4, v5
	global_store_dwordx2 v[6:7], v[2:3], off offset:96
	global_load_dwordx4 v[2:5], v122, s[20:21] offset:224
	v_pk_mul_f32 v[8:9], v[78:79], v[0:1] op_sel_hi:[1,0]
	v_pk_mul_f32 v[10:11], v[80:81], v[0:1] op_sel_hi:[1,0]
	s_waitcnt vmcnt(0)
	v_pk_mul_f32 v[2:3], v[8:9], v[2:3]
	v_pk_mul_f32 v[4:5], v[10:11], v[4:5]
	v_cvt_pk_bf16_f32 v2, v2, v3
	v_cvt_pk_bf16_f32 v3, v4, v5
	global_store_dwordx2 v[6:7], v[2:3], off offset:112

.LBB0_552:
	s_or_b64 exec, exec, s[0:1]
	v_readlane_b32 s4, v253, 46
	s_lshl_b32 s30, s28, 11
	v_readlane_b32 s16, v253, 58
	v_readlane_b32 s17, v253, 59
	s_add_u32 s0, s16, s30
	v_readlane_b32 s18, v253, 60
	s_addc_u32 s1, s17, 0
	v_mov_b32_e32 v3, v1
	v_readlane_b32 s19, v253, 61
	v_lshl_add_u64 v[60:61], s[0:1], 0, v[2:3]
	s_add_u32 s0, s18, s30
	s_addc_u32 s1, s19, 0
	v_lshl_add_u64 v[62:63], s[0:1], 0, v[2:3]
	v_lshlrev_b64 v[2:3], 12, v[0:1]
	v_lshl_add_u64 v[4:5], v[60:61], 0, v[2:3]
	global_load_dword v94, v[4:5], off
	v_or_b32_e32 v4, 4, v74
	v_xor_b32_e32 v0, 0xfb, v74
	v_readlane_b32 s6, v253, 48
	v_cndmask_b32_e64 v0, v0, v4, s[40:41]
	v_lshl_add_u64 v[2:3], v[62:63], 0, v[2:3]
	v_or_b32_e32 v0, s53, v0
	s_movk_i32 s6, 0x1c00
	global_load_dword v95, v[2:3], off
	v_mad_u64_u32 v[2:3], s[0:1], v0, s6, v[58:59]
	s_movk_i32 s4, 0x1000
	v_add_co_u32_e32 v8, vcc, s4, v2
	v_readlane_b32 s5, v253, 47
	s_nop 0
	v_addc_co_u32_e32 v9, vcc, 0, v3, vcc
	s_waitcnt vmcnt(29)
	v_add_co_u32_e32 v10, vcc, s22, v2
	s_movk_i32 s5, 0x2000
	s_nop 0
	v_addc_co_u32_e32 v11, vcc, -1, v3, vcc
	global_load_dword v96, v[2:3], off
	global_load_dword v97, v[2:3], off offset:2048
	global_load_dword v98, v[8:9], off
	global_load_dword v100, v[10:11], off offset:-3072
	global_load_dword v101, v[10:11], off offset:-1024
	global_load_dword v99, v[2:3], off offset:-3072
	global_load_dword v102, v[8:9], off offset:3072
	v_add_co_u32_e32 v2, vcc, s5, v2
	v_and_b32_e32 v5, 64, v209
	s_nop 0
	v_addc_co_u32_e32 v3, vcc, 0, v3, vcc
	global_load_dword v106, v[2:3], off offset:1024
	global_load_dword v105, v[2:3], off offset:3072
	v_lshlrev_b64 v[2:3], 12, v[0:1]
	v_lshl_add_u64 v[8:9], v[60:61], 0, v[2:3]
	v_lshl_add_u64 v[2:3], v[62:63], 0, v[2:3]
	global_load_dword v108, v[2:3], off
	v_or_b32_e32 v3, 8, v74
	v_xor_b32_e32 v0, 0xf7, v74
	v_cndmask_b32_e64 v0, v0, v3, s[40:41]
	v_or_b32_e32 v0, s53, v0
	global_load_dword v107, v[8:9], off
	v_mad_u64_u32 v[8:9], s[0:1], v0, s6, v[58:59]
	v_add_co_u32_e32 v10, vcc, s4, v8
	global_load_dword v109, v[8:9], off
	global_load_dword v110, v[8:9], off offset:2048
	v_addc_co_u32_e32 v11, vcc, 0, v9, vcc
	s_waitcnt vmcnt(41)
	v_add_co_u32_e32 v12, vcc, s22, v8
	global_load_dword v111, v[10:11], off
	s_waitcnt vmcnt(41)
	v_addc_co_u32_e32 v13, vcc, -1, v9, vcc
	global_load_dword v113, v[12:13], off offset:-3072
	global_load_dword v114, v[12:13], off offset:-1024
	global_load_dword v112, v[8:9], off offset:-3072
	global_load_dword v115, v[10:11], off offset:3072
	v_add_co_u32_e32 v8, vcc, s5, v8
	v_or_b32_e32 v2, 12, v74
	s_nop 0
	v_addc_co_u32_e32 v9, vcc, 0, v9, vcc
	global_load_dword v117, v[8:9], off offset:1024
	global_load_dword v116, v[8:9], off offset:3072
	v_lshlrev_b64 v[8:9], 12, v[0:1]
	v_xor_b32_e32 v0, 0xf3, v74
	v_cndmask_b32_e64 v0, v0, v2, s[40:41]
	v_lshl_add_u64 v[10:11], v[60:61], 0, v[8:9]
	v_lshl_add_u64 v[8:9], v[62:63], 0, v[8:9]
	v_or_b32_e32 v0, s53, v0
	global_load_dword v120, v[8:9], off
	v_mad_u64_u32 v[8:9], s[0:1], v0, s6, v[58:59]
	global_load_dword v119, v[10:11], off
	v_add_co_u32_e32 v10, vcc, s4, v8
	global_load_dword v121, v[8:9], off
	global_load_dword v122, v[8:9], off offset:2048
	v_addc_co_u32_e32 v11, vcc, 0, v9, vcc
	v_add_co_u32_e32 v12, vcc, s22, v8
	global_load_dword v123, v[10:11], off
	s_nop 0
	v_addc_co_u32_e32 v13, vcc, -1, v9, vcc
	global_load_dword v125, v[12:13], off offset:-3072
	global_load_dword v126, v[12:13], off offset:-1024
	global_load_dword v124, v[8:9], off offset:-3072
	global_load_dword v127, v[10:11], off offset:3072
	v_add_co_u32_e32 v8, vcc, s5, v8
	v_add_u32_e32 v5, 64, v5
	s_nop 0
	v_addc_co_u32_e32 v9, vcc, 0, v9, vcc
	global_load_dword v130, v[8:9], off offset:1024
	global_load_dword v128, v[8:9], off offset:3072
	v_lshlrev_b64 v[8:9], 12, v[0:1]
	v_lshl_add_u64 v[10:11], v[60:61], 0, v[8:9]
	v_lshl_add_u64 v[8:9], v[62:63], 0, v[8:9]
	v_xor_b32_e32 v0, 16, v209
	global_load_dword v131, v[10:11], off
	global_load_dword v132, v[8:9], off
	v_cmp_lt_i32_e32 vcc, v0, v5
	s_waitcnt vmcnt(35)
	v_sub_f32_e32 v8, v93, v85
	s_mov_b32 s0, 0xf800000
	v_cndmask_b32_e32 v0, v209, v0, vcc
	v_lshlrev_b32_e32 v103, 2, v0
	v_xor_b32_e32 v0, 32, v209
	v_cmp_lt_i32_e32 vcc, v0, v5
	v_sub_f32_e32 v5, v91, v84
	v_and_b32_e32 v90, 0xff, v6
	v_cndmask_b32_e32 v0, v209, v0, vcc
	v_lshlrev_b32_e32 v104, 2, v0
	v_sub_f32_e32 v0, v88, v84
	v_fma_f32 v0, v75, v0, v84
	v_fmac_f32_e32 v0, v77, v5
	v_sub_f32_e32 v5, v89, v85
	v_fma_f32 v5, v76, v5, v85
	v_fmac_f32_e32 v5, v78, v8
	v_sub_f32_e32 v8, v87, v86
	v_fma_f32 v13, v80, v8, v86
	v_sub_f32_e32 v8, v92, v86
	v_fmac_f32_e32 v13, v79, v8
	v_mul_f32_e32 v8, v81, v5
	v_mul_f32_e32 v9, v8, v8
	v_lshl_add_u32 v17, v90, 2, s33
	s_waitcnt lgkmcnt(0)
	v_mov_b32_dpp v9, v9 quad_perm:[1,0,3,2] row_mask:0xf bank_mask:0xf bound_ctrl:1
	v_fmac_f32_e32 v9, v8, v8
	s_barrier
	s_nop 0
	v_add_f32_dpp v9, v9, v9 quad_perm:[2,3,0,1] row_mask:0xf bank_mask:0xf bound_ctrl:1
	s_waitcnt vmcnt(34)
	ds_write_b32 v17, v94
	v_cmp_eq_u32_e64 s[42:43], 0, v7
	v_add_f32_dpp v9, v9, v9 row_half_mirror row_mask:0xf bank_mask:0xf bound_ctrl:1
	v_readlane_b32 s7, v253, 49
	v_readlane_b32 s8, v253, 50
	v_add_f32_dpp v9, v9, v9 row_mirror row_mask:0xf bank_mask:0xf bound_ctrl:1
	v_mov_b32_e32 v10, v9
	s_nop 1
	v_permlane16_swap_b32_e32 v9, v10
	v_readlane_b32 s9, v253, 51
	v_readlane_b32 s10, v253, 52
	v_readlane_b32 s11, v253, 53
	v_readlane_b32 s12, v253, 54
	s_waitcnt lgkmcnt(0)
	v_add_f32_e32 v9, v9, v10
	v_mov_b32_e32 v10, v9
	s_nop 1
	v_permlane32_swap_b32_e32 v9, v10
	v_readlane_b32 s13, v253, 55
	v_readlane_b32 s14, v253, 56
	v_readlane_b32 s15, v253, 57
	s_waitcnt lgkmcnt(0)
	v_add_f32_e32 v9, v9, v10
	v_cmp_gt_f32_e32 vcc, s0, v9
	v_mul_f32_e32 v10, 0x4f800000, v9
	s_nop 0
	v_cndmask_b32_e32 v9, v9, v10, vcc
	v_sqrt_f32_e32 v10, v9
	s_nop 0
	v_add_u32_e32 v11, -1, v10
	v_fma_f32 v12, -v11, v10, v9
	v_cmp_ge_f32_e64 s[44:45], 0, v12
	v_add_u32_e32 v12, 1, v10
	s_nop 0
	v_cndmask_b32_e64 v11, v10, v11, s[44:45]
	v_fma_f32 v10, -v12, v10, v9
	v_cmp_lt_f32_e64 s[44:45], 0, v10
	s_nop 1
	v_cndmask_b32_e64 v10, v11, v12, s[44:45]
	v_mul_f32_e32 v11, 0x37800000, v10
	v_cndmask_b32_e32 v10, v10, v11, vcc
	v_cmp_class_f32_e32 vcc, v9, v204
	s_nop 1
	v_cndmask_b32_e32 v9, v10, v9, vcc
	v_max_f32_e32 v9, 0x2b8cbccc, v9
	v_div_scale_f32 v10, s[0:1], v9, v9, v8
	v_rcp_f32_e32 v11, v10
	s_movk_i32 s0, 0xc0
	v_and_or_b32 v118, v6, s0, v7
	v_lshl_add_u32 v17, v118, 2, s33
	v_fma_f32 v12, -v10, v11, 1.0
	v_fmac_f32_e32 v11, v12, v11
	v_div_scale_f32 v12, vcc, v8, v9, v8
	v_mul_f32_e32 v14, v12, v11
	v_fma_f32 v15, -v10, v14, v12
	v_fmac_f32_e32 v14, v15, v11
	v_fma_f32 v10, -v10, v14, v12
	v_div_fmas_f32 v10, v10, v11, v14
	v_div_fixup_f32 v14, v10, v9, v8
	s_waitcnt vmcnt(33)
	v_add_f32_e32 v8, -1.0, v95
	v_fma_f32 v8, v82, v8, 1.0
	v_mul_f32_e32 v15, v5, v8
	v_mul_f32_e32 v11, v0, v15
	v_mul_f32_e32 v16, v95, v14
	v_mul_f32_e32 v5, v83, v11
	v_mul_f32_e32 v9, v0, v16
	v_xor_b32_e32 v14, 0x80000000, v14
	v_mov_b32_dpp v5, v5 quad_perm:[1,0,3,2] row_mask:0xf bank_mask:0xf bound_ctrl:1
	v_fmac_f32_e32 v5, v83, v11
	v_mov_b32_dpp v9, v9 quad_perm:[1,0,3,2] row_mask:0xf bank_mask:0xf bound_ctrl:1
	v_mov_b32_dpp v11, v11 quad_perm:[1,0,3,2] row_mask:0xf bank_mask:0xf bound_ctrl:1
	v_fmac_f32_e32 v9, v0, v16
	v_fmac_f32_e32 v11, v0, v15
	v_add_f32_dpp v5, v5, v5 quad_perm:[2,3,0,1] row_mask:0xf bank_mask:0xf bound_ctrl:1
	v_add_f32_dpp v9, v9, v9 quad_perm:[2,3,0,1] row_mask:0xf bank_mask:0xf bound_ctrl:1
	v_add_f32_dpp v11, v11, v11 quad_perm:[2,3,0,1] row_mask:0xf bank_mask:0xf bound_ctrl:1
	v_add_f32_dpp v5, v5, v5 row_half_mirror row_mask:0xf bank_mask:0xf bound_ctrl:1
	v_add_f32_dpp v9, v9, v9 row_half_mirror row_mask:0xf bank_mask:0xf bound_ctrl:1
	v_add_f32_dpp v11, v11, v11 row_half_mirror row_mask:0xf bank_mask:0xf bound_ctrl:1
	v_add_f32_dpp v5, v5, v5 row_mirror row_mask:0xf bank_mask:0xf bound_ctrl:1
	v_add_f32_dpp v9, v9, v9 row_mirror row_mask:0xf bank_mask:0xf bound_ctrl:1
	v_add_f32_dpp v11, v11, v11 row_mirror row_mask:0xf bank_mask:0xf bound_ctrl:1
	v_mov_b32_e32 v8, v5
	s_nop 1
	v_permlane16_swap_b32_e32 v5, v8
	v_mov_b32_e32 v10, v9
	s_nop 1
	v_permlane16_swap_b32_e32 v9, v10
	v_mov_b32_e32 v12, v11
	s_nop 1
	v_permlane16_swap_b32_e32 v11, v12
	v_mul_f32_e32 v0, v0, v94
	ds_write2st64_b32 v17, v14, v16 offset0:16 offset1:32
	s_waitcnt lgkmcnt(3)
	v_add_f32_e32 v5, v5, v8
	s_waitcnt lgkmcnt(2)
	v_add_f32_e32 v9, v9, v10
	s_waitcnt lgkmcnt(1)
	v_add_f32_e32 v11, v11, v12
	v_mov_b32_e32 v8, v5
	s_nop 1
	v_permlane32_swap_b32_e32 v5, v8
	v_mov_b32_e32 v10, v9
	s_nop 1
	v_permlane32_swap_b32_e32 v9, v10
	v_mov_b32_e32 v12, v11
	s_nop 1
	v_permlane32_swap_b32_e32 v11, v12
	ds_write2st64_b32 v17, v15, v0 offset0:48 offset1:64
	ds_write_b32 v17, v13 offset:20480
	v_lshl_add_u32 v0, v74, 2, s33
	s_and_saveexec_b64 s[0:1], s[42:43]
	s_cbranch_execz .LBB0_554
	s_waitcnt lgkmcnt(2)
	v_add_f32_e32 v11, v11, v12
	v_add_f32_e32 v5, v5, v8
	v_add_f32_e32 v5, v5, v11
	v_add_f32_e32 v8, v9, v10
	v_add_u32_e32 v9, 0x6000, v0
	ds_write2_b32 v9, v8, v5 offset1:16
.LBB0_554:
	s_or_b64 exec, exec, s[0:1]
	s_waitcnt vmcnt(28)
	v_sub_f32_e32 v5, v101, v97
	v_fma_f32 v5, v76, v5, v97
	s_waitcnt vmcnt(25) lgkmcnt(4)
	v_sub_f32_e32 v8, v106, v97
	v_fmac_f32_e32 v5, v78, v8
	v_mul_f32_e32 v8, v81, v5
	v_mul_f32_e32 v9, v8, v8
	s_mov_b32 s0, 0xf800000
	v_sub_f32_e32 v11, v100, v96
	v_mov_b32_dpp v9, v9 quad_perm:[1,0,3,2] row_mask:0xf bank_mask:0xf bound_ctrl:1
	v_fmac_f32_e32 v9, v8, v8
	s_waitcnt lgkmcnt(2)
	v_sub_f32_e32 v12, v102, v96
	v_fma_f32 v14, v75, v11, v96
	v_add_f32_dpp v9, v9, v9 quad_perm:[2,3,0,1] row_mask:0xf bank_mask:0xf bound_ctrl:1
	v_fmac_f32_e32 v14, v77, v12
	v_sub_f32_e32 v13, v99, v98
	v_add_f32_dpp v9, v9, v9 row_half_mirror row_mask:0xf bank_mask:0xf bound_ctrl:1
	v_fma_f32 v13, v80, v13, v98
	v_lshl_or_b32 v129, v4, 6, v7
	v_add_f32_dpp v9, v9, v9 row_mirror row_mask:0xf bank_mask:0xf bound_ctrl:1
	v_mov_b32_e32 v10, v9
	s_nop 1
	v_permlane16_swap_b32_e32 v9, v10
	v_lshl_add_u32 v4, v129, 2, s33
	s_waitcnt lgkmcnt(0)
	v_add_f32_e32 v9, v9, v10
	v_mov_b32_e32 v10, v9
	s_nop 1
	v_permlane32_swap_b32_e32 v9, v10
	s_waitcnt lgkmcnt(0)
	v_add_f32_e32 v9, v9, v10
	v_mul_f32_e32 v10, 0x4f800000, v9
	v_cmp_gt_f32_e32 vcc, s0, v9
	s_nop 1
	v_cndmask_b32_e32 v9, v9, v10, vcc
	v_sqrt_f32_e32 v10, v9
	s_nop 0
	v_add_u32_e32 v11, -1, v10
	v_add_u32_e32 v12, 1, v10
	v_fma_f32 v15, -v11, v10, v9
	v_fma_f32 v16, -v12, v10, v9
	v_cmp_ge_f32_e64 s[44:45], 0, v15
	s_nop 1
	v_cndmask_b32_e64 v10, v10, v11, s[44:45]
	v_cmp_lt_f32_e64 s[44:45], 0, v16
	s_nop 1
	v_cndmask_b32_e64 v10, v10, v12, s[44:45]
	v_mul_f32_e32 v11, 0x37800000, v10
	v_cndmask_b32_e32 v10, v10, v11, vcc
	v_cmp_class_f32_e32 vcc, v9, v204
	s_waitcnt vmcnt(24)
	v_sub_f32_e32 v12, v105, v98
	v_fmac_f32_e32 v13, v79, v12
	v_cndmask_b32_e32 v9, v10, v9, vcc
	v_max_f32_e32 v9, 0x2b8cbccc, v9
	v_div_scale_f32 v10, s[0:1], v9, v9, v8
	v_rcp_f32_e32 v11, v10
	s_nop 0
	v_fma_f32 v12, -v10, v11, 1.0
	v_fmac_f32_e32 v11, v12, v11
	v_div_scale_f32 v12, vcc, v8, v9, v8
	v_mul_f32_e32 v15, v12, v11
	v_fma_f32 v16, -v10, v15, v12
	v_fmac_f32_e32 v15, v16, v11
	v_fma_f32 v10, -v10, v15, v12
	v_div_fmas_f32 v10, v10, v11, v15
	v_div_fixup_f32 v15, v10, v9, v8
	s_waitcnt vmcnt(23)
	v_add_f32_e32 v8, -1.0, v108
	v_fma_f32 v8, v82, v8, 1.0
	v_mul_f32_e32 v16, v5, v8
	v_mul_f32_e32 v5, v14, v16
	v_mul_f32_e32 v17, v108, v15
	v_mul_f32_e32 v8, v83, v5
	v_mul_f32_e32 v10, v14, v17
	v_xor_b32_e32 v15, 0x80000000, v15
	v_mov_b32_dpp v8, v8 quad_perm:[1,0,3,2] row_mask:0xf bank_mask:0xf bound_ctrl:1
	v_fmac_f32_e32 v8, v83, v5
	v_mov_b32_dpp v10, v10 quad_perm:[1,0,3,2] row_mask:0xf bank_mask:0xf bound_ctrl:1
	v_mov_b32_dpp v5, v5 quad_perm:[1,0,3,2] row_mask:0xf bank_mask:0xf bound_ctrl:1
	v_fmac_f32_e32 v10, v14, v17
	v_fmac_f32_e32 v5, v14, v16
	v_add_f32_dpp v8, v8, v8 quad_perm:[2,3,0,1] row_mask:0xf bank_mask:0xf bound_ctrl:1
	v_add_f32_dpp v10, v10, v10 quad_perm:[2,3,0,1] row_mask:0xf bank_mask:0xf bound_ctrl:1
	v_add_f32_dpp v5, v5, v5 quad_perm:[2,3,0,1] row_mask:0xf bank_mask:0xf bound_ctrl:1
	v_add_f32_dpp v8, v8, v8 row_half_mirror row_mask:0xf bank_mask:0xf bound_ctrl:1
	v_add_f32_dpp v10, v10, v10 row_half_mirror row_mask:0xf bank_mask:0xf bound_ctrl:1
	v_add_f32_dpp v5, v5, v5 row_half_mirror row_mask:0xf bank_mask:0xf bound_ctrl:1
	v_add_f32_dpp v8, v8, v8 row_mirror row_mask:0xf bank_mask:0xf bound_ctrl:1
	v_add_f32_dpp v10, v10, v10 row_mirror row_mask:0xf bank_mask:0xf bound_ctrl:1
	v_add_f32_dpp v12, v5, v5 row_mirror row_mask:0xf bank_mask:0xf bound_ctrl:1
	v_mov_b32_e32 v9, v8
	s_nop 1
	v_permlane16_swap_b32_e32 v8, v9
	v_mov_b32_e32 v11, v10
	s_nop 1
	v_permlane16_swap_b32_e32 v10, v11
	v_mov_b32_e32 v18, v12
	s_nop 1
	v_permlane16_swap_b32_e32 v12, v18
	s_waitcnt vmcnt(22)
	v_mul_f32_e32 v14, v14, v107
	ds_write2st64_b32 v4, v107, v15 offset1:16
	ds_write2st64_b32 v4, v17, v16 offset0:32 offset1:48
	s_waitcnt lgkmcnt(4)
	v_add_f32_e32 v5, v8, v9
	s_waitcnt lgkmcnt(3)
	v_add_f32_e32 v8, v10, v11
	s_waitcnt lgkmcnt(2)
	v_add_f32_e32 v11, v12, v18
	v_mov_b32_e32 v9, v5
	s_nop 1
	v_permlane32_swap_b32_e32 v5, v9
	v_mov_b32_e32 v10, v8
	s_nop 1
	v_permlane32_swap_b32_e32 v8, v10
	v_mov_b32_e32 v12, v11
	s_nop 1
	v_permlane32_swap_b32_e32 v11, v12
	ds_write2st64_b32 v4, v14, v13 offset0:64 offset1:80
	s_and_saveexec_b64 s[0:1], s[42:43]
	s_cbranch_execz .LBB0_556
	s_waitcnt lgkmcnt(1)
	v_add_f32_e32 v4, v11, v12
	v_add_f32_e32 v5, v5, v9
	v_add_f32_e32 v4, v5, v4
	v_add_f32_e32 v5, v8, v10
	v_add_u32_e32 v8, 0x6000, v0
	ds_write2_b32 v8, v5, v4 offset0:4 offset1:20
.LBB0_556:
	s_or_b64 exec, exec, s[0:1]
	s_waitcnt vmcnt(17)
	v_sub_f32_e32 v4, v114, v110
	v_fma_f32 v4, v76, v4, v110
	s_waitcnt vmcnt(14)
	v_sub_f32_e32 v5, v117, v110
	v_fmac_f32_e32 v4, v78, v5
	v_mul_f32_e32 v5, v81, v4
	v_mul_f32_e32 v8, v5, v5
	s_mov_b32 s0, 0xf800000
	s_waitcnt lgkmcnt(2)
	v_sub_f32_e32 v10, v113, v109
	v_mov_b32_dpp v8, v8 quad_perm:[1,0,3,2] row_mask:0xf bank_mask:0xf bound_ctrl:1
	v_fmac_f32_e32 v8, v5, v5
	v_sub_f32_e32 v11, v115, v109
	v_fma_f32 v13, v75, v10, v109
	v_add_f32_dpp v8, v8, v8 quad_perm:[2,3,0,1] row_mask:0xf bank_mask:0xf bound_ctrl:1
	v_fmac_f32_e32 v13, v77, v11
	s_waitcnt lgkmcnt(1)
	v_sub_f32_e32 v12, v112, v111
	v_add_f32_dpp v8, v8, v8 row_half_mirror row_mask:0xf bank_mask:0xf bound_ctrl:1
	v_fma_f32 v12, v80, v12, v111
	v_lshl_or_b32 v133, v3, 6, v7
	v_add_f32_dpp v8, v8, v8 row_mirror row_mask:0xf bank_mask:0xf bound_ctrl:1
	v_mov_b32_e32 v9, v8
	s_nop 1
	v_permlane16_swap_b32_e32 v8, v9
	v_lshl_add_u32 v3, v133, 2, s33
	s_waitcnt lgkmcnt(0)
	v_add_f32_e32 v8, v8, v9
	v_mov_b32_e32 v9, v8
	s_nop 1
	v_permlane32_swap_b32_e32 v8, v9
	s_waitcnt lgkmcnt(0)
	v_add_f32_e32 v8, v8, v9
	v_mul_f32_e32 v9, 0x4f800000, v8
	v_cmp_gt_f32_e32 vcc, s0, v8
	s_nop 1
	v_cndmask_b32_e32 v8, v8, v9, vcc
	v_sqrt_f32_e32 v9, v8
	s_nop 0
	v_add_u32_e32 v10, -1, v9
	v_add_u32_e32 v11, 1, v9
	v_fma_f32 v14, -v10, v9, v8
	v_fma_f32 v15, -v11, v9, v8
	v_cmp_ge_f32_e64 s[44:45], 0, v14
	s_nop 1
	v_cndmask_b32_e64 v9, v9, v10, s[44:45]
	v_cmp_lt_f32_e64 s[44:45], 0, v15
	s_nop 1
	v_cndmask_b32_e64 v9, v9, v11, s[44:45]
	v_mul_f32_e32 v10, 0x37800000, v9
	v_cndmask_b32_e32 v9, v9, v10, vcc
	v_cmp_class_f32_e32 vcc, v8, v204
	s_waitcnt vmcnt(13)
	v_sub_f32_e32 v11, v116, v111
	v_fmac_f32_e32 v12, v79, v11
	v_cndmask_b32_e32 v8, v9, v8, vcc
	v_max_f32_e32 v8, 0x2b8cbccc, v8
	v_div_scale_f32 v9, s[0:1], v8, v8, v5
	v_rcp_f32_e32 v10, v9
	s_nop 0
	v_fma_f32 v11, -v9, v10, 1.0
	v_fmac_f32_e32 v10, v11, v10
	v_div_scale_f32 v11, vcc, v5, v8, v5
	v_mul_f32_e32 v14, v11, v10
	v_fma_f32 v15, -v9, v14, v11
	v_fmac_f32_e32 v14, v15, v10
	v_fma_f32 v9, -v9, v14, v11
	v_div_fmas_f32 v9, v9, v10, v14
	v_div_fixup_f32 v14, v9, v8, v5
	s_waitcnt vmcnt(12)
	v_add_f32_e32 v5, -1.0, v120
	v_fma_f32 v5, v82, v5, 1.0
	v_mul_f32_e32 v15, v4, v5
	v_mul_f32_e32 v4, v13, v15
	v_mul_f32_e32 v16, v120, v14
	v_mul_f32_e32 v5, v83, v4
	v_mul_f32_e32 v9, v13, v16
	v_xor_b32_e32 v14, 0x80000000, v14
	v_mov_b32_dpp v5, v5 quad_perm:[1,0,3,2] row_mask:0xf bank_mask:0xf bound_ctrl:1
	v_fmac_f32_e32 v5, v83, v4
	v_mov_b32_dpp v9, v9 quad_perm:[1,0,3,2] row_mask:0xf bank_mask:0xf bound_ctrl:1
	v_mov_b32_dpp v4, v4 quad_perm:[1,0,3,2] row_mask:0xf bank_mask:0xf bound_ctrl:1
	v_fmac_f32_e32 v9, v13, v16
	v_fmac_f32_e32 v4, v13, v15
	v_add_f32_dpp v5, v5, v5 quad_perm:[2,3,0,1] row_mask:0xf bank_mask:0xf bound_ctrl:1
	v_add_f32_dpp v9, v9, v9 quad_perm:[2,3,0,1] row_mask:0xf bank_mask:0xf bound_ctrl:1
	v_add_f32_dpp v4, v4, v4 quad_perm:[2,3,0,1] row_mask:0xf bank_mask:0xf bound_ctrl:1
	v_add_f32_dpp v5, v5, v5 row_half_mirror row_mask:0xf bank_mask:0xf bound_ctrl:1
	v_add_f32_dpp v9, v9, v9 row_half_mirror row_mask:0xf bank_mask:0xf bound_ctrl:1
	v_add_f32_dpp v4, v4, v4 row_half_mirror row_mask:0xf bank_mask:0xf bound_ctrl:1
	v_add_f32_dpp v5, v5, v5 row_mirror row_mask:0xf bank_mask:0xf bound_ctrl:1
	v_add_f32_dpp v9, v9, v9 row_mirror row_mask:0xf bank_mask:0xf bound_ctrl:1
	v_add_f32_dpp v11, v4, v4 row_mirror row_mask:0xf bank_mask:0xf bound_ctrl:1
	v_mov_b32_e32 v8, v5
	s_nop 1
	v_permlane16_swap_b32_e32 v5, v8
	v_mov_b32_e32 v10, v9
	s_nop 1
	v_permlane16_swap_b32_e32 v9, v10
	v_mov_b32_e32 v17, v11
	s_nop 1
	v_permlane16_swap_b32_e32 v11, v17
	s_waitcnt vmcnt(11)
	v_mul_f32_e32 v13, v13, v119
	ds_write2st64_b32 v3, v119, v14 offset1:16
	ds_write2st64_b32 v3, v16, v15 offset0:32 offset1:48
	s_waitcnt lgkmcnt(4)
	v_add_f32_e32 v4, v5, v8
	s_waitcnt lgkmcnt(3)
	v_add_f32_e32 v5, v9, v10
	s_waitcnt lgkmcnt(2)
	v_add_f32_e32 v10, v11, v17
	v_mov_b32_e32 v8, v4
	s_nop 1
	v_permlane32_swap_b32_e32 v4, v8
	v_mov_b32_e32 v9, v5
	s_nop 1
	v_permlane32_swap_b32_e32 v5, v9
	v_mov_b32_e32 v11, v10
	s_nop 1
	v_permlane32_swap_b32_e32 v10, v11
	ds_write2st64_b32 v3, v13, v12 offset0:64 offset1:80
	s_and_saveexec_b64 s[0:1], s[42:43]
	s_cbranch_execz .LBB0_558
	s_waitcnt lgkmcnt(1)
	v_add_f32_e32 v3, v10, v11
	v_add_f32_e32 v4, v4, v8
	v_add_f32_e32 v3, v4, v3
	v_add_f32_e32 v4, v5, v9
	v_add_u32_e32 v5, 0x6000, v0
	ds_write2_b32 v5, v4, v3 offset0:8 offset1:24
.LBB0_558:
	s_or_b64 exec, exec, s[0:1]
	s_waitcnt vmcnt(6)
	v_sub_f32_e32 v3, v126, v122
	v_fma_f32 v3, v76, v3, v122
	s_waitcnt vmcnt(3)
	v_sub_f32_e32 v4, v130, v122
	v_fmac_f32_e32 v3, v78, v4
	v_mul_f32_e32 v4, v81, v3
	v_mul_f32_e32 v5, v4, v4
	s_mov_b32 s0, 0xf800000
	s_waitcnt lgkmcnt(2)
	v_sub_f32_e32 v9, v125, v121
	v_mov_b32_dpp v5, v5 quad_perm:[1,0,3,2] row_mask:0xf bank_mask:0xf bound_ctrl:1
	v_fmac_f32_e32 v5, v4, v4
	v_sub_f32_e32 v10, v127, v121
	v_fma_f32 v12, v75, v9, v121
	v_add_f32_dpp v5, v5, v5 quad_perm:[2,3,0,1] row_mask:0xf bank_mask:0xf bound_ctrl:1
	v_fmac_f32_e32 v12, v77, v10
	s_waitcnt lgkmcnt(1)
	v_sub_f32_e32 v11, v124, v123
	v_add_f32_dpp v5, v5, v5 row_half_mirror row_mask:0xf bank_mask:0xf bound_ctrl:1
	v_fma_f32 v11, v80, v11, v123
	v_lshl_or_b32 v137, v2, 6, v7
	v_add_f32_dpp v5, v5, v5 row_mirror row_mask:0xf bank_mask:0xf bound_ctrl:1
	v_mov_b32_e32 v8, v5
	s_nop 1
	v_permlane16_swap_b32_e32 v5, v8
	v_lshl_add_u32 v2, v137, 2, s33
	s_waitcnt lgkmcnt(0)
	v_add_f32_e32 v5, v5, v8
	v_mov_b32_e32 v8, v5
	s_nop 1
	v_permlane32_swap_b32_e32 v5, v8
	s_waitcnt lgkmcnt(0)
	v_add_f32_e32 v5, v5, v8
	v_mul_f32_e32 v8, 0x4f800000, v5
	v_cmp_gt_f32_e32 vcc, s0, v5
	s_nop 1
	v_cndmask_b32_e32 v5, v5, v8, vcc
	v_sqrt_f32_e32 v8, v5
	s_nop 0
	v_add_u32_e32 v9, -1, v8
	v_add_u32_e32 v10, 1, v8
	v_fma_f32 v13, -v9, v8, v5
	v_fma_f32 v14, -v10, v8, v5
	v_cmp_ge_f32_e64 s[44:45], 0, v13
	s_nop 1
	v_cndmask_b32_e64 v8, v8, v9, s[44:45]
	v_cmp_lt_f32_e64 s[44:45], 0, v14
	s_nop 1
	v_cndmask_b32_e64 v8, v8, v10, s[44:45]
	v_mul_f32_e32 v9, 0x37800000, v8
	v_cndmask_b32_e32 v8, v8, v9, vcc
	v_cmp_class_f32_e32 vcc, v5, v204
	s_waitcnt vmcnt(2)
	v_sub_f32_e32 v10, v128, v123
	v_fmac_f32_e32 v11, v79, v10
	v_cndmask_b32_e32 v5, v8, v5, vcc
	v_max_f32_e32 v5, 0x2b8cbccc, v5
	v_div_scale_f32 v8, s[0:1], v5, v5, v4
	v_rcp_f32_e32 v9, v8
	s_nop 0
	v_fma_f32 v10, -v8, v9, 1.0
	v_fmac_f32_e32 v9, v10, v9
	v_div_scale_f32 v10, vcc, v4, v5, v4
	v_mul_f32_e32 v13, v10, v9
	v_fma_f32 v14, -v8, v13, v10
	v_fmac_f32_e32 v13, v14, v9
	v_fma_f32 v8, -v8, v13, v10
	v_div_fmas_f32 v8, v8, v9, v13
	v_div_fixup_f32 v13, v8, v5, v4
	s_waitcnt vmcnt(0)
	v_add_f32_e32 v4, -1.0, v132
	v_fma_f32 v4, v82, v4, 1.0
	v_mul_f32_e32 v14, v3, v4
	v_mul_f32_e32 v3, v12, v14
	v_mul_f32_e32 v15, v132, v13
	v_mul_f32_e32 v4, v83, v3
	v_mul_f32_e32 v8, v12, v15
	v_xor_b32_e32 v7, 0x80000000, v13
	v_mov_b32_dpp v4, v4 quad_perm:[1,0,3,2] row_mask:0xf bank_mask:0xf bound_ctrl:1
	v_fmac_f32_e32 v4, v83, v3
	v_mov_b32_dpp v8, v8 quad_perm:[1,0,3,2] row_mask:0xf bank_mask:0xf bound_ctrl:1
	v_mov_b32_dpp v3, v3 quad_perm:[1,0,3,2] row_mask:0xf bank_mask:0xf bound_ctrl:1
	v_fmac_f32_e32 v8, v12, v15
	v_fmac_f32_e32 v3, v12, v14
	v_add_f32_dpp v4, v4, v4 quad_perm:[2,3,0,1] row_mask:0xf bank_mask:0xf bound_ctrl:1
	v_add_f32_dpp v8, v8, v8 quad_perm:[2,3,0,1] row_mask:0xf bank_mask:0xf bound_ctrl:1
	v_add_f32_dpp v3, v3, v3 quad_perm:[2,3,0,1] row_mask:0xf bank_mask:0xf bound_ctrl:1
	v_add_f32_dpp v4, v4, v4 row_half_mirror row_mask:0xf bank_mask:0xf bound_ctrl:1
	v_add_f32_dpp v8, v8, v8 row_half_mirror row_mask:0xf bank_mask:0xf bound_ctrl:1
	v_add_f32_dpp v3, v3, v3 row_half_mirror row_mask:0xf bank_mask:0xf bound_ctrl:1
	v_add_f32_dpp v4, v4, v4 row_mirror row_mask:0xf bank_mask:0xf bound_ctrl:1
	v_add_f32_dpp v8, v8, v8 row_mirror row_mask:0xf bank_mask:0xf bound_ctrl:1
	v_add_f32_dpp v10, v3, v3 row_mirror row_mask:0xf bank_mask:0xf bound_ctrl:1
	v_mov_b32_e32 v5, v4
	s_nop 1
	v_permlane16_swap_b32_e32 v4, v5
	v_mov_b32_e32 v9, v8
	s_nop 1
	v_permlane16_swap_b32_e32 v8, v9
	v_mov_b32_e32 v16, v10
	s_nop 1
	v_permlane16_swap_b32_e32 v10, v16
	ds_write2st64_b32 v2, v131, v7 offset1:16
	ds_write2st64_b32 v2, v15, v14 offset0:32 offset1:48
	v_mul_f32_e32 v7, v12, v131
	s_waitcnt lgkmcnt(4)
	v_add_f32_e32 v3, v4, v5
	s_waitcnt lgkmcnt(3)
	v_add_f32_e32 v4, v8, v9
	s_waitcnt lgkmcnt(2)
	v_add_f32_e32 v9, v10, v16
	v_mov_b32_e32 v5, v3
	s_nop 1
	v_permlane32_swap_b32_e32 v3, v5
	v_mov_b32_e32 v8, v4
	s_nop 1
	v_permlane32_swap_b32_e32 v4, v8
	v_mov_b32_e32 v10, v9
	s_nop 1
	v_permlane32_swap_b32_e32 v9, v10
	ds_write2st64_b32 v2, v7, v11 offset0:64 offset1:80
	s_and_saveexec_b64 s[0:1], s[42:43]
	s_cbranch_execz .LBB0_560
	s_waitcnt lgkmcnt(1)
	v_add_f32_e32 v2, v9, v10
	v_add_f32_e32 v3, v3, v5
	v_add_f32_e32 v2, v3, v2
	v_add_f32_e32 v3, v4, v8
	v_add_u32_e32 v0, 0x6000, v0
	ds_write2_b32 v0, v3, v2 offset0:12 offset1:28

.LBB0_595:
	s_bitcmp1_b32 s30, 0
	s_cselect_b32 s46, 0x6080, 0
	s_add_i32 s0, s33, s46
	v_lshl_add_u32 v140, v136, 2, s0
	v_add_u32_e32 v141, s46, v138
	s_add_i32 s0, s50, s46
	v_mov_b32_e32 v231, s0
	s_add_i32 s0, s88, -1
	s_add_i32 s1, s89, 1
	s_movk_i32 s91, 0x800
	s_movk_i32 s92, 0xf800
	s_and_b64 s[94:95], s[40:41], exec
	s_cselect_b32 s30, s0, s1
	s_cselect_b32 s91, s91, s92
	s_add_i32 s30, s30, s53
	s_lshl_b32 s30, s30, 11
	s_movk_i32 s47, 8
	s_waitcnt lgkmcnt(0)
	ds_read_b128 v[18:21], v140 offset:4096
	ds_read_b128 v[22:25], v140 offset:4112
	ds_read_b128 v[26:29], v140 offset:16384
	ds_read_b128 v[30:33], v140 offset:16400
	ds_read_b64 v[66:67], v141
	ds_read2_b32 v[68:69], v231 offset0:0 offset1:16
	ds_read_b128 v[42:45], v140 offset:8192
	ds_read_b128 v[46:49], v140 offset:8208
	ds_read_b128 v[34:37], v140
	ds_read_b128 v[38:41], v140 offset:16
	ds_read_b128 v[50:53], v140 offset:12288
	ds_read_b128 v[54:57], v140 offset:12304
.Lscan1_loop:
	s_waitcnt lgkmcnt(0)
	ds_read_b128 v[162:165], v140 offset:4352
	ds_read_b128 v[166:169], v140 offset:4368
	ds_read_b128 v[170:173], v140 offset:16640
	ds_read_b128 v[174:177], v140 offset:16656
	ds_read_b64 v[240:241], v141 offset:256
	ds_read2_b32 v[242:243], v231 offset0:1 offset1:17
	ds_read_b128 v[186:189], v140 offset:8448
	ds_read_b128 v[190:193], v140 offset:8464
	ds_read_b128 v[178:181], v140 offset:256
	ds_read_b128 v[182:185], v140 offset:272
	ds_read_b128 v[232:235], v140 offset:12544
	ds_read_b128 v[236:239], v140 offset:12560
	v_pk_mul_f32 v[142:143], v[18:19], v[14:15]
	v_pk_mul_f32 v[144:145], v[18:19], v[6:7]
	v_pk_mul_f32 v[244:245], v[26:27], v[14:15]
	v_pk_mul_f32 v[246:247], v[26:27], v[6:7]
	v_pk_fma_f32 v[142:143], v[20:21], v[16:17], v[142:143]
	v_pk_fma_f32 v[144:145], v[20:21], v[8:9], v[144:145]
	v_pk_fma_f32 v[244:245], v[28:29], v[16:17], v[244:245]
	v_pk_fma_f32 v[246:247], v[28:29], v[8:9], v[246:247]
	v_pk_fma_f32 v[142:143], v[22:23], v[10:11], v[142:143]
	v_pk_fma_f32 v[144:145], v[22:23], v[2:3], v[144:145]
	v_pk_fma_f32 v[244:245], v[30:31], v[10:11], v[244:245]
	v_pk_fma_f32 v[246:247], v[30:31], v[2:3], v[246:247]
	v_pk_fma_f32 v[142:143], v[24:25], v[12:13], v[142:143]
	v_pk_fma_f32 v[144:145], v[24:25], v[4:5], v[144:145]
	v_pk_fma_f32 v[244:245], v[32:33], v[12:13], v[244:245]
	v_pk_fma_f32 v[246:247], v[32:33], v[4:5], v[246:247]
	v_add_f32_e32 v70, v142, v143
	v_add_f32_e32 v71, v144, v145
	v_add_f32_e32 v72, v244, v245
	v_add_f32_e32 v73, v246, v247
	v_add_f32_dpp v70, v70, v70 quad_perm:[1,0,3,2] row_mask:0xf bank_mask:0xf bound_ctrl:1
	v_add_f32_dpp v71, v71, v71 quad_perm:[1,0,3,2] row_mask:0xf bank_mask:0xf bound_ctrl:1
	v_add_f32_dpp v72, v72, v72 quad_perm:[1,0,3,2] row_mask:0xf bank_mask:0xf bound_ctrl:1
	v_add_f32_dpp v73, v73, v73 quad_perm:[1,0,3,2] row_mask:0xf bank_mask:0xf bound_ctrl:1
	v_add_f32_dpp v70, v70, v70 quad_perm:[2,3,0,1] row_mask:0xf bank_mask:0xf bound_ctrl:1
	v_add_f32_dpp v71, v71, v71 quad_perm:[2,3,0,1] row_mask:0xf bank_mask:0xf bound_ctrl:1
	v_add_f32_dpp v72, v72, v72 quad_perm:[2,3,0,1] row_mask:0xf bank_mask:0xf bound_ctrl:1
	v_add_f32_dpp v73, v73, v73 quad_perm:[2,3,0,1] row_mask:0xf bank_mask:0xf bound_ctrl:1
	v_add_f32_dpp v70, v70, v70 row_half_mirror row_mask:0xf bank_mask:0xf bound_ctrl:1
	v_add_f32_dpp v71, v71, v71 row_half_mirror row_mask:0xf bank_mask:0xf bound_ctrl:1
	v_add_f32_dpp v72, v72, v72 row_half_mirror row_mask:0xf bank_mask:0xf bound_ctrl:1
	v_add_f32_dpp v73, v73, v73 row_half_mirror row_mask:0xf bank_mask:0xf bound_ctrl:1
	v_pk_fma_f32 v[72:73], v[70:71], v[68:69], v[72:73] op_sel_hi:[1,0,1]
	v_pk_fma_f32 v[72:73], v[66:67], v[68:69], v[72:73] op_sel:[0,1,0]
	v_lshl_add_u64 v[248:249], v[64:65], 0, s[30:31]
	s_and_saveexec_b64 s[0:1], s[44:45]
	global_store_dwordx2 v[248:249], v[72:73], off
	s_mov_b64 exec, s[0:1]
	s_add_i32 s30, s30, s91
	v_pk_mul_f32 v[142:143], v[70:71], v[42:43] op_sel_hi:[0,1]
	v_pk_mul_f32 v[144:145], v[70:71], v[42:43] op_sel:[1,0]
	v_pk_fma_f32 v[14:15], v[14:15], v[34:35], v[142:143]
	v_pk_fma_f32 v[6:7], v[6:7], v[34:35], v[144:145]
	v_pk_fma_f32 v[14:15], v[66:67], v[50:51], v[14:15] op_sel_hi:[0,1,1]
	v_pk_fma_f32 v[6:7], v[66:67], v[50:51], v[6:7] op_sel:[1,0,0]
	v_pk_mul_f32 v[244:245], v[70:71], v[44:45] op_sel_hi:[0,1]
	v_pk_mul_f32 v[246:247], v[70:71], v[44:45] op_sel:[1,0]
	v_pk_fma_f32 v[16:17], v[16:17], v[36:37], v[244:245]
	v_pk_fma_f32 v[8:9], v[8:9], v[36:37], v[246:247]
	v_pk_fma_f32 v[16:17], v[66:67], v[52:53], v[16:17] op_sel_hi:[0,1,1]
	v_pk_fma_f32 v[8:9], v[66:67], v[52:53], v[8:9] op_sel:[1,0,0]
	v_pk_mul_f32 v[142:143], v[70:71], v[46:47] op_sel_hi:[0,1]
	v_pk_mul_f32 v[144:145], v[70:71], v[46:47] op_sel:[1,0]
	v_pk_fma_f32 v[10:11], v[10:11], v[38:39], v[142:143]
	v_pk_fma_f32 v[2:3], v[2:3], v[38:39], v[144:145]
	v_pk_fma_f32 v[10:11], v[66:67], v[54:55], v[10:11] op_sel_hi:[0,1,1]
	v_pk_fma_f32 v[2:3], v[66:67], v[54:55], v[2:3] op_sel:[1,0,0]
	v_pk_mul_f32 v[244:245], v[70:71], v[48:49] op_sel_hi:[0,1]
	v_pk_mul_f32 v[246:247], v[70:71], v[48:49] op_sel:[1,0]
	v_pk_fma_f32 v[12:13], v[12:13], v[40:41], v[244:245]
	v_pk_fma_f32 v[4:5], v[4:5], v[40:41], v[246:247]
	v_pk_fma_f32 v[12:13], v[66:67], v[56:57], v[12:13] op_sel_hi:[0,1,1]
	v_pk_fma_f32 v[4:5], v[66:67], v[56:57], v[4:5] op_sel:[1,0,0]
	s_waitcnt lgkmcnt(0)
	ds_read_b128 v[18:21], v140 offset:4608
	ds_read_b128 v[22:25], v140 offset:4624
	ds_read_b128 v[26:29], v140 offset:16896
	ds_read_b128 v[30:33], v140 offset:16912
	ds_read_b64 v[66:67], v141 offset:512
	ds_read2_b32 v[68:69], v231 offset0:2 offset1:18
	ds_read_b128 v[42:45], v140 offset:8704
	ds_read_b128 v[46:49], v140 offset:8720
	ds_read_b128 v[34:37], v140 offset:512
	ds_read_b128 v[38:41], v140 offset:528
	ds_read_b128 v[50:53], v140 offset:12800
	ds_read_b128 v[54:57], v140 offset:12816
	v_pk_mul_f32 v[142:143], v[162:163], v[14:15]
	v_pk_mul_f32 v[144:145], v[162:163], v[6:7]
	v_pk_mul_f32 v[244:245], v[170:171], v[14:15]
	v_pk_mul_f32 v[246:247], v[170:171], v[6:7]
	v_pk_fma_f32 v[142:143], v[164:165], v[16:17], v[142:143]
	v_pk_fma_f32 v[144:145], v[164:165], v[8:9], v[144:145]
	v_pk_fma_f32 v[244:245], v[172:173], v[16:17], v[244:245]
	v_pk_fma_f32 v[246:247], v[172:173], v[8:9], v[246:247]
	v_pk_fma_f32 v[142:143], v[166:167], v[10:11], v[142:143]
	v_pk_fma_f32 v[144:145], v[166:167], v[2:3], v[144:145]
	v_pk_fma_f32 v[244:245], v[174:175], v[10:11], v[244:245]
	v_pk_fma_f32 v[246:247], v[174:175], v[2:3], v[246:247]
	v_pk_fma_f32 v[142:143], v[168:169], v[12:13], v[142:143]
	v_pk_fma_f32 v[144:145], v[168:169], v[4:5], v[144:145]
	v_pk_fma_f32 v[244:245], v[176:177], v[12:13], v[244:245]
	v_pk_fma_f32 v[246:247], v[176:177], v[4:5], v[246:247]
	v_add_f32_e32 v70, v142, v143
	v_add_f32_e32 v71, v144, v145
	v_add_f32_e32 v72, v244, v245
	v_add_f32_e32 v73, v246, v247
	v_add_f32_dpp v70, v70, v70 quad_perm:[1,0,3,2] row_mask:0xf bank_mask:0xf bound_ctrl:1
	v_add_f32_dpp v71, v71, v71 quad_perm:[1,0,3,2] row_mask:0xf bank_mask:0xf bound_ctrl:1
	v_add_f32_dpp v72, v72, v72 quad_perm:[1,0,3,2] row_mask:0xf bank_mask:0xf bound_ctrl:1
	v_add_f32_dpp v73, v73, v73 quad_perm:[1,0,3,2] row_mask:0xf bank_mask:0xf bound_ctrl:1
	v_add_f32_dpp v70, v70, v70 quad_perm:[2,3,0,1] row_mask:0xf bank_mask:0xf bound_ctrl:1
	v_add_f32_dpp v71, v71, v71 quad_perm:[2,3,0,1] row_mask:0xf bank_mask:0xf bound_ctrl:1
	v_add_f32_dpp v72, v72, v72 quad_perm:[2,3,0,1] row_mask:0xf bank_mask:0xf bound_ctrl:1
	v_add_f32_dpp v73, v73, v73 quad_perm:[2,3,0,1] row_mask:0xf bank_mask:0xf bound_ctrl:1
	v_add_f32_dpp v70, v70, v70 row_half_mirror row_mask:0xf bank_mask:0xf bound_ctrl:1
	v_add_f32_dpp v71, v71, v71 row_half_mirror row_mask:0xf bank_mask:0xf bound_ctrl:1
	v_add_f32_dpp v72, v72, v72 row_half_mirror row_mask:0xf bank_mask:0xf bound_ctrl:1
	v_add_f32_dpp v73, v73, v73 row_half_mirror row_mask:0xf bank_mask:0xf bound_ctrl:1
	v_pk_fma_f32 v[72:73], v[70:71], v[242:243], v[72:73] op_sel_hi:[1,0,1]
	v_pk_fma_f32 v[72:73], v[240:241], v[242:243], v[72:73] op_sel:[0,1,0]
	v_lshl_add_u64 v[248:249], v[64:65], 0, s[30:31]
	s_and_saveexec_b64 s[0:1], s[44:45]
	global_store_dwordx2 v[248:249], v[72:73], off
	s_mov_b64 exec, s[0:1]
	s_add_i32 s30, s30, s91
	v_pk_mul_f32 v[142:143], v[70:71], v[186:187] op_sel_hi:[0,1]
	v_pk_mul_f32 v[144:145], v[70:71], v[186:187] op_sel:[1,0]
	v_pk_fma_f32 v[14:15], v[14:15], v[178:179], v[142:143]
	v_pk_fma_f32 v[6:7], v[6:7], v[178:179], v[144:145]
	v_pk_fma_f32 v[14:15], v[240:241], v[232:233], v[14:15] op_sel_hi:[0,1,1]
	v_pk_fma_f32 v[6:7], v[240:241], v[232:233], v[6:7] op_sel:[1,0,0]
	v_pk_mul_f32 v[244:245], v[70:71], v[188:189] op_sel_hi:[0,1]
	v_pk_mul_f32 v[246:247], v[70:71], v[188:189] op_sel:[1,0]
	v_pk_fma_f32 v[16:17], v[16:17], v[180:181], v[244:245]
	v_pk_fma_f32 v[8:9], v[8:9], v[180:181], v[246:247]
	v_pk_fma_f32 v[16:17], v[240:241], v[234:235], v[16:17] op_sel_hi:[0,1,1]
	v_pk_fma_f32 v[8:9], v[240:241], v[234:235], v[8:9] op_sel:[1,0,0]
	v_pk_mul_f32 v[142:143], v[70:71], v[190:191] op_sel_hi:[0,1]
	v_pk_mul_f32 v[144:145], v[70:71], v[190:191] op_sel:[1,0]
	v_pk_fma_f32 v[10:11], v[10:11], v[182:183], v[142:143]
	v_pk_fma_f32 v[2:3], v[2:3], v[182:183], v[144:145]
	v_pk_fma_f32 v[10:11], v[240:241], v[236:237], v[10:11] op_sel_hi:[0,1,1]
	v_pk_fma_f32 v[2:3], v[240:241], v[236:237], v[2:3] op_sel:[1,0,0]
	v_pk_mul_f32 v[244:245], v[70:71], v[192:193] op_sel_hi:[0,1]
	v_pk_mul_f32 v[246:247], v[70:71], v[192:193] op_sel:[1,0]
	v_pk_fma_f32 v[12:13], v[12:13], v[184:185], v[244:245]
	v_pk_fma_f32 v[4:5], v[4:5], v[184:185], v[246:247]
	v_pk_fma_f32 v[12:13], v[240:241], v[238:239], v[12:13] op_sel_hi:[0,1,1]
	v_pk_fma_f32 v[4:5], v[240:241], v[238:239], v[4:5] op_sel:[1,0,0]
	v_add_u32_e32 v140, 0x200, v140
	v_add_u32_e32 v141, 0x200, v141
	v_add_u32_e32 v231, 8, v231
	s_add_i32 s47, s47, -1
	s_cmp_lg_u32 s47, 0
	s_cbranch_scc1 .Lscan1_loop
.LBB0_601:
	s_and_b64 vcc, exec, s[28:29]
	s_cbranch_vccz .LBB0_611
	s_waitcnt vmcnt(17)
	v_sub_f32_e32 v0, v89, v85
	v_fma_f32 v0, v76, v0, v85
	v_sub_f32_e32 v18, v93, v85
	v_fmac_f32_e32 v0, v78, v18
	v_mul_f32_e32 v18, v81, v0
	v_mul_f32_e32 v19, v18, v18
	s_mov_b32 s1, 0xf800000
	v_sub_f32_e32 v21, v88, v84
	v_mov_b32_dpp v19, v19 quad_perm:[1,0,3,2] row_mask:0xf bank_mask:0xf bound_ctrl:1
	v_fmac_f32_e32 v19, v18, v18
	v_sub_f32_e32 v22, v91, v84
	v_fma_f32 v24, v75, v21, v84
	v_add_f32_dpp v19, v19, v19 quad_perm:[2,3,0,1] row_mask:0xf bank_mask:0xf bound_ctrl:1
	v_fmac_f32_e32 v24, v77, v22
	s_bitcmp1_b32 s90, 0
	v_add_f32_dpp v19, v19, v19 row_half_mirror row_mask:0xf bank_mask:0xf bound_ctrl:1
	s_cselect_b32 s0, 0x6080, 0
	s_add_i32 s28, s33, s0
	v_add_f32_dpp v19, v19, v19 row_mirror row_mask:0xf bank_mask:0xf bound_ctrl:1
	v_mov_b32_e32 v20, v19
	s_nop 1
	v_permlane16_swap_b32_e32 v19, v20
	v_sub_f32_e32 v23, v87, v86
	v_fma_f32 v25, v80, v23, v86
	s_waitcnt lgkmcnt(0)
	v_add_f32_e32 v19, v19, v20
	v_mov_b32_e32 v20, v19
	s_nop 1
	v_permlane32_swap_b32_e32 v19, v20
	s_waitcnt lgkmcnt(0)
	v_add_f32_e32 v19, v19, v20
	v_mul_f32_e32 v20, 0x4f800000, v19
	v_cmp_gt_f32_e32 vcc, s1, v19
	s_nop 1
	v_cndmask_b32_e32 v19, v19, v20, vcc
	v_sqrt_f32_e32 v20, v19
	s_nop 0
	v_add_u32_e32 v21, -1, v20
	v_fma_f32 v22, -v21, v20, v19
	v_cmp_ge_f32_e64 s[46:47], 0, v22
	v_add_u32_e32 v22, 1, v20
	s_nop 0
	v_cndmask_b32_e64 v21, v20, v21, s[46:47]
	v_fma_f32 v20, -v22, v20, v19
	v_cmp_lt_f32_e64 s[46:47], 0, v20
	s_nop 1
	v_cndmask_b32_e64 v20, v21, v22, s[46:47]
	v_mul_f32_e32 v21, 0x37800000, v20
	v_cndmask_b32_e32 v20, v20, v21, vcc
	v_cmp_class_f32_e32 vcc, v19, v204
	v_sub_f32_e32 v22, v92, v86
	v_fmac_f32_e32 v25, v79, v22
	v_cndmask_b32_e32 v19, v20, v19, vcc
	v_max_f32_e32 v19, 0x2b8cbccc, v19
	v_div_scale_f32 v20, s[0:1], v19, v19, v18
	v_rcp_f32_e32 v21, v20
	s_nop 0
	v_fma_f32 v22, -v20, v21, 1.0
	v_fmac_f32_e32 v21, v22, v21
	v_div_scale_f32 v22, vcc, v18, v19, v18
	v_mul_f32_e32 v23, v22, v21
	v_fma_f32 v26, -v20, v23, v22
	v_fmac_f32_e32 v23, v26, v21
	v_fma_f32 v20, -v20, v23, v22
	v_div_fmas_f32 v20, v20, v21, v23
	v_div_fixup_f32 v26, v20, v19, v18
	s_waitcnt vmcnt(16)
	v_add_f32_e32 v18, -1.0, v95
	v_fma_f32 v18, v82, v18, 1.0
	v_mul_f32_e32 v0, v0, v18
	v_mul_f32_e32 v18, v24, v0
	v_mul_f32_e32 v27, v95, v26
	v_mul_f32_e32 v19, v83, v18
	v_mul_f32_e32 v21, v24, v27
	v_xor_b32_e32 v26, 0x80000000, v26
	v_mov_b32_dpp v19, v19 quad_perm:[1,0,3,2] row_mask:0xf bank_mask:0xf bound_ctrl:1
	v_fmac_f32_e32 v19, v83, v18
	v_mov_b32_dpp v21, v21 quad_perm:[1,0,3,2] row_mask:0xf bank_mask:0xf bound_ctrl:1
	v_mov_b32_dpp v18, v18 quad_perm:[1,0,3,2] row_mask:0xf bank_mask:0xf bound_ctrl:1
	v_fmac_f32_e32 v21, v24, v27
	v_fmac_f32_e32 v18, v24, v0
	v_add_f32_dpp v19, v19, v19 quad_perm:[2,3,0,1] row_mask:0xf bank_mask:0xf bound_ctrl:1
	v_add_f32_dpp v21, v21, v21 quad_perm:[2,3,0,1] row_mask:0xf bank_mask:0xf bound_ctrl:1
	v_add_f32_dpp v18, v18, v18 quad_perm:[2,3,0,1] row_mask:0xf bank_mask:0xf bound_ctrl:1
	v_add_f32_dpp v19, v19, v19 row_half_mirror row_mask:0xf bank_mask:0xf bound_ctrl:1
	v_add_f32_dpp v21, v21, v21 row_half_mirror row_mask:0xf bank_mask:0xf bound_ctrl:1
	v_add_f32_dpp v18, v18, v18 row_half_mirror row_mask:0xf bank_mask:0xf bound_ctrl:1
	v_add_f32_dpp v19, v19, v19 row_mirror row_mask:0xf bank_mask:0xf bound_ctrl:1
	v_add_f32_dpp v21, v21, v21 row_mirror row_mask:0xf bank_mask:0xf bound_ctrl:1
	v_add_f32_dpp v23, v18, v18 row_mirror row_mask:0xf bank_mask:0xf bound_ctrl:1
	v_mov_b32_e32 v20, v19
	s_nop 1
	v_permlane16_swap_b32_e32 v19, v20
	v_mov_b32_e32 v22, v21
	s_nop 1
	v_permlane16_swap_b32_e32 v21, v22
	v_mov_b32_e32 v28, v23
	s_nop 1
	v_permlane16_swap_b32_e32 v23, v28
	s_waitcnt vmcnt(15)
	v_mul_f32_e32 v24, v24, v94
	s_waitcnt lgkmcnt(2)
	v_add_f32_e32 v18, v19, v20
	s_waitcnt lgkmcnt(1)
	v_add_f32_e32 v19, v21, v22
	s_waitcnt lgkmcnt(0)
	v_add_f32_e32 v22, v23, v28
	v_mov_b32_e32 v20, v18
	s_nop 1
	v_permlane32_swap_b32_e32 v18, v20
	v_mov_b32_e32 v21, v19
	s_nop 1
	v_permlane32_swap_b32_e32 v19, v21
	v_mov_b32_e32 v23, v22
	s_nop 1
	v_permlane32_swap_b32_e32 v22, v23
	v_lshl_add_u32 v28, v90, 2, s28
	ds_write_b32 v28, v94
	v_lshl_add_u32 v28, v118, 2, s28
	ds_write2st64_b32 v28, v26, v27 offset0:16 offset1:32
	ds_write2st64_b32 v28, v0, v24 offset0:48 offset1:64
	ds_write_b32 v28, v25 offset:20480
	v_lshl_add_u32 v0, v74, 2, s28
	s_and_saveexec_b64 s[0:1], s[42:43]
	s_cbranch_execz .LBB0_604
	s_waitcnt lgkmcnt(4)
	v_add_f32_e32 v22, v22, v23
	v_add_f32_e32 v18, v18, v20
	v_add_f32_e32 v18, v18, v22
	v_add_f32_e32 v19, v19, v21
	v_add_u32_e32 v20, 0x6000, v0
	ds_write2_b32 v20, v19, v18 offset1:16
.LBB0_604:
	s_or_b64 exec, exec, s[0:1]
	s_waitcnt vmcnt(12)
	v_sub_f32_e32 v18, v101, v97
	v_fma_f32 v18, v76, v18, v97
	v_sub_f32_e32 v19, v106, v97
	v_fmac_f32_e32 v18, v78, v19
	v_mul_f32_e32 v19, v81, v18
	s_waitcnt lgkmcnt(6)
	v_mul_f32_e32 v20, v19, v19
	s_mov_b32 s0, 0xf800000
	v_sub_f32_e32 v22, v100, v96
	v_mov_b32_dpp v20, v20 quad_perm:[1,0,3,2] row_mask:0xf bank_mask:0xf bound_ctrl:1
	v_fmac_f32_e32 v20, v19, v19
	s_waitcnt lgkmcnt(4)
	v_sub_f32_e32 v23, v102, v96
	v_fma_f32 v25, v75, v22, v96
	v_add_f32_dpp v20, v20, v20 quad_perm:[2,3,0,1] row_mask:0xf bank_mask:0xf bound_ctrl:1
	v_fmac_f32_e32 v25, v77, v23
	v_sub_f32_e32 v24, v99, v98
	v_add_f32_dpp v20, v20, v20 row_half_mirror row_mask:0xf bank_mask:0xf bound_ctrl:1
	v_fma_f32 v24, v80, v24, v98
	s_nop 0
	v_add_f32_dpp v20, v20, v20 row_mirror row_mask:0xf bank_mask:0xf bound_ctrl:1
	v_mov_b32_e32 v21, v20
	s_nop 1
	v_permlane16_swap_b32_e32 v20, v21
	s_waitcnt lgkmcnt(0)
	v_add_f32_e32 v20, v20, v21
	v_mov_b32_e32 v21, v20
	s_nop 1
	v_permlane32_swap_b32_e32 v20, v21
	s_waitcnt lgkmcnt(0)
	v_add_f32_e32 v20, v20, v21
	v_mul_f32_e32 v21, 0x4f800000, v20
	v_cmp_gt_f32_e32 vcc, s0, v20
	s_nop 1
	v_cndmask_b32_e32 v20, v20, v21, vcc
	v_sqrt_f32_e32 v21, v20
	s_nop 0
	v_add_u32_e32 v22, -1, v21
	v_add_u32_e32 v23, 1, v21
	v_fma_f32 v26, -v22, v21, v20
	v_fma_f32 v27, -v23, v21, v20
	v_cmp_ge_f32_e64 s[46:47], 0, v26
	s_nop 1
	v_cndmask_b32_e64 v21, v21, v22, s[46:47]
	v_cmp_lt_f32_e64 s[46:47], 0, v27
	s_nop 1
	v_cndmask_b32_e64 v21, v21, v23, s[46:47]
	v_mul_f32_e32 v22, 0x37800000, v21
	v_cndmask_b32_e32 v21, v21, v22, vcc
	v_cmp_class_f32_e32 vcc, v20, v204
	v_sub_f32_e32 v23, v105, v98
	v_fmac_f32_e32 v24, v79, v23
	v_cndmask_b32_e32 v20, v21, v20, vcc
	v_max_f32_e32 v20, 0x2b8cbccc, v20
	v_div_scale_f32 v21, s[0:1], v20, v20, v19
	v_rcp_f32_e32 v22, v21
	s_nop 0
	v_fma_f32 v23, -v21, v22, 1.0
	v_fmac_f32_e32 v22, v23, v22
	v_div_scale_f32 v23, vcc, v19, v20, v19
	v_mul_f32_e32 v26, v23, v22
	v_fma_f32 v27, -v21, v26, v23
	v_fmac_f32_e32 v26, v27, v22
	v_fma_f32 v21, -v21, v26, v23
	v_div_fmas_f32 v21, v21, v22, v26
	v_div_fixup_f32 v26, v21, v20, v19
	s_waitcnt vmcnt(11)
	v_add_f32_e32 v19, -1.0, v108
	v_fma_f32 v19, v82, v19, 1.0
	v_mul_f32_e32 v27, v18, v19
	v_mul_f32_e32 v18, v25, v27
	v_mul_f32_e32 v28, v108, v26
	v_mul_f32_e32 v19, v83, v18
	v_mul_f32_e32 v21, v25, v28
	v_xor_b32_e32 v26, 0x80000000, v26
	v_mov_b32_dpp v19, v19 quad_perm:[1,0,3,2] row_mask:0xf bank_mask:0xf bound_ctrl:1
	v_fmac_f32_e32 v19, v83, v18
	v_mov_b32_dpp v21, v21 quad_perm:[1,0,3,2] row_mask:0xf bank_mask:0xf bound_ctrl:1
	v_mov_b32_dpp v18, v18 quad_perm:[1,0,3,2] row_mask:0xf bank_mask:0xf bound_ctrl:1
	v_fmac_f32_e32 v21, v25, v28
	v_fmac_f32_e32 v18, v25, v27
	v_add_f32_dpp v19, v19, v19 quad_perm:[2,3,0,1] row_mask:0xf bank_mask:0xf bound_ctrl:1
	v_add_f32_dpp v21, v21, v21 quad_perm:[2,3,0,1] row_mask:0xf bank_mask:0xf bound_ctrl:1
	v_add_f32_dpp v18, v18, v18 quad_perm:[2,3,0,1] row_mask:0xf bank_mask:0xf bound_ctrl:1
	v_add_f32_dpp v19, v19, v19 row_half_mirror row_mask:0xf bank_mask:0xf bound_ctrl:1
	v_add_f32_dpp v21, v21, v21 row_half_mirror row_mask:0xf bank_mask:0xf bound_ctrl:1
	v_add_f32_dpp v18, v18, v18 row_half_mirror row_mask:0xf bank_mask:0xf bound_ctrl:1
	v_add_f32_dpp v19, v19, v19 row_mirror row_mask:0xf bank_mask:0xf bound_ctrl:1
	v_add_f32_dpp v21, v21, v21 row_mirror row_mask:0xf bank_mask:0xf bound_ctrl:1
	v_add_f32_dpp v23, v18, v18 row_mirror row_mask:0xf bank_mask:0xf bound_ctrl:1
	v_mov_b32_e32 v20, v19
	s_nop 1
	v_permlane16_swap_b32_e32 v19, v20
	v_mov_b32_e32 v22, v21
	s_nop 1
	v_permlane16_swap_b32_e32 v21, v22
	v_mov_b32_e32 v29, v23
	s_nop 1
	v_permlane16_swap_b32_e32 v23, v29
	s_waitcnt vmcnt(10)
	v_mul_f32_e32 v25, v25, v107
	s_waitcnt lgkmcnt(2)
	v_add_f32_e32 v18, v19, v20
	s_waitcnt lgkmcnt(1)
	v_add_f32_e32 v19, v21, v22
	s_waitcnt lgkmcnt(0)
	v_add_f32_e32 v22, v23, v29
	v_mov_b32_e32 v20, v18
	s_nop 1
	v_permlane32_swap_b32_e32 v18, v20
	v_mov_b32_e32 v21, v19
	s_nop 1
	v_permlane32_swap_b32_e32 v19, v21
	v_mov_b32_e32 v23, v22
	s_nop 1
	v_permlane32_swap_b32_e32 v22, v23
	v_lshl_add_u32 v29, v129, 2, s28
	ds_write_b32 v29, v107
	ds_write2st64_b32 v29, v26, v28 offset0:16 offset1:32
	ds_write2st64_b32 v29, v27, v25 offset0:48 offset1:64
	ds_write_b32 v29, v24 offset:20480
	s_and_saveexec_b64 s[0:1], s[42:43]
	s_cbranch_execz .LBB0_606
	s_waitcnt lgkmcnt(4)
	v_add_f32_e32 v22, v22, v23
	v_add_f32_e32 v18, v18, v20
	v_add_f32_e32 v18, v18, v22
	v_add_f32_e32 v19, v19, v21
	v_add_u32_e32 v20, 0x6000, v0
	ds_write2_b32 v20, v19, v18 offset0:4 offset1:20
.LBB0_606:
	s_or_b64 exec, exec, s[0:1]
	s_waitcnt vmcnt(7)
	v_sub_f32_e32 v18, v114, v110
	v_fma_f32 v18, v76, v18, v110
	v_sub_f32_e32 v19, v117, v110
	v_fmac_f32_e32 v18, v78, v19
	v_mul_f32_e32 v19, v81, v18
	s_waitcnt lgkmcnt(6)
	v_mul_f32_e32 v20, v19, v19
	s_mov_b32 s0, 0xf800000
	v_sub_f32_e32 v22, v113, v109
	v_mov_b32_dpp v20, v20 quad_perm:[1,0,3,2] row_mask:0xf bank_mask:0xf bound_ctrl:1
	v_fmac_f32_e32 v20, v19, v19
	s_waitcnt lgkmcnt(4)
	v_sub_f32_e32 v23, v115, v109
	v_fma_f32 v25, v75, v22, v109
	v_add_f32_dpp v20, v20, v20 quad_perm:[2,3,0,1] row_mask:0xf bank_mask:0xf bound_ctrl:1
	v_fmac_f32_e32 v25, v77, v23
	v_sub_f32_e32 v24, v112, v111
	v_add_f32_dpp v20, v20, v20 row_half_mirror row_mask:0xf bank_mask:0xf bound_ctrl:1
	v_fma_f32 v24, v80, v24, v111
	s_nop 0
	v_add_f32_dpp v20, v20, v20 row_mirror row_mask:0xf bank_mask:0xf bound_ctrl:1
	v_mov_b32_e32 v21, v20
	s_nop 1
	v_permlane16_swap_b32_e32 v20, v21
	s_waitcnt lgkmcnt(0)
	v_add_f32_e32 v20, v20, v21
	v_mov_b32_e32 v21, v20
	s_nop 1
	v_permlane32_swap_b32_e32 v20, v21
	s_waitcnt lgkmcnt(0)
	v_add_f32_e32 v20, v20, v21
	v_mul_f32_e32 v21, 0x4f800000, v20
	v_cmp_gt_f32_e32 vcc, s0, v20
	s_nop 1
	v_cndmask_b32_e32 v20, v20, v21, vcc
	v_sqrt_f32_e32 v21, v20
	s_nop 0
	v_add_u32_e32 v22, -1, v21
	v_add_u32_e32 v23, 1, v21
	v_fma_f32 v26, -v22, v21, v20
	v_fma_f32 v27, -v23, v21, v20
	v_cmp_ge_f32_e64 s[46:47], 0, v26
	s_nop 1
	v_cndmask_b32_e64 v21, v21, v22, s[46:47]
	v_cmp_lt_f32_e64 s[46:47], 0, v27
	s_nop 1
	v_cndmask_b32_e64 v21, v21, v23, s[46:47]
	v_mul_f32_e32 v22, 0x37800000, v21
	v_cndmask_b32_e32 v21, v21, v22, vcc
	v_cmp_class_f32_e32 vcc, v20, v204
	v_sub_f32_e32 v23, v116, v111
	v_fmac_f32_e32 v24, v79, v23
	v_cndmask_b32_e32 v20, v21, v20, vcc
	v_max_f32_e32 v20, 0x2b8cbccc, v20
	v_div_scale_f32 v21, s[0:1], v20, v20, v19
	v_rcp_f32_e32 v22, v21
	s_nop 0
	v_fma_f32 v23, -v21, v22, 1.0
	v_fmac_f32_e32 v22, v23, v22
	v_div_scale_f32 v23, vcc, v19, v20, v19
	v_mul_f32_e32 v26, v23, v22
	v_fma_f32 v27, -v21, v26, v23
	v_fmac_f32_e32 v26, v27, v22
	v_fma_f32 v21, -v21, v26, v23
	v_div_fmas_f32 v21, v21, v22, v26
	v_div_fixup_f32 v26, v21, v20, v19
	s_waitcnt vmcnt(6)
	v_add_f32_e32 v19, -1.0, v120
	v_fma_f32 v19, v82, v19, 1.0
	v_mul_f32_e32 v27, v18, v19
	v_mul_f32_e32 v18, v25, v27
	v_mul_f32_e32 v28, v120, v26
	v_mul_f32_e32 v19, v83, v18
	v_mul_f32_e32 v21, v25, v28
	v_xor_b32_e32 v26, 0x80000000, v26
	v_mov_b32_dpp v19, v19 quad_perm:[1,0,3,2] row_mask:0xf bank_mask:0xf bound_ctrl:1
	v_fmac_f32_e32 v19, v83, v18
	v_mov_b32_dpp v21, v21 quad_perm:[1,0,3,2] row_mask:0xf bank_mask:0xf bound_ctrl:1
	v_mov_b32_dpp v18, v18 quad_perm:[1,0,3,2] row_mask:0xf bank_mask:0xf bound_ctrl:1
	v_fmac_f32_e32 v21, v25, v28
	v_fmac_f32_e32 v18, v25, v27
	v_add_f32_dpp v19, v19, v19 quad_perm:[2,3,0,1] row_mask:0xf bank_mask:0xf bound_ctrl:1
	v_add_f32_dpp v21, v21, v21 quad_perm:[2,3,0,1] row_mask:0xf bank_mask:0xf bound_ctrl:1
	v_add_f32_dpp v18, v18, v18 quad_perm:[2,3,0,1] row_mask:0xf bank_mask:0xf bound_ctrl:1
	v_add_f32_dpp v19, v19, v19 row_half_mirror row_mask:0xf bank_mask:0xf bound_ctrl:1
	v_add_f32_dpp v21, v21, v21 row_half_mirror row_mask:0xf bank_mask:0xf bound_ctrl:1
	v_add_f32_dpp v18, v18, v18 row_half_mirror row_mask:0xf bank_mask:0xf bound_ctrl:1
	v_add_f32_dpp v19, v19, v19 row_mirror row_mask:0xf bank_mask:0xf bound_ctrl:1
	v_add_f32_dpp v21, v21, v21 row_mirror row_mask:0xf bank_mask:0xf bound_ctrl:1
	v_add_f32_dpp v23, v18, v18 row_mirror row_mask:0xf bank_mask:0xf bound_ctrl:1
	v_mov_b32_e32 v20, v19
	s_nop 1
	v_permlane16_swap_b32_e32 v19, v20
	v_mov_b32_e32 v22, v21
	s_nop 1
	v_permlane16_swap_b32_e32 v21, v22
	v_mov_b32_e32 v29, v23
	s_nop 1
	v_permlane16_swap_b32_e32 v23, v29
	s_waitcnt vmcnt(5)
	v_mul_f32_e32 v25, v25, v119
	s_waitcnt lgkmcnt(2)
	v_add_f32_e32 v18, v19, v20
	s_waitcnt lgkmcnt(1)
	v_add_f32_e32 v19, v21, v22
	s_waitcnt lgkmcnt(0)
	v_add_f32_e32 v22, v23, v29
	v_mov_b32_e32 v20, v18
	s_nop 1
	v_permlane32_swap_b32_e32 v18, v20
	v_mov_b32_e32 v21, v19
	s_nop 1
	v_permlane32_swap_b32_e32 v19, v21
	v_mov_b32_e32 v23, v22
	s_nop 1
	v_permlane32_swap_b32_e32 v22, v23
	v_lshl_add_u32 v29, v133, 2, s28
	ds_write_b32 v29, v119
	ds_write2st64_b32 v29, v26, v28 offset0:16 offset1:32
	ds_write2st64_b32 v29, v27, v25 offset0:48 offset1:64
	ds_write_b32 v29, v24 offset:20480
	s_and_saveexec_b64 s[0:1], s[42:43]
	s_cbranch_execz .LBB0_608
	s_waitcnt lgkmcnt(4)
	v_add_f32_e32 v22, v22, v23
	v_add_f32_e32 v18, v18, v20
	v_add_f32_e32 v18, v18, v22
	v_add_f32_e32 v19, v19, v21
	v_add_u32_e32 v20, 0x6000, v0
	ds_write2_b32 v20, v19, v18 offset0:8 offset1:24
.LBB0_608:
	s_or_b64 exec, exec, s[0:1]
	s_waitcnt vmcnt(2)
	v_sub_f32_e32 v18, v126, v122
	v_fma_f32 v18, v76, v18, v122
	v_sub_f32_e32 v19, v130, v122
	v_fmac_f32_e32 v18, v78, v19
	v_mul_f32_e32 v19, v81, v18
	s_waitcnt lgkmcnt(6)
	v_mul_f32_e32 v20, v19, v19
	s_mov_b32 s0, 0xf800000
	v_sub_f32_e32 v22, v125, v121
	v_mov_b32_dpp v20, v20 quad_perm:[1,0,3,2] row_mask:0xf bank_mask:0xf bound_ctrl:1
	v_fmac_f32_e32 v20, v19, v19
	s_waitcnt lgkmcnt(4)
	v_sub_f32_e32 v23, v127, v121
	v_fma_f32 v25, v75, v22, v121
	v_add_f32_dpp v20, v20, v20 quad_perm:[2,3,0,1] row_mask:0xf bank_mask:0xf bound_ctrl:1
	v_fmac_f32_e32 v25, v77, v23
	v_sub_f32_e32 v24, v124, v123
	v_add_f32_dpp v20, v20, v20 row_half_mirror row_mask:0xf bank_mask:0xf bound_ctrl:1
	v_fma_f32 v24, v80, v24, v123
	s_nop 0
	v_add_f32_dpp v20, v20, v20 row_mirror row_mask:0xf bank_mask:0xf bound_ctrl:1
	v_mov_b32_e32 v21, v20
	s_nop 1
	v_permlane16_swap_b32_e32 v20, v21
	s_waitcnt lgkmcnt(0)
	v_add_f32_e32 v20, v20, v21
	v_mov_b32_e32 v21, v20
	s_nop 1
	v_permlane32_swap_b32_e32 v20, v21
	s_waitcnt lgkmcnt(0)
	v_add_f32_e32 v20, v20, v21
	v_mul_f32_e32 v21, 0x4f800000, v20
	v_cmp_gt_f32_e32 vcc, s0, v20
	s_nop 1
	v_cndmask_b32_e32 v20, v20, v21, vcc
	v_sqrt_f32_e32 v21, v20
	s_nop 0
	v_add_u32_e32 v22, -1, v21
	v_add_u32_e32 v23, 1, v21
	v_fma_f32 v26, -v22, v21, v20
	v_fma_f32 v27, -v23, v21, v20
	v_cmp_ge_f32_e64 s[46:47], 0, v26
	s_nop 1
	v_cndmask_b32_e64 v21, v21, v22, s[46:47]
	v_cmp_lt_f32_e64 s[46:47], 0, v27
	s_nop 1
	v_cndmask_b32_e64 v21, v21, v23, s[46:47]
	v_mul_f32_e32 v22, 0x37800000, v21
	v_cndmask_b32_e32 v21, v21, v22, vcc
	v_cmp_class_f32_e32 vcc, v20, v204
	v_sub_f32_e32 v23, v128, v123
	v_fmac_f32_e32 v24, v79, v23
	v_cndmask_b32_e32 v20, v21, v20, vcc
	v_max_f32_e32 v20, 0x2b8cbccc, v20
	v_div_scale_f32 v21, s[0:1], v20, v20, v19
	v_rcp_f32_e32 v22, v21
	s_nop 0
	v_fma_f32 v23, -v21, v22, 1.0
	v_fmac_f32_e32 v22, v23, v22
	v_div_scale_f32 v23, vcc, v19, v20, v19
	v_mul_f32_e32 v26, v23, v22
	v_fma_f32 v27, -v21, v26, v23
	v_fmac_f32_e32 v26, v27, v22
	v_fma_f32 v21, -v21, v26, v23
	v_div_fmas_f32 v21, v21, v22, v26
	v_div_fixup_f32 v26, v21, v20, v19
	s_waitcnt vmcnt(0)
	v_add_f32_e32 v19, -1.0, v132
	v_fma_f32 v19, v82, v19, 1.0
	v_mul_f32_e32 v27, v18, v19
	v_mul_f32_e32 v18, v25, v27
	v_mul_f32_e32 v28, v132, v26
	v_mul_f32_e32 v19, v83, v18
	v_mul_f32_e32 v21, v25, v28
	v_xor_b32_e32 v26, 0x80000000, v26
	v_mov_b32_dpp v19, v19 quad_perm:[1,0,3,2] row_mask:0xf bank_mask:0xf bound_ctrl:1
	v_fmac_f32_e32 v19, v83, v18
	v_mov_b32_dpp v21, v21 quad_perm:[1,0,3,2] row_mask:0xf bank_mask:0xf bound_ctrl:1
	v_mov_b32_dpp v18, v18 quad_perm:[1,0,3,2] row_mask:0xf bank_mask:0xf bound_ctrl:1
	v_fmac_f32_e32 v21, v25, v28
	v_fmac_f32_e32 v18, v25, v27
	v_add_f32_dpp v19, v19, v19 quad_perm:[2,3,0,1] row_mask:0xf bank_mask:0xf bound_ctrl:1
	v_add_f32_dpp v21, v21, v21 quad_perm:[2,3,0,1] row_mask:0xf bank_mask:0xf bound_ctrl:1
	v_add_f32_dpp v18, v18, v18 quad_perm:[2,3,0,1] row_mask:0xf bank_mask:0xf bound_ctrl:1
	v_add_f32_dpp v19, v19, v19 row_half_mirror row_mask:0xf bank_mask:0xf bound_ctrl:1
	v_add_f32_dpp v21, v21, v21 row_half_mirror row_mask:0xf bank_mask:0xf bound_ctrl:1
	v_add_f32_dpp v18, v18, v18 row_half_mirror row_mask:0xf bank_mask:0xf bound_ctrl:1
	v_add_f32_dpp v19, v19, v19 row_mirror row_mask:0xf bank_mask:0xf bound_ctrl:1
	v_add_f32_dpp v21, v21, v21 row_mirror row_mask:0xf bank_mask:0xf bound_ctrl:1
	v_add_f32_dpp v23, v18, v18 row_mirror row_mask:0xf bank_mask:0xf bound_ctrl:1
	v_mov_b32_e32 v20, v19
	s_nop 1
	v_permlane16_swap_b32_e32 v19, v20
	v_mov_b32_e32 v22, v21
	s_nop 1
	v_permlane16_swap_b32_e32 v21, v22
	v_mov_b32_e32 v29, v23
	s_nop 1
	v_permlane16_swap_b32_e32 v23, v29
	v_mul_f32_e32 v25, v25, v131
	s_waitcnt lgkmcnt(2)
	v_add_f32_e32 v18, v19, v20
	s_waitcnt lgkmcnt(1)
	v_add_f32_e32 v19, v21, v22
	s_waitcnt lgkmcnt(0)
	v_add_f32_e32 v22, v23, v29
	v_mov_b32_e32 v20, v18
	s_nop 1
	v_permlane32_swap_b32_e32 v18, v20
	v_mov_b32_e32 v21, v19
	s_nop 1
	v_permlane32_swap_b32_e32 v19, v21
	v_mov_b32_e32 v23, v22
	s_nop 1
	v_permlane32_swap_b32_e32 v22, v23
	v_lshl_add_u32 v29, v137, 2, s28
	ds_write_b32 v29, v131
	ds_write2st64_b32 v29, v26, v28 offset0:16 offset1:32
	ds_write2st64_b32 v29, v27, v25 offset0:48 offset1:64
	ds_write_b32 v29, v24 offset:20480
	s_and_saveexec_b64 s[0:1], s[42:43]
	s_cbranch_execz .LBB0_610
	s_waitcnt lgkmcnt(4)
	v_add_f32_e32 v22, v22, v23
	v_add_f32_e32 v18, v18, v20
	v_add_f32_e32 v18, v18, v22
	v_add_f32_e32 v19, v19, v21
	v_add_u32_e32 v0, 0x6000, v0
	ds_write2_b32 v0, v19, v18 offset0:12 offset1:28

.LBB0_624:
	s_or_b64 exec, exec, s[0:1]
	v_readlane_b32 s4, v253, 46
	s_lshl_b32 s29, s21, 11
	v_readlane_b32 s16, v253, 58
	v_readlane_b32 s17, v253, 59
	s_add_u32 s0, s16, s29
	v_readlane_b32 s18, v253, 60
	s_addc_u32 s1, s17, 0
	v_readlane_b32 s19, v253, 61
	v_lshl_add_u64 v[116:117], s[0:1], 0, v[0:1]
	s_add_u32 s0, s18, s29
	v_ashrrev_i32_e32 v3, 31, v2
	s_addc_u32 s1, s19, 0
	s_waitcnt vmcnt(21)
	v_lshl_add_u64 v[118:119], s[0:1], 0, v[0:1]
	v_lshlrev_b64 v[2:3], 12, v[2:3]
	v_lshl_add_u64 v[4:5], v[116:117], 0, v[2:3]
	v_lshl_add_u64 v[2:3], v[118:119], 0, v[2:3]
	global_load_dword v166, v[2:3], off
	v_or_b32_e32 v0, 4, v152
	v_sub_u32_e32 v2, 0x7fb, v152
	v_readlane_b32 s6, v253, 48
	v_cndmask_b32_e64 v0, v2, v0, s[40:41]
	v_or_b32_e32 v2, s53, v0
	s_movk_i32 s6, 0x1c00
	global_load_dword v165, v[4:5], off
	v_mad_i64_i32 v[4:5], s[0:1], v2, s6, v[114:115]
	s_movk_i32 s4, 0x1000
	v_add_co_u32_e32 v8, vcc, s4, v4
	v_readlane_b32 s5, v253, 47
	s_nop 0
	v_addc_co_u32_e32 v9, vcc, 0, v5, vcc
	v_add_co_u32_e32 v10, vcc, s22, v4
	s_movk_i32 s5, 0x2000
	s_nop 0
	v_addc_co_u32_e32 v11, vcc, -1, v5, vcc
	v_ashrrev_i32_e32 v3, 31, v2
	global_load_dword v167, v[4:5], off
	global_load_dword v168, v[4:5], off offset:2048
	global_load_dword v169, v[8:9], off
	global_load_dword v171, v[10:11], off offset:-3072
	global_load_dword v172, v[10:11], off offset:-1024
	global_load_dword v170, v[4:5], off offset:-3072
	global_load_dword v173, v[8:9], off offset:3072
	v_add_co_u32_e32 v4, vcc, s5, v4
	v_lshlrev_b64 v[2:3], 12, v[2:3]
	s_nop 0
	v_addc_co_u32_e32 v5, vcc, 0, v5, vcc
	global_load_dword v177, v[4:5], off offset:1024
	global_load_dword v176, v[4:5], off offset:3072
	v_lshl_add_u64 v[4:5], v[116:117], 0, v[2:3]
	v_lshl_add_u64 v[2:3], v[118:119], 0, v[2:3]
	global_load_dword v179, v[2:3], off
	v_or_b32_e32 v0, 8, v152
	v_sub_u32_e32 v2, 0x7f7, v152
	v_cndmask_b32_e64 v0, v2, v0, s[40:41]
	v_or_b32_e32 v2, s53, v0
	global_load_dword v178, v[4:5], off
	v_mad_i64_i32 v[4:5], s[0:1], v2, s6, v[114:115]
	v_add_co_u32_e32 v8, vcc, s4, v4
	v_ashrrev_i32_e32 v3, 31, v2
	s_nop 0
	v_addc_co_u32_e32 v9, vcc, 0, v5, vcc
	v_add_co_u32_e32 v10, vcc, s22, v4
	global_load_dword v180, v[4:5], off
	global_load_dword v181, v[4:5], off offset:2048
	v_addc_co_u32_e32 v11, vcc, -1, v5, vcc
	global_load_dword v182, v[8:9], off
	global_load_dword v184, v[10:11], off offset:-3072
	global_load_dword v185, v[10:11], off offset:-1024
	global_load_dword v183, v[4:5], off offset:-3072
	global_load_dword v186, v[8:9], off offset:3072
	v_add_co_u32_e32 v4, vcc, s5, v4
	v_lshlrev_b64 v[2:3], 12, v[2:3]
	s_nop 0
	v_addc_co_u32_e32 v5, vcc, 0, v5, vcc
	global_load_dword v188, v[4:5], off offset:1024
	global_load_dword v187, v[4:5], off offset:3072
	v_lshl_add_u64 v[4:5], v[116:117], 0, v[2:3]
	v_lshl_add_u64 v[2:3], v[118:119], 0, v[2:3]
	global_load_dword v191, v[2:3], off
	v_or_b32_e32 v0, 12, v152
	v_sub_u32_e32 v2, 0x7f3, v152
	v_cndmask_b32_e64 v0, v2, v0, s[40:41]
	v_or_b32_e32 v2, s53, v0
	global_load_dword v190, v[4:5], off
	v_mad_i64_i32 v[4:5], s[0:1], v2, s6, v[114:115]
	v_add_co_u32_e32 v8, vcc, s4, v4
	v_ashrrev_i32_e32 v3, 31, v2
	s_nop 0
	v_addc_co_u32_e32 v9, vcc, 0, v5, vcc
	v_add_co_u32_e32 v10, vcc, s22, v4
	global_load_dword v192, v[4:5], off
	global_load_dword v193, v[4:5], off offset:2048
	v_addc_co_u32_e32 v11, vcc, -1, v5, vcc
	global_load_dword v194, v[8:9], off
	global_load_dword v231, v[10:11], off offset:-3072
	global_load_dword v232, v[10:11], off offset:-1024
	global_load_dword v195, v[4:5], off offset:-3072
	global_load_dword v233, v[8:9], off offset:3072
	v_add_co_u32_e32 v4, vcc, s5, v4
	v_lshlrev_b64 v[2:3], 12, v[2:3]
	s_nop 0
	v_addc_co_u32_e32 v5, vcc, 0, v5, vcc
	global_load_dword v236, v[4:5], off offset:1024
	global_load_dword v235, v[4:5], off offset:3072
	v_lshl_add_u64 v[4:5], v[116:117], 0, v[2:3]
	v_lshl_add_u64 v[2:3], v[118:119], 0, v[2:3]
	global_load_dword v238, v[2:3], off
	v_and_b32_e32 v2, 64, v209
	v_xor_b32_e32 v0, 16, v209
	v_add_u32_e32 v2, 64, v2
	global_load_dword v237, v[4:5], off
	v_cmp_lt_i32_e32 vcc, v0, v2
	s_waitcnt vmcnt(35)
	v_sub_f32_e32 v3, v164, v154
	s_mov_b32 s0, 0xf800000
	v_cndmask_b32_e32 v0, v209, v0, vcc
	v_lshlrev_b32_e32 v174, 2, v0
	v_xor_b32_e32 v0, 32, v209
	v_cmp_lt_i32_e32 vcc, v0, v2
	v_sub_f32_e32 v2, v162, v153
	v_and_b32_e32 v161, 0xff, v6
	v_cndmask_b32_e32 v0, v209, v0, vcc
	v_lshlrev_b32_e32 v175, 2, v0
	v_sub_f32_e32 v0, v157, v153
	v_fma_f32 v0, v142, v0, v153
	v_fmac_f32_e32 v0, v144, v2
	v_sub_f32_e32 v2, v160, v154
	v_fma_f32 v2, v143, v2, v154
	v_fmac_f32_e32 v2, v145, v3
	v_sub_f32_e32 v3, v156, v155
	v_fma_f32 v10, v147, v3, v155
	v_sub_f32_e32 v3, v163, v155
	v_fmac_f32_e32 v10, v146, v3
	v_mul_f32_e32 v3, v148, v2
	v_mul_f32_e32 v4, v3, v3
	v_lshl_add_u32 v14, v161, 2, s33
	s_waitcnt lgkmcnt(0)
	v_mov_b32_dpp v4, v4 quad_perm:[1,0,3,2] row_mask:0xf bank_mask:0xf bound_ctrl:1
	v_fmac_f32_e32 v4, v3, v3
	s_barrier
	s_nop 0
	v_add_f32_dpp v4, v4, v4 quad_perm:[2,3,0,1] row_mask:0xf bank_mask:0xf bound_ctrl:1
	s_waitcnt vmcnt(33)
	ds_write_b32 v14, v165
	v_cmp_eq_u32_e64 s[42:43], 0, v7
	v_add_f32_dpp v4, v4, v4 row_half_mirror row_mask:0xf bank_mask:0xf bound_ctrl:1
	v_readlane_b32 s7, v253, 49
	v_readlane_b32 s8, v253, 50
	v_add_f32_dpp v4, v4, v4 row_mirror row_mask:0xf bank_mask:0xf bound_ctrl:1
	v_mov_b32_e32 v5, v4
	s_nop 1
	v_permlane16_swap_b32_e32 v4, v5
	v_readlane_b32 s9, v253, 51
	v_readlane_b32 s10, v253, 52
	v_readlane_b32 s11, v253, 53
	v_readlane_b32 s12, v253, 54
	s_waitcnt lgkmcnt(0)
	v_add_f32_e32 v4, v4, v5
	v_mov_b32_e32 v5, v4
	s_nop 1
	v_permlane32_swap_b32_e32 v4, v5
	v_readlane_b32 s13, v253, 55
	v_readlane_b32 s14, v253, 56
	v_readlane_b32 s15, v253, 57
	s_waitcnt lgkmcnt(0)
	v_add_f32_e32 v4, v4, v5
	v_cmp_gt_f32_e32 vcc, s0, v4
	v_mul_f32_e32 v5, 0x4f800000, v4
	s_nop 0
	v_cndmask_b32_e32 v4, v4, v5, vcc
	v_sqrt_f32_e32 v5, v4
	s_nop 0
	v_add_u32_e32 v8, -1, v5
	v_fma_f32 v9, -v8, v5, v4
	v_cmp_ge_f32_e64 s[44:45], 0, v9
	v_add_u32_e32 v9, 1, v5
	s_nop 0
	v_cndmask_b32_e64 v8, v5, v8, s[44:45]
	v_fma_f32 v5, -v9, v5, v4
	v_cmp_lt_f32_e64 s[44:45], 0, v5
	s_nop 1
	v_cndmask_b32_e64 v5, v8, v9, s[44:45]
	v_mul_f32_e32 v8, 0x37800000, v5
	v_cndmask_b32_e32 v5, v5, v8, vcc
	v_cmp_class_f32_e32 vcc, v4, v204
	s_nop 1
	v_cndmask_b32_e32 v4, v5, v4, vcc
	v_max_f32_e32 v4, 0x2b8cbccc, v4
	v_div_scale_f32 v5, s[0:1], v4, v4, v3
	v_rcp_f32_e32 v8, v5
	s_movk_i32 s0, 0xc0
	v_and_or_b32 v189, v6, s0, v7
	v_lshl_add_u32 v14, v189, 2, s33
	v_fma_f32 v9, -v5, v8, 1.0
	v_fmac_f32_e32 v8, v9, v8
	v_div_scale_f32 v9, vcc, v3, v4, v3
	v_mul_f32_e32 v11, v9, v8
	v_fma_f32 v12, -v5, v11, v9
	v_fmac_f32_e32 v11, v12, v8
	v_fma_f32 v5, -v5, v11, v9
	v_div_fmas_f32 v5, v5, v8, v11
	v_div_fixup_f32 v11, v5, v4, v3
	v_add_f32_e32 v3, -1.0, v166
	v_fma_f32 v3, v149, v3, 1.0
	v_mul_f32_e32 v12, v2, v3
	v_mul_f32_e32 v8, v0, v12
	v_mul_f32_e32 v13, v166, v11
	v_mul_f32_e32 v2, v150, v8
	v_mul_f32_e32 v4, v0, v13
	v_xor_b32_e32 v11, 0x80000000, v11
	v_mov_b32_dpp v2, v2 quad_perm:[1,0,3,2] row_mask:0xf bank_mask:0xf bound_ctrl:1
	v_fmac_f32_e32 v2, v150, v8
	v_mov_b32_dpp v4, v4 quad_perm:[1,0,3,2] row_mask:0xf bank_mask:0xf bound_ctrl:1
	v_mov_b32_dpp v8, v8 quad_perm:[1,0,3,2] row_mask:0xf bank_mask:0xf bound_ctrl:1
	v_fmac_f32_e32 v4, v0, v13
	v_fmac_f32_e32 v8, v0, v12
	v_add_f32_dpp v2, v2, v2 quad_perm:[2,3,0,1] row_mask:0xf bank_mask:0xf bound_ctrl:1
	v_add_f32_dpp v4, v4, v4 quad_perm:[2,3,0,1] row_mask:0xf bank_mask:0xf bound_ctrl:1
	v_add_f32_dpp v8, v8, v8 quad_perm:[2,3,0,1] row_mask:0xf bank_mask:0xf bound_ctrl:1
	v_add_f32_dpp v2, v2, v2 row_half_mirror row_mask:0xf bank_mask:0xf bound_ctrl:1
	v_add_f32_dpp v4, v4, v4 row_half_mirror row_mask:0xf bank_mask:0xf bound_ctrl:1
	v_add_f32_dpp v8, v8, v8 row_half_mirror row_mask:0xf bank_mask:0xf bound_ctrl:1
	v_add_f32_dpp v2, v2, v2 row_mirror row_mask:0xf bank_mask:0xf bound_ctrl:1
	v_add_f32_dpp v4, v4, v4 row_mirror row_mask:0xf bank_mask:0xf bound_ctrl:1
	v_add_f32_dpp v8, v8, v8 row_mirror row_mask:0xf bank_mask:0xf bound_ctrl:1
	v_mov_b32_e32 v3, v2
	s_nop 1
	v_permlane16_swap_b32_e32 v2, v3
	v_mov_b32_e32 v5, v4
	s_nop 1
	v_permlane16_swap_b32_e32 v4, v5
	v_mov_b32_e32 v9, v8
	s_nop 1
	v_permlane16_swap_b32_e32 v8, v9
	v_mul_f32_e32 v0, v0, v165
	ds_write2st64_b32 v14, v11, v13 offset0:16 offset1:32
	s_waitcnt lgkmcnt(3)
	v_add_f32_e32 v2, v2, v3
	s_waitcnt lgkmcnt(2)
	v_add_f32_e32 v4, v4, v5
	s_waitcnt lgkmcnt(1)
	v_add_f32_e32 v8, v8, v9
	v_mov_b32_e32 v3, v2
	s_nop 1
	v_permlane32_swap_b32_e32 v2, v3
	v_mov_b32_e32 v5, v4
	s_nop 1
	v_permlane32_swap_b32_e32 v4, v5
	v_mov_b32_e32 v9, v8
	s_nop 1
	v_permlane32_swap_b32_e32 v8, v9
	ds_write2st64_b32 v14, v12, v0 offset0:48 offset1:64
	ds_write_b32 v14, v10 offset:20480
	v_lshl_add_u32 v0, v151, 2, s33
	s_and_saveexec_b64 s[0:1], s[42:43]
	s_cbranch_execz .LBB0_626
	s_waitcnt lgkmcnt(2)
	v_add_f32_e32 v8, v8, v9
	v_add_f32_e32 v2, v2, v3
	v_add_f32_e32 v2, v2, v8
	v_add_f32_e32 v3, v4, v5
	v_add_u32_e32 v4, 0x6000, v0
	ds_write2_b32 v4, v3, v2 offset1:16
.LBB0_626:
	s_or_b64 exec, exec, s[0:1]
	s_waitcnt vmcnt(28)
	v_sub_f32_e32 v2, v172, v168
	s_waitcnt lgkmcnt(4)
	v_fma_f32 v3, v143, v2, v168
	s_waitcnt vmcnt(25)
	v_sub_f32_e32 v2, v177, v168
	v_fmac_f32_e32 v3, v145, v2
	v_mul_f32_e32 v4, v148, v3
	v_mul_f32_e32 v2, v4, v4
	s_mov_b32 s0, 0xf800000
	s_waitcnt lgkmcnt(2)
	v_sub_f32_e32 v9, v171, v167
	v_mov_b32_dpp v2, v2 quad_perm:[1,0,3,2] row_mask:0xf bank_mask:0xf bound_ctrl:1
	v_fmac_f32_e32 v2, v4, v4
	v_sub_f32_e32 v10, v173, v167
	v_fma_f32 v12, v142, v9, v167
	v_add_f32_dpp v2, v2, v2 quad_perm:[2,3,0,1] row_mask:0xf bank_mask:0xf bound_ctrl:1
	v_fmac_f32_e32 v12, v144, v10
	v_sub_f32_e32 v11, v170, v169
	v_add_f32_dpp v2, v2, v2 row_half_mirror row_mask:0xf bank_mask:0xf bound_ctrl:1
	v_fma_f32 v11, v147, v11, v169
	s_nop 0
	v_add_f32_dpp v2, v2, v2 row_mirror row_mask:0xf bank_mask:0xf bound_ctrl:1
	v_mov_b32_e32 v5, v2
	s_nop 1
	v_permlane16_swap_b32_e32 v2, v5
	s_waitcnt lgkmcnt(0)
	v_add_f32_e32 v5, v2, v5
	v_mov_b32_e32 v8, v5
	s_nop 1
	v_permlane32_swap_b32_e32 v5, v8
	v_lshlrev_b32_e32 v2, 6, v151
	s_waitcnt lgkmcnt(0)
	v_add_f32_e32 v5, v5, v8
	v_mul_f32_e32 v8, 0x4f800000, v5
	v_cmp_gt_f32_e32 vcc, s0, v5
	s_nop 1
	v_cndmask_b32_e32 v5, v5, v8, vcc
	v_sqrt_f32_e32 v8, v5
	s_nop 0
	v_add_u32_e32 v9, -1, v8
	v_add_u32_e32 v10, 1, v8
	v_fma_f32 v13, -v9, v8, v5
	v_fma_f32 v14, -v10, v8, v5
	v_cmp_ge_f32_e64 s[44:45], 0, v13
	s_nop 1
	v_cndmask_b32_e64 v8, v8, v9, s[44:45]
	v_cmp_lt_f32_e64 s[44:45], 0, v14
	s_nop 1
	v_cndmask_b32_e64 v8, v8, v10, s[44:45]
	v_mul_f32_e32 v9, 0x37800000, v8
	v_cndmask_b32_e32 v8, v8, v9, vcc
	v_cmp_class_f32_e32 vcc, v5, v204
	s_waitcnt vmcnt(24)
	v_sub_f32_e32 v10, v176, v169
	v_fmac_f32_e32 v11, v146, v10
	v_cndmask_b32_e32 v5, v8, v5, vcc
	v_max_f32_e32 v5, 0x2b8cbccc, v5
	v_div_scale_f32 v8, s[0:1], v5, v5, v4
	v_rcp_f32_e32 v9, v8
	s_movk_i32 s0, 0x100
	v_or3_b32 v234, v2, v7, s0
	v_fma_f32 v10, -v8, v9, 1.0
	v_fmac_f32_e32 v9, v10, v9
	v_div_scale_f32 v10, vcc, v4, v5, v4
	v_mul_f32_e32 v13, v10, v9
	v_fma_f32 v14, -v8, v13, v10
	v_fmac_f32_e32 v13, v14, v9
	v_fma_f32 v8, -v8, v13, v10
	v_div_fmas_f32 v8, v8, v9, v13
	v_div_fixup_f32 v13, v8, v5, v4
	s_waitcnt vmcnt(23)
	v_add_f32_e32 v4, -1.0, v179
	v_fma_f32 v4, v149, v4, 1.0
	v_mul_f32_e32 v14, v3, v4
	v_mul_f32_e32 v3, v12, v14
	v_mul_f32_e32 v15, v179, v13
	v_mul_f32_e32 v4, v150, v3
	v_mul_f32_e32 v8, v12, v15
	v_xor_b32_e32 v13, 0x80000000, v13
	v_mov_b32_dpp v4, v4 quad_perm:[1,0,3,2] row_mask:0xf bank_mask:0xf bound_ctrl:1
	v_fmac_f32_e32 v4, v150, v3
	v_mov_b32_dpp v8, v8 quad_perm:[1,0,3,2] row_mask:0xf bank_mask:0xf bound_ctrl:1
	v_mov_b32_dpp v3, v3 quad_perm:[1,0,3,2] row_mask:0xf bank_mask:0xf bound_ctrl:1
	v_fmac_f32_e32 v8, v12, v15
	v_fmac_f32_e32 v3, v12, v14
	v_add_f32_dpp v4, v4, v4 quad_perm:[2,3,0,1] row_mask:0xf bank_mask:0xf bound_ctrl:1
	v_add_f32_dpp v8, v8, v8 quad_perm:[2,3,0,1] row_mask:0xf bank_mask:0xf bound_ctrl:1
	v_add_f32_dpp v3, v3, v3 quad_perm:[2,3,0,1] row_mask:0xf bank_mask:0xf bound_ctrl:1
	v_add_f32_dpp v4, v4, v4 row_half_mirror row_mask:0xf bank_mask:0xf bound_ctrl:1
	v_add_f32_dpp v8, v8, v8 row_half_mirror row_mask:0xf bank_mask:0xf bound_ctrl:1
	v_add_f32_dpp v3, v3, v3 row_half_mirror row_mask:0xf bank_mask:0xf bound_ctrl:1
	v_add_f32_dpp v4, v4, v4 row_mirror row_mask:0xf bank_mask:0xf bound_ctrl:1
	v_add_f32_dpp v8, v8, v8 row_mirror row_mask:0xf bank_mask:0xf bound_ctrl:1
	v_add_f32_dpp v10, v3, v3 row_mirror row_mask:0xf bank_mask:0xf bound_ctrl:1
	v_mov_b32_e32 v5, v4
	s_nop 1
	v_permlane16_swap_b32_e32 v4, v5
	v_mov_b32_e32 v9, v8
	s_nop 1
	v_permlane16_swap_b32_e32 v8, v9
	v_mov_b32_e32 v16, v10
	s_nop 1
	v_permlane16_swap_b32_e32 v10, v16
	s_waitcnt vmcnt(22)
	v_mul_f32_e32 v12, v12, v178
	s_waitcnt lgkmcnt(2)
	v_add_f32_e32 v3, v4, v5
	s_waitcnt lgkmcnt(1)
	v_add_f32_e32 v4, v8, v9
	s_waitcnt lgkmcnt(0)
	v_add_f32_e32 v9, v10, v16
	v_mov_b32_e32 v5, v3
	s_nop 1
	v_permlane32_swap_b32_e32 v3, v5
	v_mov_b32_e32 v8, v4
	s_nop 1
	v_permlane32_swap_b32_e32 v4, v8
	v_mov_b32_e32 v10, v9
	s_nop 1
	v_permlane32_swap_b32_e32 v9, v10
	v_lshl_add_u32 v16, v234, 2, s33
	ds_write2st64_b32 v16, v178, v13 offset1:16
	ds_write2st64_b32 v16, v15, v14 offset0:32 offset1:48
	ds_write2st64_b32 v16, v12, v11 offset0:64 offset1:80
	s_and_saveexec_b64 s[0:1], s[42:43]
	s_cbranch_execz .LBB0_628
	s_waitcnt lgkmcnt(3)
	v_add_f32_e32 v9, v9, v10
	v_add_f32_e32 v3, v3, v5
	v_add_f32_e32 v3, v3, v9
	v_add_f32_e32 v4, v4, v8
	v_add_u32_e32 v5, 0x6000, v0
	ds_write2_b32 v5, v4, v3 offset0:4 offset1:20
.LBB0_628:
	s_or_b64 exec, exec, s[0:1]
	s_waitcnt vmcnt(17)
	v_sub_f32_e32 v3, v185, v181
	v_fma_f32 v3, v143, v3, v181
	s_waitcnt vmcnt(14)
	v_sub_f32_e32 v4, v188, v181
	v_fmac_f32_e32 v3, v145, v4
	v_mul_f32_e32 v4, v148, v3
	s_waitcnt lgkmcnt(5)
	v_mul_f32_e32 v5, v4, v4
	s_mov_b32 s0, 0xf800000
	v_sub_f32_e32 v9, v184, v180
	v_mov_b32_dpp v5, v5 quad_perm:[1,0,3,2] row_mask:0xf bank_mask:0xf bound_ctrl:1
	v_fmac_f32_e32 v5, v4, v4
	s_waitcnt lgkmcnt(3)
	v_sub_f32_e32 v10, v186, v180
	v_fma_f32 v12, v142, v9, v180
	v_add_f32_dpp v5, v5, v5 quad_perm:[2,3,0,1] row_mask:0xf bank_mask:0xf bound_ctrl:1
	v_fmac_f32_e32 v12, v144, v10
	v_sub_f32_e32 v11, v183, v182
	v_add_f32_dpp v5, v5, v5 row_half_mirror row_mask:0xf bank_mask:0xf bound_ctrl:1
	v_fma_f32 v11, v147, v11, v182
	s_nop 0
	v_add_f32_dpp v5, v5, v5 row_mirror row_mask:0xf bank_mask:0xf bound_ctrl:1
	v_mov_b32_e32 v8, v5
	s_nop 1
	v_permlane16_swap_b32_e32 v5, v8
	s_waitcnt lgkmcnt(0)
	v_add_f32_e32 v5, v5, v8
	v_mov_b32_e32 v8, v5
	s_nop 1
	v_permlane32_swap_b32_e32 v5, v8
	s_waitcnt lgkmcnt(0)
	v_add_f32_e32 v5, v5, v8
	v_mul_f32_e32 v8, 0x4f800000, v5
	v_cmp_gt_f32_e32 vcc, s0, v5
	s_nop 1
	v_cndmask_b32_e32 v5, v5, v8, vcc
	v_sqrt_f32_e32 v8, v5
	s_nop 0
	v_add_u32_e32 v9, -1, v8
	v_add_u32_e32 v10, 1, v8
	v_fma_f32 v13, -v9, v8, v5
	v_fma_f32 v14, -v10, v8, v5
	v_cmp_ge_f32_e64 s[44:45], 0, v13
	s_nop 1
	v_cndmask_b32_e64 v8, v8, v9, s[44:45]
	v_cmp_lt_f32_e64 s[44:45], 0, v14
	s_nop 1
	v_cndmask_b32_e64 v8, v8, v10, s[44:45]
	v_mul_f32_e32 v9, 0x37800000, v8
	v_cndmask_b32_e32 v8, v8, v9, vcc
	v_cmp_class_f32_e32 vcc, v5, v204
	s_waitcnt vmcnt(13)
	v_sub_f32_e32 v10, v187, v182
	v_fmac_f32_e32 v11, v146, v10
	v_cndmask_b32_e32 v5, v8, v5, vcc
	v_max_f32_e32 v5, 0x2b8cbccc, v5
	v_div_scale_f32 v8, s[0:1], v5, v5, v4
	v_rcp_f32_e32 v9, v8
	s_movk_i32 s0, 0x200
	v_or3_b32 v239, v2, v7, s0
	v_fma_f32 v10, -v8, v9, 1.0
	v_fmac_f32_e32 v9, v10, v9
	v_div_scale_f32 v10, vcc, v4, v5, v4
	v_mul_f32_e32 v13, v10, v9
	v_fma_f32 v14, -v8, v13, v10
	v_fmac_f32_e32 v13, v14, v9
	v_fma_f32 v8, -v8, v13, v10
	v_div_fmas_f32 v8, v8, v9, v13
	v_div_fixup_f32 v13, v8, v5, v4
	s_waitcnt vmcnt(12)
	v_add_f32_e32 v4, -1.0, v191
	v_fma_f32 v4, v149, v4, 1.0
	v_mul_f32_e32 v14, v3, v4
	v_mul_f32_e32 v3, v12, v14
	v_mul_f32_e32 v15, v191, v13
	v_mul_f32_e32 v4, v150, v3
	v_mul_f32_e32 v8, v12, v15
	v_xor_b32_e32 v13, 0x80000000, v13
	v_mov_b32_dpp v4, v4 quad_perm:[1,0,3,2] row_mask:0xf bank_mask:0xf bound_ctrl:1
	v_fmac_f32_e32 v4, v150, v3
	v_mov_b32_dpp v8, v8 quad_perm:[1,0,3,2] row_mask:0xf bank_mask:0xf bound_ctrl:1
	v_mov_b32_dpp v3, v3 quad_perm:[1,0,3,2] row_mask:0xf bank_mask:0xf bound_ctrl:1
	v_fmac_f32_e32 v8, v12, v15
	v_fmac_f32_e32 v3, v12, v14
	v_add_f32_dpp v4, v4, v4 quad_perm:[2,3,0,1] row_mask:0xf bank_mask:0xf bound_ctrl:1
	v_add_f32_dpp v8, v8, v8 quad_perm:[2,3,0,1] row_mask:0xf bank_mask:0xf bound_ctrl:1
	v_add_f32_dpp v3, v3, v3 quad_perm:[2,3,0,1] row_mask:0xf bank_mask:0xf bound_ctrl:1
	v_add_f32_dpp v4, v4, v4 row_half_mirror row_mask:0xf bank_mask:0xf bound_ctrl:1
	v_add_f32_dpp v8, v8, v8 row_half_mirror row_mask:0xf bank_mask:0xf bound_ctrl:1
	v_add_f32_dpp v3, v3, v3 row_half_mirror row_mask:0xf bank_mask:0xf bound_ctrl:1
	v_add_f32_dpp v4, v4, v4 row_mirror row_mask:0xf bank_mask:0xf bound_ctrl:1
	v_add_f32_dpp v8, v8, v8 row_mirror row_mask:0xf bank_mask:0xf bound_ctrl:1
	v_add_f32_dpp v10, v3, v3 row_mirror row_mask:0xf bank_mask:0xf bound_ctrl:1
	v_mov_b32_e32 v5, v4
	s_nop 1
	v_permlane16_swap_b32_e32 v4, v5
	v_mov_b32_e32 v9, v8
	s_nop 1
	v_permlane16_swap_b32_e32 v8, v9
	v_mov_b32_e32 v16, v10
	s_nop 1
	v_permlane16_swap_b32_e32 v10, v16
	s_waitcnt vmcnt(11)
	v_mul_f32_e32 v12, v12, v190
	s_waitcnt lgkmcnt(2)
	v_add_f32_e32 v3, v4, v5
	s_waitcnt lgkmcnt(1)
	v_add_f32_e32 v4, v8, v9
	s_waitcnt lgkmcnt(0)
	v_add_f32_e32 v9, v10, v16
	v_mov_b32_e32 v5, v3
	s_nop 1
	v_permlane32_swap_b32_e32 v3, v5
	v_mov_b32_e32 v8, v4
	s_nop 1
	v_permlane32_swap_b32_e32 v4, v8
	v_mov_b32_e32 v10, v9
	s_nop 1
	v_permlane32_swap_b32_e32 v9, v10
	v_lshl_add_u32 v16, v239, 2, s33
	ds_write2st64_b32 v16, v190, v13 offset1:16
	ds_write2st64_b32 v16, v15, v14 offset0:32 offset1:48
	ds_write2st64_b32 v16, v12, v11 offset0:64 offset1:80
	s_and_saveexec_b64 s[0:1], s[42:43]
	s_cbranch_execz .LBB0_630
	s_waitcnt lgkmcnt(3)
	v_add_f32_e32 v9, v9, v10
	v_add_f32_e32 v3, v3, v5
	v_add_f32_e32 v3, v3, v9
	v_add_f32_e32 v4, v4, v8
	v_add_u32_e32 v5, 0x6000, v0
	ds_write2_b32 v5, v4, v3 offset0:8 offset1:24
.LBB0_630:
	s_or_b64 exec, exec, s[0:1]
	s_waitcnt vmcnt(6)
	v_sub_f32_e32 v3, v232, v193
	v_fma_f32 v3, v143, v3, v193
	s_waitcnt vmcnt(3)
	v_sub_f32_e32 v4, v236, v193
	v_fmac_f32_e32 v3, v145, v4
	v_mul_f32_e32 v4, v148, v3
	s_waitcnt lgkmcnt(5)
	v_mul_f32_e32 v5, v4, v4
	s_mov_b32 s0, 0xf800000
	v_sub_f32_e32 v9, v231, v192
	v_mov_b32_dpp v5, v5 quad_perm:[1,0,3,2] row_mask:0xf bank_mask:0xf bound_ctrl:1
	v_fmac_f32_e32 v5, v4, v4
	s_waitcnt lgkmcnt(3)
	v_sub_f32_e32 v10, v233, v192
	v_fma_f32 v12, v142, v9, v192
	v_add_f32_dpp v5, v5, v5 quad_perm:[2,3,0,1] row_mask:0xf bank_mask:0xf bound_ctrl:1
	v_fmac_f32_e32 v12, v144, v10
	v_sub_f32_e32 v11, v195, v194
	v_add_f32_dpp v5, v5, v5 row_half_mirror row_mask:0xf bank_mask:0xf bound_ctrl:1
	v_fma_f32 v11, v147, v11, v194
	s_nop 0
	v_add_f32_dpp v5, v5, v5 row_mirror row_mask:0xf bank_mask:0xf bound_ctrl:1
	v_mov_b32_e32 v8, v5
	s_nop 1
	v_permlane16_swap_b32_e32 v5, v8
	s_waitcnt lgkmcnt(0)
	v_add_f32_e32 v5, v5, v8
	v_mov_b32_e32 v8, v5
	s_nop 1
	v_permlane32_swap_b32_e32 v5, v8
	s_waitcnt lgkmcnt(0)
	v_add_f32_e32 v5, v5, v8
	v_mul_f32_e32 v8, 0x4f800000, v5
	v_cmp_gt_f32_e32 vcc, s0, v5
	s_nop 1
	v_cndmask_b32_e32 v5, v5, v8, vcc
	v_sqrt_f32_e32 v8, v5
	s_nop 0
	v_add_u32_e32 v9, -1, v8
	v_add_u32_e32 v10, 1, v8
	v_fma_f32 v13, -v9, v8, v5
	v_fma_f32 v14, -v10, v8, v5
	v_cmp_ge_f32_e64 s[44:45], 0, v13
	s_nop 1
	v_cndmask_b32_e64 v8, v8, v9, s[44:45]
	v_cmp_lt_f32_e64 s[44:45], 0, v14
	s_nop 1
	v_cndmask_b32_e64 v8, v8, v10, s[44:45]
	v_mul_f32_e32 v9, 0x37800000, v8
	v_cndmask_b32_e32 v8, v8, v9, vcc
	v_cmp_class_f32_e32 vcc, v5, v204
	s_waitcnt vmcnt(2)
	v_sub_f32_e32 v10, v235, v194
	v_fmac_f32_e32 v11, v146, v10
	v_cndmask_b32_e32 v5, v8, v5, vcc
	v_max_f32_e32 v5, 0x2b8cbccc, v5
	v_div_scale_f32 v8, s[0:1], v5, v5, v4
	v_rcp_f32_e32 v9, v8
	s_movk_i32 s0, 0x300
	v_or3_b32 v242, v2, v7, s0
	v_lshl_add_u32 v2, v242, 2, s33
	v_fma_f32 v10, -v8, v9, 1.0
	v_fmac_f32_e32 v9, v10, v9
	v_div_scale_f32 v10, vcc, v4, v5, v4
	v_mul_f32_e32 v13, v10, v9
	v_fma_f32 v14, -v8, v13, v10
	v_fmac_f32_e32 v13, v14, v9
	v_fma_f32 v8, -v8, v13, v10
	v_div_fmas_f32 v8, v8, v9, v13
	v_div_fixup_f32 v13, v8, v5, v4
	s_waitcnt vmcnt(1)
	v_add_f32_e32 v4, -1.0, v238
	v_fma_f32 v4, v149, v4, 1.0
	v_mul_f32_e32 v14, v3, v4
	v_mul_f32_e32 v3, v12, v14
	v_mul_f32_e32 v15, v238, v13
	v_mul_f32_e32 v4, v150, v3
	v_mul_f32_e32 v8, v12, v15
	v_xor_b32_e32 v7, 0x80000000, v13
	v_mov_b32_dpp v4, v4 quad_perm:[1,0,3,2] row_mask:0xf bank_mask:0xf bound_ctrl:1
	v_fmac_f32_e32 v4, v150, v3
	v_mov_b32_dpp v8, v8 quad_perm:[1,0,3,2] row_mask:0xf bank_mask:0xf bound_ctrl:1
	v_mov_b32_dpp v3, v3 quad_perm:[1,0,3,2] row_mask:0xf bank_mask:0xf bound_ctrl:1
	v_fmac_f32_e32 v8, v12, v15
	v_fmac_f32_e32 v3, v12, v14
	v_add_f32_dpp v4, v4, v4 quad_perm:[2,3,0,1] row_mask:0xf bank_mask:0xf bound_ctrl:1
	v_add_f32_dpp v8, v8, v8 quad_perm:[2,3,0,1] row_mask:0xf bank_mask:0xf bound_ctrl:1
	v_add_f32_dpp v3, v3, v3 quad_perm:[2,3,0,1] row_mask:0xf bank_mask:0xf bound_ctrl:1
	v_add_f32_dpp v4, v4, v4 row_half_mirror row_mask:0xf bank_mask:0xf bound_ctrl:1
	v_add_f32_dpp v8, v8, v8 row_half_mirror row_mask:0xf bank_mask:0xf bound_ctrl:1
	v_add_f32_dpp v3, v3, v3 row_half_mirror row_mask:0xf bank_mask:0xf bound_ctrl:1
	v_add_f32_dpp v4, v4, v4 row_mirror row_mask:0xf bank_mask:0xf bound_ctrl:1
	v_add_f32_dpp v8, v8, v8 row_mirror row_mask:0xf bank_mask:0xf bound_ctrl:1
	v_add_f32_dpp v10, v3, v3 row_mirror row_mask:0xf bank_mask:0xf bound_ctrl:1
	v_mov_b32_e32 v5, v4
	s_nop 1
	v_permlane16_swap_b32_e32 v4, v5
	v_mov_b32_e32 v9, v8
	s_nop 1
	v_permlane16_swap_b32_e32 v8, v9
	v_mov_b32_e32 v16, v10
	s_nop 1
	v_permlane16_swap_b32_e32 v10, v16
	s_waitcnt vmcnt(0)
	ds_write2st64_b32 v2, v237, v7 offset1:16
	ds_write2st64_b32 v2, v15, v14 offset0:32 offset1:48
	v_mul_f32_e32 v7, v12, v237
	s_waitcnt lgkmcnt(4)
	v_add_f32_e32 v3, v4, v5
	s_waitcnt lgkmcnt(3)
	v_add_f32_e32 v4, v8, v9
	s_waitcnt lgkmcnt(2)
	v_add_f32_e32 v9, v10, v16
	v_mov_b32_e32 v5, v3
	s_nop 1
	v_permlane32_swap_b32_e32 v3, v5
	v_mov_b32_e32 v8, v4
	s_nop 1
	v_permlane32_swap_b32_e32 v4, v8
	v_mov_b32_e32 v10, v9
	s_nop 1
	v_permlane32_swap_b32_e32 v9, v10
	ds_write2st64_b32 v2, v7, v11 offset0:64 offset1:80
	s_and_saveexec_b64 s[0:1], s[42:43]
	s_cbranch_execz .LBB0_632
	s_waitcnt lgkmcnt(1)
	v_add_f32_e32 v2, v9, v10
	v_add_f32_e32 v3, v3, v5
	v_add_f32_e32 v2, v3, v2
	v_add_f32_e32 v3, v4, v8
	v_add_u32_e32 v0, 0x6000, v0
	ds_write2_b32 v0, v3, v2 offset0:12 offset1:28

.LBB0_673:
	s_and_b64 vcc, exec, s[28:29]
	s_cbranch_vccz .LBB0_683
	s_waitcnt vmcnt(17)
	v_sub_f32_e32 v0, v160, v154
	v_fma_f32 v0, v143, v0, v154
	v_sub_f32_e32 v34, v164, v154
	v_fmac_f32_e32 v0, v145, v34
	v_mul_f32_e32 v34, v148, v0
	v_mul_f32_e32 v35, v34, v34
	s_mov_b32 s1, 0xf800000
	v_sub_f32_e32 v37, v157, v153
	v_mov_b32_dpp v35, v35 quad_perm:[1,0,3,2] row_mask:0xf bank_mask:0xf bound_ctrl:1
	v_fmac_f32_e32 v35, v34, v34
	v_sub_f32_e32 v38, v162, v153
	v_fma_f32 v40, v142, v37, v153
	v_add_f32_dpp v35, v35, v35 quad_perm:[2,3,0,1] row_mask:0xf bank_mask:0xf bound_ctrl:1
	v_fmac_f32_e32 v40, v144, v38
	s_bitcmp1_b32 s90, 0
	v_add_f32_dpp v35, v35, v35 row_half_mirror row_mask:0xf bank_mask:0xf bound_ctrl:1
	s_cselect_b32 s0, 0x6080, 0
	s_add_i32 s28, s33, s0
	v_add_f32_dpp v35, v35, v35 row_mirror row_mask:0xf bank_mask:0xf bound_ctrl:1
	v_mov_b32_e32 v36, v35
	s_nop 1
	v_permlane16_swap_b32_e32 v35, v36
	v_sub_f32_e32 v39, v156, v155
	v_fma_f32 v41, v147, v39, v155
	s_waitcnt lgkmcnt(0)
	v_add_f32_e32 v35, v35, v36
	v_mov_b32_e32 v36, v35
	s_nop 1
	v_permlane32_swap_b32_e32 v35, v36
	s_waitcnt lgkmcnt(0)
	v_add_f32_e32 v35, v35, v36
	v_mul_f32_e32 v36, 0x4f800000, v35
	v_cmp_gt_f32_e32 vcc, s1, v35
	s_nop 1
	v_cndmask_b32_e32 v35, v35, v36, vcc
	v_sqrt_f32_e32 v36, v35
	s_nop 0
	v_add_u32_e32 v37, -1, v36
	v_fma_f32 v38, -v37, v36, v35
	v_cmp_ge_f32_e64 s[46:47], 0, v38
	v_add_u32_e32 v38, 1, v36
	s_nop 0
	v_cndmask_b32_e64 v37, v36, v37, s[46:47]
	v_fma_f32 v36, -v38, v36, v35
	v_cmp_lt_f32_e64 s[46:47], 0, v36
	s_nop 1
	v_cndmask_b32_e64 v36, v37, v38, s[46:47]
	v_mul_f32_e32 v37, 0x37800000, v36
	v_cndmask_b32_e32 v36, v36, v37, vcc
	v_cmp_class_f32_e32 vcc, v35, v204
	v_sub_f32_e32 v38, v163, v155
	v_fmac_f32_e32 v41, v146, v38
	v_cndmask_b32_e32 v35, v36, v35, vcc
	v_max_f32_e32 v35, 0x2b8cbccc, v35
	v_div_scale_f32 v36, s[0:1], v35, v35, v34
	v_rcp_f32_e32 v37, v36
	s_nop 0
	v_fma_f32 v38, -v36, v37, 1.0
	v_fmac_f32_e32 v37, v38, v37
	v_div_scale_f32 v38, vcc, v34, v35, v34
	v_mul_f32_e32 v39, v38, v37
	v_fma_f32 v42, -v36, v39, v38
	v_fmac_f32_e32 v39, v42, v37
	v_fma_f32 v36, -v36, v39, v38
	v_div_fmas_f32 v36, v36, v37, v39
	v_div_fixup_f32 v42, v36, v35, v34
	s_waitcnt vmcnt(16)
	v_add_f32_e32 v34, -1.0, v166
	v_fma_f32 v34, v149, v34, 1.0
	v_mul_f32_e32 v0, v0, v34
	v_mul_f32_e32 v34, v40, v0
	v_mul_f32_e32 v43, v166, v42
	v_mul_f32_e32 v35, v150, v34
	v_mul_f32_e32 v37, v40, v43
	v_xor_b32_e32 v42, 0x80000000, v42
	v_mov_b32_dpp v35, v35 quad_perm:[1,0,3,2] row_mask:0xf bank_mask:0xf bound_ctrl:1
	v_fmac_f32_e32 v35, v150, v34
	v_mov_b32_dpp v37, v37 quad_perm:[1,0,3,2] row_mask:0xf bank_mask:0xf bound_ctrl:1
	v_mov_b32_dpp v34, v34 quad_perm:[1,0,3,2] row_mask:0xf bank_mask:0xf bound_ctrl:1
	v_fmac_f32_e32 v37, v40, v43
	v_fmac_f32_e32 v34, v40, v0
	v_add_f32_dpp v35, v35, v35 quad_perm:[2,3,0,1] row_mask:0xf bank_mask:0xf bound_ctrl:1
	v_add_f32_dpp v37, v37, v37 quad_perm:[2,3,0,1] row_mask:0xf bank_mask:0xf bound_ctrl:1
	v_add_f32_dpp v34, v34, v34 quad_perm:[2,3,0,1] row_mask:0xf bank_mask:0xf bound_ctrl:1
	v_add_f32_dpp v35, v35, v35 row_half_mirror row_mask:0xf bank_mask:0xf bound_ctrl:1
	v_add_f32_dpp v37, v37, v37 row_half_mirror row_mask:0xf bank_mask:0xf bound_ctrl:1
	v_add_f32_dpp v34, v34, v34 row_half_mirror row_mask:0xf bank_mask:0xf bound_ctrl:1
	v_add_f32_dpp v35, v35, v35 row_mirror row_mask:0xf bank_mask:0xf bound_ctrl:1
	v_add_f32_dpp v37, v37, v37 row_mirror row_mask:0xf bank_mask:0xf bound_ctrl:1
	v_add_f32_dpp v39, v34, v34 row_mirror row_mask:0xf bank_mask:0xf bound_ctrl:1
	v_mov_b32_e32 v36, v35
	s_nop 1
	v_permlane16_swap_b32_e32 v35, v36
	v_mov_b32_e32 v38, v37
	s_nop 1
	v_permlane16_swap_b32_e32 v37, v38
	v_mov_b32_e32 v44, v39
	s_nop 1
	v_permlane16_swap_b32_e32 v39, v44
	s_waitcnt vmcnt(15)
	v_mul_f32_e32 v40, v40, v165
	s_waitcnt lgkmcnt(2)
	v_add_f32_e32 v34, v35, v36
	s_waitcnt lgkmcnt(1)
	v_add_f32_e32 v35, v37, v38
	s_waitcnt lgkmcnt(0)
	v_add_f32_e32 v38, v39, v44
	v_mov_b32_e32 v36, v34
	s_nop 1
	v_permlane32_swap_b32_e32 v34, v36
	v_mov_b32_e32 v37, v35
	s_nop 1
	v_permlane32_swap_b32_e32 v35, v37
	v_mov_b32_e32 v39, v38
	s_nop 1
	v_permlane32_swap_b32_e32 v38, v39
	v_lshl_add_u32 v44, v161, 2, s28
	ds_write_b32 v44, v165
	v_lshl_add_u32 v44, v189, 2, s28
	ds_write2st64_b32 v44, v42, v43 offset0:16 offset1:32
	ds_write2st64_b32 v44, v0, v40 offset0:48 offset1:64
	ds_write_b32 v44, v41 offset:20480
	v_lshl_add_u32 v0, v151, 2, s28
	s_and_saveexec_b64 s[0:1], s[42:43]
	s_cbranch_execz .LBB0_676
	s_waitcnt lgkmcnt(4)
	v_add_f32_e32 v38, v38, v39
	v_add_f32_e32 v34, v34, v36
	v_add_f32_e32 v34, v34, v38
	v_add_f32_e32 v35, v35, v37
	v_add_u32_e32 v36, 0x6000, v0
	ds_write2_b32 v36, v35, v34 offset1:16
.LBB0_676:
	s_or_b64 exec, exec, s[0:1]
	s_waitcnt vmcnt(12)
	v_sub_f32_e32 v34, v172, v168
	v_fma_f32 v34, v143, v34, v168
	v_sub_f32_e32 v35, v177, v168
	v_fmac_f32_e32 v34, v145, v35
	v_mul_f32_e32 v35, v148, v34
	s_waitcnt lgkmcnt(6)
	v_mul_f32_e32 v36, v35, v35
	s_mov_b32 s0, 0xf800000
	v_sub_f32_e32 v38, v171, v167
	v_mov_b32_dpp v36, v36 quad_perm:[1,0,3,2] row_mask:0xf bank_mask:0xf bound_ctrl:1
	v_fmac_f32_e32 v36, v35, v35
	s_waitcnt lgkmcnt(4)
	v_sub_f32_e32 v39, v173, v167
	v_fma_f32 v41, v142, v38, v167
	v_add_f32_dpp v36, v36, v36 quad_perm:[2,3,0,1] row_mask:0xf bank_mask:0xf bound_ctrl:1
	v_fmac_f32_e32 v41, v144, v39
	v_sub_f32_e32 v40, v170, v169
	v_add_f32_dpp v36, v36, v36 row_half_mirror row_mask:0xf bank_mask:0xf bound_ctrl:1
	v_fma_f32 v40, v147, v40, v169
	s_nop 0
	v_add_f32_dpp v36, v36, v36 row_mirror row_mask:0xf bank_mask:0xf bound_ctrl:1
	v_mov_b32_e32 v37, v36
	s_nop 1
	v_permlane16_swap_b32_e32 v36, v37
	s_waitcnt lgkmcnt(0)
	v_add_f32_e32 v36, v36, v37
	v_mov_b32_e32 v37, v36
	s_nop 1
	v_permlane32_swap_b32_e32 v36, v37
	s_waitcnt lgkmcnt(0)
	v_add_f32_e32 v36, v36, v37
	v_mul_f32_e32 v37, 0x4f800000, v36
	v_cmp_gt_f32_e32 vcc, s0, v36
	s_nop 1
	v_cndmask_b32_e32 v36, v36, v37, vcc
	v_sqrt_f32_e32 v37, v36
	s_nop 0
	v_add_u32_e32 v38, -1, v37
	v_add_u32_e32 v39, 1, v37
	v_fma_f32 v42, -v38, v37, v36
	v_fma_f32 v43, -v39, v37, v36
	v_cmp_ge_f32_e64 s[46:47], 0, v42
	s_nop 1
	v_cndmask_b32_e64 v37, v37, v38, s[46:47]
	v_cmp_lt_f32_e64 s[46:47], 0, v43
	s_nop 1
	v_cndmask_b32_e64 v37, v37, v39, s[46:47]
	v_mul_f32_e32 v38, 0x37800000, v37
	v_cndmask_b32_e32 v37, v37, v38, vcc
	v_cmp_class_f32_e32 vcc, v36, v204
	v_sub_f32_e32 v39, v176, v169
	v_fmac_f32_e32 v40, v146, v39
	v_cndmask_b32_e32 v36, v37, v36, vcc
	v_max_f32_e32 v36, 0x2b8cbccc, v36
	v_div_scale_f32 v37, s[0:1], v36, v36, v35
	v_rcp_f32_e32 v38, v37
	s_nop 0
	v_fma_f32 v39, -v37, v38, 1.0
	v_fmac_f32_e32 v38, v39, v38
	v_div_scale_f32 v39, vcc, v35, v36, v35
	v_mul_f32_e32 v42, v39, v38
	v_fma_f32 v43, -v37, v42, v39
	v_fmac_f32_e32 v42, v43, v38
	v_fma_f32 v37, -v37, v42, v39
	v_div_fmas_f32 v37, v37, v38, v42
	v_div_fixup_f32 v42, v37, v36, v35
	s_waitcnt vmcnt(11)
	v_add_f32_e32 v35, -1.0, v179
	v_fma_f32 v35, v149, v35, 1.0
	v_mul_f32_e32 v43, v34, v35
	v_mul_f32_e32 v34, v41, v43
	v_mul_f32_e32 v44, v179, v42
	v_mul_f32_e32 v35, v150, v34
	v_mul_f32_e32 v37, v41, v44
	v_xor_b32_e32 v42, 0x80000000, v42
	v_mov_b32_dpp v35, v35 quad_perm:[1,0,3,2] row_mask:0xf bank_mask:0xf bound_ctrl:1
	v_fmac_f32_e32 v35, v150, v34
	v_mov_b32_dpp v37, v37 quad_perm:[1,0,3,2] row_mask:0xf bank_mask:0xf bound_ctrl:1
	v_mov_b32_dpp v34, v34 quad_perm:[1,0,3,2] row_mask:0xf bank_mask:0xf bound_ctrl:1
	v_fmac_f32_e32 v37, v41, v44
	v_fmac_f32_e32 v34, v41, v43
	v_add_f32_dpp v35, v35, v35 quad_perm:[2,3,0,1] row_mask:0xf bank_mask:0xf bound_ctrl:1
	v_add_f32_dpp v37, v37, v37 quad_perm:[2,3,0,1] row_mask:0xf bank_mask:0xf bound_ctrl:1
	v_add_f32_dpp v34, v34, v34 quad_perm:[2,3,0,1] row_mask:0xf bank_mask:0xf bound_ctrl:1
	v_add_f32_dpp v35, v35, v35 row_half_mirror row_mask:0xf bank_mask:0xf bound_ctrl:1
	v_add_f32_dpp v37, v37, v37 row_half_mirror row_mask:0xf bank_mask:0xf bound_ctrl:1
	v_add_f32_dpp v34, v34, v34 row_half_mirror row_mask:0xf bank_mask:0xf bound_ctrl:1
	v_add_f32_dpp v35, v35, v35 row_mirror row_mask:0xf bank_mask:0xf bound_ctrl:1
	v_add_f32_dpp v37, v37, v37 row_mirror row_mask:0xf bank_mask:0xf bound_ctrl:1
	v_add_f32_dpp v39, v34, v34 row_mirror row_mask:0xf bank_mask:0xf bound_ctrl:1
	v_mov_b32_e32 v36, v35
	s_nop 1
	v_permlane16_swap_b32_e32 v35, v36
	v_mov_b32_e32 v38, v37
	s_nop 1
	v_permlane16_swap_b32_e32 v37, v38
	v_mov_b32_e32 v45, v39
	s_nop 1
	v_permlane16_swap_b32_e32 v39, v45
	s_waitcnt vmcnt(10)
	v_mul_f32_e32 v41, v41, v178
	s_waitcnt lgkmcnt(2)
	v_add_f32_e32 v34, v35, v36
	s_waitcnt lgkmcnt(1)
	v_add_f32_e32 v35, v37, v38
	s_waitcnt lgkmcnt(0)
	v_add_f32_e32 v38, v39, v45
	v_mov_b32_e32 v36, v34
	s_nop 1
	v_permlane32_swap_b32_e32 v34, v36
	v_mov_b32_e32 v37, v35
	s_nop 1
	v_permlane32_swap_b32_e32 v35, v37
	v_mov_b32_e32 v39, v38
	s_nop 1
	v_permlane32_swap_b32_e32 v38, v39
	v_lshl_add_u32 v45, v234, 2, s28
	ds_write_b32 v45, v178
	ds_write2st64_b32 v45, v42, v44 offset0:16 offset1:32
	ds_write2st64_b32 v45, v43, v41 offset0:48 offset1:64
	ds_write_b32 v45, v40 offset:20480
	s_and_saveexec_b64 s[0:1], s[42:43]
	s_cbranch_execz .LBB0_678
	s_waitcnt lgkmcnt(4)
	v_add_f32_e32 v38, v38, v39
	v_add_f32_e32 v34, v34, v36
	v_add_f32_e32 v34, v34, v38
	v_add_f32_e32 v35, v35, v37
	v_add_u32_e32 v36, 0x6000, v0
	ds_write2_b32 v36, v35, v34 offset0:4 offset1:20
.LBB0_678:
	s_or_b64 exec, exec, s[0:1]
	s_waitcnt vmcnt(7)
	v_sub_f32_e32 v34, v185, v181
	v_fma_f32 v34, v143, v34, v181
	v_sub_f32_e32 v35, v188, v181
	v_fmac_f32_e32 v34, v145, v35
	v_mul_f32_e32 v35, v148, v34
	s_waitcnt lgkmcnt(6)
	v_mul_f32_e32 v36, v35, v35
	s_mov_b32 s0, 0xf800000
	v_sub_f32_e32 v38, v184, v180
	v_mov_b32_dpp v36, v36 quad_perm:[1,0,3,2] row_mask:0xf bank_mask:0xf bound_ctrl:1
	v_fmac_f32_e32 v36, v35, v35
	s_waitcnt lgkmcnt(4)
	v_sub_f32_e32 v39, v186, v180
	v_fma_f32 v41, v142, v38, v180
	v_add_f32_dpp v36, v36, v36 quad_perm:[2,3,0,1] row_mask:0xf bank_mask:0xf bound_ctrl:1
	v_fmac_f32_e32 v41, v144, v39
	v_sub_f32_e32 v40, v183, v182
	v_add_f32_dpp v36, v36, v36 row_half_mirror row_mask:0xf bank_mask:0xf bound_ctrl:1
	v_fma_f32 v40, v147, v40, v182
	s_nop 0
	v_add_f32_dpp v36, v36, v36 row_mirror row_mask:0xf bank_mask:0xf bound_ctrl:1
	v_mov_b32_e32 v37, v36
	s_nop 1
	v_permlane16_swap_b32_e32 v36, v37
	s_waitcnt lgkmcnt(0)
	v_add_f32_e32 v36, v36, v37
	v_mov_b32_e32 v37, v36
	s_nop 1
	v_permlane32_swap_b32_e32 v36, v37
	s_waitcnt lgkmcnt(0)
	v_add_f32_e32 v36, v36, v37
	v_mul_f32_e32 v37, 0x4f800000, v36
	v_cmp_gt_f32_e32 vcc, s0, v36
	s_nop 1
	v_cndmask_b32_e32 v36, v36, v37, vcc
	v_sqrt_f32_e32 v37, v36
	s_nop 0
	v_add_u32_e32 v38, -1, v37
	v_add_u32_e32 v39, 1, v37
	v_fma_f32 v42, -v38, v37, v36
	v_fma_f32 v43, -v39, v37, v36
	v_cmp_ge_f32_e64 s[46:47], 0, v42
	s_nop 1
	v_cndmask_b32_e64 v37, v37, v38, s[46:47]
	v_cmp_lt_f32_e64 s[46:47], 0, v43
	s_nop 1
	v_cndmask_b32_e64 v37, v37, v39, s[46:47]
	v_mul_f32_e32 v38, 0x37800000, v37
	v_cndmask_b32_e32 v37, v37, v38, vcc
	v_cmp_class_f32_e32 vcc, v36, v204
	v_sub_f32_e32 v39, v187, v182
	v_fmac_f32_e32 v40, v146, v39
	v_cndmask_b32_e32 v36, v37, v36, vcc
	v_max_f32_e32 v36, 0x2b8cbccc, v36
	v_div_scale_f32 v37, s[0:1], v36, v36, v35
	v_rcp_f32_e32 v38, v37
	s_nop 0
	v_fma_f32 v39, -v37, v38, 1.0
	v_fmac_f32_e32 v38, v39, v38
	v_div_scale_f32 v39, vcc, v35, v36, v35
	v_mul_f32_e32 v42, v39, v38
	v_fma_f32 v43, -v37, v42, v39
	v_fmac_f32_e32 v42, v43, v38
	v_fma_f32 v37, -v37, v42, v39
	v_div_fmas_f32 v37, v37, v38, v42
	v_div_fixup_f32 v42, v37, v36, v35
	s_waitcnt vmcnt(6)
	v_add_f32_e32 v35, -1.0, v191
	v_fma_f32 v35, v149, v35, 1.0
	v_mul_f32_e32 v43, v34, v35
	v_mul_f32_e32 v34, v41, v43
	v_mul_f32_e32 v44, v191, v42
	v_mul_f32_e32 v35, v150, v34
	v_mul_f32_e32 v37, v41, v44
	v_xor_b32_e32 v42, 0x80000000, v42
	v_mov_b32_dpp v35, v35 quad_perm:[1,0,3,2] row_mask:0xf bank_mask:0xf bound_ctrl:1
	v_fmac_f32_e32 v35, v150, v34
	v_mov_b32_dpp v37, v37 quad_perm:[1,0,3,2] row_mask:0xf bank_mask:0xf bound_ctrl:1
	v_mov_b32_dpp v34, v34 quad_perm:[1,0,3,2] row_mask:0xf bank_mask:0xf bound_ctrl:1
	v_fmac_f32_e32 v37, v41, v44
	v_fmac_f32_e32 v34, v41, v43
	v_add_f32_dpp v35, v35, v35 quad_perm:[2,3,0,1] row_mask:0xf bank_mask:0xf bound_ctrl:1
	v_add_f32_dpp v37, v37, v37 quad_perm:[2,3,0,1] row_mask:0xf bank_mask:0xf bound_ctrl:1
	v_add_f32_dpp v34, v34, v34 quad_perm:[2,3,0,1] row_mask:0xf bank_mask:0xf bound_ctrl:1
	v_add_f32_dpp v35, v35, v35 row_half_mirror row_mask:0xf bank_mask:0xf bound_ctrl:1
	v_add_f32_dpp v37, v37, v37 row_half_mirror row_mask:0xf bank_mask:0xf bound_ctrl:1
	v_add_f32_dpp v34, v34, v34 row_half_mirror row_mask:0xf bank_mask:0xf bound_ctrl:1
	v_add_f32_dpp v35, v35, v35 row_mirror row_mask:0xf bank_mask:0xf bound_ctrl:1
	v_add_f32_dpp v37, v37, v37 row_mirror row_mask:0xf bank_mask:0xf bound_ctrl:1
	v_add_f32_dpp v39, v34, v34 row_mirror row_mask:0xf bank_mask:0xf bound_ctrl:1
	v_mov_b32_e32 v36, v35
	s_nop 1
	v_permlane16_swap_b32_e32 v35, v36
	v_mov_b32_e32 v38, v37
	s_nop 1
	v_permlane16_swap_b32_e32 v37, v38
	v_mov_b32_e32 v45, v39
	s_nop 1
	v_permlane16_swap_b32_e32 v39, v45
	s_waitcnt vmcnt(5)
	v_mul_f32_e32 v41, v41, v190
	s_waitcnt lgkmcnt(2)
	v_add_f32_e32 v34, v35, v36
	s_waitcnt lgkmcnt(1)
	v_add_f32_e32 v35, v37, v38
	s_waitcnt lgkmcnt(0)
	v_add_f32_e32 v38, v39, v45
	v_mov_b32_e32 v36, v34
	s_nop 1
	v_permlane32_swap_b32_e32 v34, v36
	v_mov_b32_e32 v37, v35
	s_nop 1
	v_permlane32_swap_b32_e32 v35, v37
	v_mov_b32_e32 v39, v38
	s_nop 1
	v_permlane32_swap_b32_e32 v38, v39
	v_lshl_add_u32 v45, v239, 2, s28
	ds_write_b32 v45, v190
	ds_write2st64_b32 v45, v42, v44 offset0:16 offset1:32
	ds_write2st64_b32 v45, v43, v41 offset0:48 offset1:64
	ds_write_b32 v45, v40 offset:20480
	s_and_saveexec_b64 s[0:1], s[42:43]
	s_cbranch_execz .LBB0_680
	s_waitcnt lgkmcnt(4)
	v_add_f32_e32 v38, v38, v39
	v_add_f32_e32 v34, v34, v36
	v_add_f32_e32 v34, v34, v38
	v_add_f32_e32 v35, v35, v37
	v_add_u32_e32 v36, 0x6000, v0
	ds_write2_b32 v36, v35, v34 offset0:8 offset1:24
.LBB0_680:
	s_or_b64 exec, exec, s[0:1]
	s_waitcnt vmcnt(2)
	v_sub_f32_e32 v34, v232, v193
	v_fma_f32 v34, v143, v34, v193
	v_sub_f32_e32 v35, v236, v193
	v_fmac_f32_e32 v34, v145, v35
	v_mul_f32_e32 v35, v148, v34
	s_waitcnt lgkmcnt(6)
	v_mul_f32_e32 v36, v35, v35
	s_mov_b32 s0, 0xf800000
	v_sub_f32_e32 v38, v231, v192
	v_mov_b32_dpp v36, v36 quad_perm:[1,0,3,2] row_mask:0xf bank_mask:0xf bound_ctrl:1
	v_fmac_f32_e32 v36, v35, v35
	s_waitcnt lgkmcnt(4)
	v_sub_f32_e32 v39, v233, v192
	v_fma_f32 v41, v142, v38, v192
	v_add_f32_dpp v36, v36, v36 quad_perm:[2,3,0,1] row_mask:0xf bank_mask:0xf bound_ctrl:1
	v_fmac_f32_e32 v41, v144, v39
	v_sub_f32_e32 v40, v195, v194
	v_add_f32_dpp v36, v36, v36 row_half_mirror row_mask:0xf bank_mask:0xf bound_ctrl:1
	v_fma_f32 v40, v147, v40, v194
	s_nop 0
	v_add_f32_dpp v36, v36, v36 row_mirror row_mask:0xf bank_mask:0xf bound_ctrl:1
	v_mov_b32_e32 v37, v36
	s_nop 1
	v_permlane16_swap_b32_e32 v36, v37
	s_waitcnt lgkmcnt(0)
	v_add_f32_e32 v36, v36, v37
	v_mov_b32_e32 v37, v36
	s_nop 1
	v_permlane32_swap_b32_e32 v36, v37
	s_waitcnt lgkmcnt(0)
	v_add_f32_e32 v36, v36, v37
	v_mul_f32_e32 v37, 0x4f800000, v36
	v_cmp_gt_f32_e32 vcc, s0, v36
	s_nop 1
	v_cndmask_b32_e32 v36, v36, v37, vcc
	v_sqrt_f32_e32 v37, v36
	s_nop 0
	v_add_u32_e32 v38, -1, v37
	v_add_u32_e32 v39, 1, v37
	v_fma_f32 v42, -v38, v37, v36
	v_fma_f32 v43, -v39, v37, v36
	v_cmp_ge_f32_e64 s[46:47], 0, v42
	s_nop 1
	v_cndmask_b32_e64 v37, v37, v38, s[46:47]
	v_cmp_lt_f32_e64 s[46:47], 0, v43
	s_nop 1
	v_cndmask_b32_e64 v37, v37, v39, s[46:47]
	v_mul_f32_e32 v38, 0x37800000, v37
	v_cndmask_b32_e32 v37, v37, v38, vcc
	v_cmp_class_f32_e32 vcc, v36, v204
	v_sub_f32_e32 v39, v235, v194
	v_fmac_f32_e32 v40, v146, v39
	v_cndmask_b32_e32 v36, v37, v36, vcc
	v_max_f32_e32 v36, 0x2b8cbccc, v36
	v_div_scale_f32 v37, s[0:1], v36, v36, v35
	v_rcp_f32_e32 v38, v37
	s_nop 0
	v_fma_f32 v39, -v37, v38, 1.0
	v_fmac_f32_e32 v38, v39, v38
	v_div_scale_f32 v39, vcc, v35, v36, v35
	v_mul_f32_e32 v42, v39, v38
	v_fma_f32 v43, -v37, v42, v39
	v_fmac_f32_e32 v42, v43, v38
	v_fma_f32 v37, -v37, v42, v39
	v_div_fmas_f32 v37, v37, v38, v42
	v_div_fixup_f32 v42, v37, v36, v35
	s_waitcnt vmcnt(0)
	v_add_f32_e32 v35, -1.0, v238
	v_fma_f32 v35, v149, v35, 1.0
	v_mul_f32_e32 v43, v34, v35
	v_mul_f32_e32 v34, v41, v43
	v_mul_f32_e32 v44, v238, v42
	v_mul_f32_e32 v35, v150, v34
	v_mul_f32_e32 v37, v41, v44
	v_xor_b32_e32 v42, 0x80000000, v42
	v_mov_b32_dpp v35, v35 quad_perm:[1,0,3,2] row_mask:0xf bank_mask:0xf bound_ctrl:1
	v_fmac_f32_e32 v35, v150, v34
	v_mov_b32_dpp v37, v37 quad_perm:[1,0,3,2] row_mask:0xf bank_mask:0xf bound_ctrl:1
	v_mov_b32_dpp v34, v34 quad_perm:[1,0,3,2] row_mask:0xf bank_mask:0xf bound_ctrl:1
	v_fmac_f32_e32 v37, v41, v44
	v_fmac_f32_e32 v34, v41, v43
	v_add_f32_dpp v35, v35, v35 quad_perm:[2,3,0,1] row_mask:0xf bank_mask:0xf bound_ctrl:1
	v_add_f32_dpp v37, v37, v37 quad_perm:[2,3,0,1] row_mask:0xf bank_mask:0xf bound_ctrl:1
	v_add_f32_dpp v34, v34, v34 quad_perm:[2,3,0,1] row_mask:0xf bank_mask:0xf bound_ctrl:1
	v_add_f32_dpp v35, v35, v35 row_half_mirror row_mask:0xf bank_mask:0xf bound_ctrl:1
	v_add_f32_dpp v37, v37, v37 row_half_mirror row_mask:0xf bank_mask:0xf bound_ctrl:1
	v_add_f32_dpp v34, v34, v34 row_half_mirror row_mask:0xf bank_mask:0xf bound_ctrl:1
	v_add_f32_dpp v35, v35, v35 row_mirror row_mask:0xf bank_mask:0xf bound_ctrl:1
	v_add_f32_dpp v37, v37, v37 row_mirror row_mask:0xf bank_mask:0xf bound_ctrl:1
	v_add_f32_dpp v39, v34, v34 row_mirror row_mask:0xf bank_mask:0xf bound_ctrl:1
	v_mov_b32_e32 v36, v35
	s_nop 1
	v_permlane16_swap_b32_e32 v35, v36
	v_mov_b32_e32 v38, v37
	s_nop 1
	v_permlane16_swap_b32_e32 v37, v38
	v_mov_b32_e32 v45, v39
	s_nop 1
	v_permlane16_swap_b32_e32 v39, v45
	v_mul_f32_e32 v41, v41, v237
	s_waitcnt lgkmcnt(2)
	v_add_f32_e32 v34, v35, v36
	s_waitcnt lgkmcnt(1)
	v_add_f32_e32 v35, v37, v38
	s_waitcnt lgkmcnt(0)
	v_add_f32_e32 v38, v39, v45
	v_mov_b32_e32 v36, v34
	s_nop 1
	v_permlane32_swap_b32_e32 v34, v36
	v_mov_b32_e32 v37, v35
	s_nop 1
	v_permlane32_swap_b32_e32 v35, v37
	v_mov_b32_e32 v39, v38
	s_nop 1
	v_permlane32_swap_b32_e32 v38, v39
	v_lshl_add_u32 v45, v242, 2, s28
	ds_write_b32 v45, v237
	ds_write2st64_b32 v45, v42, v44 offset0:16 offset1:32
	ds_write2st64_b32 v45, v43, v41 offset0:48 offset1:64
	ds_write_b32 v45, v40 offset:20480
	s_and_saveexec_b64 s[0:1], s[42:43]
	s_cbranch_execz .LBB0_682
	s_waitcnt lgkmcnt(4)
	v_add_f32_e32 v38, v38, v39
	v_add_f32_e32 v34, v34, v36
	v_add_f32_e32 v34, v34, v38
	v_add_f32_e32 v35, v35, v37
	v_add_u32_e32 v0, 0x6000, v0
	ds_write2_b32 v0, v35, v34 offset0:12 offset1:28

.Lw13_skipdma:
	ds_read_b128 v[144:147], v189
	ds_read_b128 v[148:151], v189 offset:4096
	ds_read_b128 v[152:155], v238 offset:32768
	ds_read_b128 v[156:159], v238 offset:36864
	ds_read_b128 v[160:163], v238 offset:40960
	ds_read_b128 v[164:167], v238 offset:45056
	s_waitcnt lgkmcnt(6)
	s_setprio 1
	v_mfma_f32_32x32x16_bf16 v[112:127], v[4:7], v[12:15], v[112:127]
	v_mfma_f32_32x32x16_bf16 v[80:95], v[8:11], v[12:15], v[80:95]
	v_mfma_f32_32x32x16_bf16 v[128:143], v[4:7], v[246:249], v[128:143]
	v_mfma_f32_32x32x16_bf16 v[96:111], v[8:11], v[246:249], v[96:111]
	v_mfma_f32_32x32x16_bf16 v[64:79], v[4:7], v[214:217], v[64:79]
	v_mfma_f32_32x32x16_bf16 v[16:31], v[8:11], v[214:217], v[16:31]
	v_mfma_f32_32x32x16_bf16 v[48:63], v[4:7], v[218:221], v[48:63]
	v_mfma_f32_32x32x16_bf16 v[32:47], v[8:11], v[218:221], v[32:47]
	s_setprio 0
	ds_read_b128 v[4:7], v190
	ds_read_b128 v[8:11], v190 offset:4096
	ds_read_b128 v[12:15], v239 offset:32768
	ds_read_b128 v[246:249], v239 offset:36864
	ds_read_b128 v[214:217], v239 offset:40960
	ds_read_b128 v[218:221], v239 offset:45056
	s_waitcnt lgkmcnt(6)
	s_setprio 1
	v_mfma_f32_32x32x16_bf16 v[112:127], v[144:147], v[152:155], v[112:127]
	v_mfma_f32_32x32x16_bf16 v[80:95], v[148:151], v[152:155], v[80:95]
	v_mfma_f32_32x32x16_bf16 v[128:143], v[144:147], v[156:159], v[128:143]
	v_mfma_f32_32x32x16_bf16 v[96:111], v[148:151], v[156:159], v[96:111]
	v_mfma_f32_32x32x16_bf16 v[64:79], v[144:147], v[160:163], v[64:79]
	v_mfma_f32_32x32x16_bf16 v[16:31], v[148:151], v[160:163], v[16:31]
	v_mfma_f32_32x32x16_bf16 v[48:63], v[144:147], v[164:167], v[48:63]
	v_mfma_f32_32x32x16_bf16 v[32:47], v[148:151], v[164:167], v[32:47]
	s_setprio 0
	ds_read_b128 v[144:147], v191
	ds_read_b128 v[148:151], v191 offset:4096
	ds_read_b128 v[152:155], v240 offset:32768
	ds_read_b128 v[156:159], v240 offset:36864
	ds_read_b128 v[160:163], v240 offset:40960
	ds_read_b128 v[164:167], v240 offset:45056
	s_waitcnt lgkmcnt(6)
	s_setprio 1
	v_mfma_f32_32x32x16_bf16 v[112:127], v[4:7], v[12:15], v[112:127]
	v_mfma_f32_32x32x16_bf16 v[80:95], v[8:11], v[12:15], v[80:95]
	v_mfma_f32_32x32x16_bf16 v[128:143], v[4:7], v[246:249], v[128:143]
	v_mfma_f32_32x32x16_bf16 v[96:111], v[8:11], v[246:249], v[96:111]
	v_mfma_f32_32x32x16_bf16 v[64:79], v[4:7], v[214:217], v[64:79]
	v_mfma_f32_32x32x16_bf16 v[16:31], v[8:11], v[214:217], v[16:31]
	v_mfma_f32_32x32x16_bf16 v[48:63], v[4:7], v[218:221], v[48:63]
	v_mfma_f32_32x32x16_bf16 v[32:47], v[8:11], v[218:221], v[32:47]
	s_setprio 0
	s_waitcnt lgkmcnt(0)
	s_setprio 1
	v_mfma_f32_32x32x16_bf16 v[112:127], v[144:147], v[152:155], v[112:127]
	v_mfma_f32_32x32x16_bf16 v[80:95], v[148:151], v[152:155], v[80:95]
	v_mfma_f32_32x32x16_bf16 v[128:143], v[144:147], v[156:159], v[128:143]
	v_mfma_f32_32x32x16_bf16 v[96:111], v[148:151], v[156:159], v[96:111]
	v_mfma_f32_32x32x16_bf16 v[64:79], v[144:147], v[160:163], v[64:79]
	v_mfma_f32_32x32x16_bf16 v[16:31], v[148:151], v[160:163], v[16:31]
	v_mfma_f32_32x32x16_bf16 v[48:63], v[144:147], v[164:167], v[48:63]
	v_mfma_f32_32x32x16_bf16 v[32:47], v[148:151], v[164:167], v[32:47]
	s_setprio 0
	s_add_i32 s1, s1, -1
	s_cmp_lg_u32 s1, 0
	s_cbranch_scc1 .Lw13_loop
	s_nop 7
	v_mul_f32_e32 v2, 0xbfb8aa3b, v112
	v_exp_f32_e32 v4, v2
	v_or_b32_e32 v2, s0, v234
	v_ashrrev_i32_e32 v2, 1, v2
	v_ashrrev_i32_e32 v3, 31, v2
	v_add_f32_e32 v4, 1.0, v4
	s_waitcnt vmcnt(7)
	v_lshl_add_u64 v[144:145], v[2:3], 1, v[176:177]
	v_add_u32_e32 v0, s20, v233
	s_movk_i32 s7, 0x1600
	v_mul_f32_e32 v3, 0xbfb8aa3b, v113
	v_exp_f32_e32 v3, v3
	v_rcp_f32_e32 v2, v4
	s_nop 0
	v_mul_f32_e32 v2, v112, v2
	v_mad_i64_i32 v[146:147], s[0:1], v0, s7, v[144:145]
	v_mul_f32_e32 v2, v128, v2
	v_add_f32_e32 v5, 1.0, v3
	v_cvt_pk_bf16_f32 v4, v2, s0
	v_mov_b32_e32 v179, v1
	v_lshl_add_u64 v[2:3], v[146:147], 0, v[178:179]
	global_store_short v[2:3], v4, off
	v_rcp_f32_e32 v4, v5
	v_mul_f32_e32 v5, 0xbfb8aa3b, v114
	v_exp_f32_e32 v5, v5
	v_mul_f32_e32 v4, v113, v4
	v_mul_f32_e32 v4, v129, v4
	v_cvt_pk_bf16_f32 v6, v4, s0
	v_add_f32_e32 v7, 1.0, v5
	s_movk_i32 s4, 0x1000
	v_add_co_u32_e32 v4, vcc, s4, v2
	s_movk_i32 s5, 0x2000
	s_nop 0
	v_addc_co_u32_e32 v5, vcc, 0, v3, vcc
	global_store_short v[4:5], v6, off offset:1536
	v_rcp_f32_e32 v6, v7
	v_mul_f32_e32 v7, 0xbfb8aa3b, v115
	v_exp_f32_e32 v7, v7
	v_mul_f32_e32 v6, v114, v6
	v_mul_f32_e32 v6, v130, v6
	v_cvt_pk_bf16_f32 v8, v6, s0
	v_add_f32_e32 v9, 1.0, v7
	v_add_co_u32_e32 v6, vcc, s5, v2
	v_mov_b32_e32 v181, v1
	s_nop 0
	v_addc_co_u32_e32 v7, vcc, 0, v3, vcc
	global_store_short v[6:7], v8, off offset:3072
	v_rcp_f32_e32 v8, v9
	v_mul_f32_e32 v9, 0xbfb8aa3b, v116
	v_exp_f32_e32 v9, v9
	v_mul_f32_e32 v8, v115, v8
	v_mul_f32_e32 v8, v131, v8
	v_cvt_pk_bf16_f32 v10, v8, s0
	v_add_f32_e32 v11, 1.0, v9
	v_lshl_add_u64 v[8:9], v[146:147], 0, v[180:181]
	global_store_short v[8:9], v10, off
	s_mov_b32 s8, 0xb000
	v_rcp_f32_e32 v10, v11
	v_mul_f32_e32 v11, 0xbfb8aa3b, v117
	v_exp_f32_e32 v11, v11
	v_mul_f32_e32 v10, v116, v10
	v_mul_f32_e32 v10, v132, v10
	v_cvt_pk_bf16_f32 v12, v10, s0
	v_add_f32_e32 v13, 1.0, v11
	v_add_co_u32_e32 v10, vcc, s8, v2
	s_mov_b32 s6, 0xd000
	s_nop 0
	v_addc_co_u32_e32 v11, vcc, 0, v3, vcc
	global_store_short v[10:11], v12, off
	v_rcp_f32_e32 v12, v13
	v_mul_f32_e32 v13, 0xbfb8aa3b, v118
	v_exp_f32_e32 v13, v13
	v_mul_f32_e32 v12, v117, v12
	v_mul_f32_e32 v12, v133, v12
	v_cvt_pk_bf16_f32 v14, v12, s0
	v_add_f32_e32 v15, 1.0, v13
	v_add_co_u32_e32 v12, vcc, s36, v2
	v_mov_b32_e32 v183, v1
	s_nop 0
	v_addc_co_u32_e32 v13, vcc, 0, v3, vcc
	global_store_short v[12:13], v14, off offset:1536
	v_rcp_f32_e32 v14, v15
	v_mul_f32_e32 v15, 0xbfb8aa3b, v119
	v_exp_f32_e32 v15, v15
	v_mul_f32_e32 v14, v118, v14
	v_mul_f32_e32 v14, v134, v14
	v_cvt_pk_bf16_f32 v112, v14, s0
	v_add_f32_e32 v113, 1.0, v15
	v_add_co_u32_e32 v14, vcc, s6, v2
	s_mov_b32 s9, 0x16000
	s_nop 0
	v_addc_co_u32_e32 v15, vcc, 0, v3, vcc
	global_store_short v[14:15], v112, off offset:3072
	v_rcp_f32_e32 v112, v113
	v_mul_f32_e32 v113, 0xbfb8aa3b, v120
	v_exp_f32_e32 v113, v113
	v_mul_f32_e32 v112, v119, v112
	v_mul_f32_e32 v112, v135, v112
	v_cvt_pk_bf16_f32 v114, v112, s0
	v_add_f32_e32 v115, 1.0, v113
	v_lshl_add_u64 v[112:113], v[146:147], 0, v[182:183]
	global_store_short v[112:113], v114, off
	s_mov_b32 s10, 0x17000
	v_rcp_f32_e32 v114, v115
	v_mul_f32_e32 v115, 0xbfb8aa3b, v121
	v_exp_f32_e32 v115, v115
	v_mul_f32_e32 v114, v120, v114
	v_mul_f32_e32 v114, v136, v114
	v_cvt_pk_bf16_f32 v116, v114, s0
	v_add_f32_e32 v117, 1.0, v115
	v_add_co_u32_e32 v114, vcc, s9, v2
	v_mov_b32_e32 v185, v1
	s_nop 0
	v_addc_co_u32_e32 v115, vcc, 0, v3, vcc
	global_store_short v[114:115], v116, off
	v_rcp_f32_e32 v116, v117
	v_mul_f32_e32 v117, 0xbfb8aa3b, v122
	v_exp_f32_e32 v117, v117
	v_mul_f32_e32 v116, v121, v116
	v_mul_f32_e32 v116, v137, v116
	v_cvt_pk_bf16_f32 v118, v116, s0
	v_add_f32_e32 v119, 1.0, v117
	v_add_co_u32_e32 v116, vcc, s10, v2
	s_mov_b32 s11, 0x21000
	s_nop 0
	v_addc_co_u32_e32 v117, vcc, 0, v3, vcc
	global_store_short v[116:117], v118, off offset:1536
	v_rcp_f32_e32 v118, v119
	v_mul_f32_e32 v119, 0xbfb8aa3b, v123
	v_exp_f32_e32 v119, v119
	v_mul_f32_e32 v118, v122, v118
	v_mul_f32_e32 v118, v138, v118
	v_cvt_pk_bf16_f32 v120, v118, s0
	v_add_f32_e32 v121, 1.0, v119
	v_add_co_u32_e32 v118, vcc, s35, v2
	s_mov_b32 s12, 0x22000
	s_nop 0
	v_addc_co_u32_e32 v119, vcc, 0, v3, vcc
	global_store_short v[118:119], v120, off offset:3072
	v_rcp_f32_e32 v120, v121
	v_mul_f32_e32 v121, 0xbfb8aa3b, v124
	v_exp_f32_e32 v121, v121
	v_mul_f32_e32 v120, v123, v120
	v_mul_f32_e32 v120, v139, v120
	v_cvt_pk_bf16_f32 v122, v120, s0
	v_add_f32_e32 v123, 1.0, v121
	v_lshl_add_u64 v[120:121], v[146:147], 0, v[184:185]
	global_store_short v[120:121], v122, off
	s_mov_b32 s13, 0x23000
	v_rcp_f32_e32 v122, v123
	v_mul_f32_e32 v123, 0xbfb8aa3b, v125
	v_exp_f32_e32 v123, v123
	v_mul_f32_e32 v122, v124, v122
	v_mul_f32_e32 v122, v140, v122
	v_cvt_pk_bf16_f32 v124, v122, s0
	v_add_f32_e32 v128, 1.0, v123
	v_add_co_u32_e32 v122, vcc, s11, v2
	v_mov_b32_e32 v187, v1
	s_nop 0
	v_addc_co_u32_e32 v123, vcc, 0, v3, vcc
	global_store_short v[122:123], v124, off
	v_rcp_f32_e32 v124, v128
	v_mul_f32_e32 v128, 0xbfb8aa3b, v126
	v_exp_f32_e32 v128, v128
	v_mul_f32_e32 v124, v125, v124
	v_mul_f32_e32 v124, v141, v124
	v_cvt_pk_bf16_f32 v129, v124, s0
	v_add_f32_e32 v128, 1.0, v128
	v_add_co_u32_e32 v124, vcc, s12, v2
	v_or_b32_e32 v0, 32, v0
	s_nop 0
	v_addc_co_u32_e32 v125, vcc, 0, v3, vcc
	global_store_short v[124:125], v129, off offset:1536
	v_rcp_f32_e32 v128, v128
	v_mul_f32_e32 v129, 0xbfb8aa3b, v127
	v_exp_f32_e32 v129, v129
	v_mul_f32_e32 v126, v126, v128
	v_mul_f32_e32 v126, v142, v126
	v_cvt_pk_bf16_f32 v126, v126, s0
	v_add_f32_e32 v130, 1.0, v129
	v_add_co_u32_e32 v128, vcc, s13, v2
	s_add_i32 s30, s30, s27
	s_nop 0
	v_addc_co_u32_e32 v129, vcc, 0, v3, vcc
	global_store_short v[128:129], v126, off offset:3072
	v_rcp_f32_e32 v126, v130
	s_nop 0
	v_mul_f32_e32 v126, v127, v126
	v_mul_f32_e32 v126, v143, v126
	v_cvt_pk_bf16_f32 v130, v126, s0
	v_mul_f32_e32 v126, 0xbfb8aa3b, v80
	v_exp_f32_e32 v131, v126
	v_lshl_add_u64 v[126:127], v[146:147], 0, v[186:187]
	global_store_short v[126:127], v130, off
	v_mad_i64_i32 v[132:133], s[0:1], v0, s7, v[144:145]
	v_add_f32_e32 v130, 1.0, v131
	s_cmpk_gt_i32 s30, 0x2bf
	v_mul_f32_e32 v131, 0xbfb8aa3b, v81
	v_exp_f32_e32 v131, v131
	v_rcp_f32_e32 v0, v130
	s_nop 0
	v_mul_f32_e32 v0, v80, v0
	v_add_f32_e32 v80, 1.0, v131
	v_mul_f32_e32 v0, v96, v0
	s_nop 0
	v_cvt_pk_bf16_f32 v0, v0, s0
	v_lshl_add_u64 v[130:131], v[132:133], 0, v[178:179]
	global_store_short v[130:131], v0, off
	v_rcp_f32_e32 v0, v80
	v_mul_f32_e32 v80, 0xbfb8aa3b, v82
	v_exp_f32_e32 v80, v80
	v_mul_f32_e32 v0, v81, v0
	v_mul_f32_e32 v0, v97, v0
	v_cvt_pk_bf16_f32 v0, v0, s0
	v_add_f32_e32 v96, 1.0, v80
	v_add_co_u32_e32 v80, vcc, s4, v130
	s_nop 1
	v_addc_co_u32_e32 v81, vcc, 0, v131, vcc
	global_store_short v[80:81], v0, off offset:1536
	v_rcp_f32_e32 v0, v96
	v_mul_f32_e32 v96, 0xbfb8aa3b, v83
	v_exp_f32_e32 v96, v96
	v_mul_f32_e32 v0, v82, v0
	v_mul_f32_e32 v0, v98, v0
	v_cvt_pk_bf16_f32 v0, v0, s0
	v_add_f32_e32 v82, 1.0, v96
	v_add_co_u32_e32 v96, vcc, s5, v130
	s_nop 1
	v_addc_co_u32_e32 v97, vcc, 0, v131, vcc
	global_store_short v[96:97], v0, off offset:3072
	v_mul_f32_e32 v98, 0xbfb8aa3b, v84
	v_exp_f32_e32 v98, v98
	v_rcp_f32_e32 v0, v82
	s_nop 0
	v_mul_f32_e32 v0, v83, v0
	v_add_f32_e32 v98, 1.0, v98
	v_mul_f32_e32 v0, v99, v0
	s_nop 0
	v_cvt_pk_bf16_f32 v0, v0, s0
	v_lshl_add_u64 v[82:83], v[132:133], 0, v[180:181]
	global_store_short v[82:83], v0, off
	v_rcp_f32_e32 v0, v98
	v_mul_f32_e32 v98, 0xbfb8aa3b, v85
	v_exp_f32_e32 v98, v98
	v_mul_f32_e32 v0, v84, v0
	v_mul_f32_e32 v0, v100, v0
	v_cvt_pk_bf16_f32 v0, v0, s0
	v_add_f32_e32 v84, 1.0, v98
	v_add_co_u32_e32 v98, vcc, s8, v130
	s_nop 1
	v_addc_co_u32_e32 v99, vcc, 0, v131, vcc
	global_store_short v[98:99], v0, off
	v_rcp_f32_e32 v0, v84
	v_mul_f32_e32 v84, 0xbfb8aa3b, v86
	v_exp_f32_e32 v84, v84
	v_mul_f32_e32 v0, v85, v0
	v_mul_f32_e32 v0, v101, v0
	v_cvt_pk_bf16_f32 v0, v0, s0
	v_add_f32_e32 v100, 1.0, v84
	v_add_co_u32_e32 v84, vcc, s36, v130
	s_nop 1
	v_addc_co_u32_e32 v85, vcc, 0, v131, vcc
	global_store_short v[84:85], v0, off offset:1536
	v_rcp_f32_e32 v0, v100
	v_mul_f32_e32 v100, 0xbfb8aa3b, v87
	v_exp_f32_e32 v100, v100
	v_mul_f32_e32 v0, v86, v0
	v_mul_f32_e32 v0, v102, v0
	v_cvt_pk_bf16_f32 v0, v0, s0
	v_add_f32_e32 v86, 1.0, v100
	v_add_co_u32_e32 v100, vcc, s6, v130
	s_nop 1
	v_addc_co_u32_e32 v101, vcc, 0, v131, vcc
	global_store_short v[100:101], v0, off offset:3072
	v_mul_f32_e32 v102, 0xbfb8aa3b, v88
	v_exp_f32_e32 v102, v102
	v_rcp_f32_e32 v0, v86
	s_nop 0
	v_mul_f32_e32 v0, v87, v0
	v_add_f32_e32 v102, 1.0, v102
	v_mul_f32_e32 v0, v103, v0
	s_nop 0
	v_cvt_pk_bf16_f32 v0, v0, s0
	v_lshl_add_u64 v[86:87], v[132:133], 0, v[182:183]
	global_store_short v[86:87], v0, off
	v_rcp_f32_e32 v0, v102
	v_mul_f32_e32 v102, 0xbfb8aa3b, v89
	v_exp_f32_e32 v102, v102
	v_mul_f32_e32 v0, v88, v0
	v_mul_f32_e32 v0, v104, v0
	v_cvt_pk_bf16_f32 v0, v0, s0
	v_add_f32_e32 v88, 1.0, v102
	v_add_co_u32_e32 v102, vcc, s9, v130
	s_nop 1
	v_addc_co_u32_e32 v103, vcc, 0, v131, vcc
	global_store_short v[102:103], v0, off
	v_rcp_f32_e32 v0, v88
	v_mul_f32_e32 v88, 0xbfb8aa3b, v90
	v_exp_f32_e32 v88, v88
	v_mul_f32_e32 v0, v89, v0
	v_mul_f32_e32 v0, v105, v0
	v_cvt_pk_bf16_f32 v0, v0, s0
	v_add_f32_e32 v104, 1.0, v88
	v_add_co_u32_e32 v88, vcc, s10, v130
	s_nop 1
	v_addc_co_u32_e32 v89, vcc, 0, v131, vcc
	global_store_short v[88:89], v0, off offset:1536
	v_rcp_f32_e32 v0, v104
	v_mul_f32_e32 v104, 0xbfb8aa3b, v91
	v_exp_f32_e32 v104, v104
	v_mul_f32_e32 v0, v90, v0
	v_mul_f32_e32 v0, v106, v0
	v_cvt_pk_bf16_f32 v0, v0, s0
	v_add_f32_e32 v90, 1.0, v104
	v_add_co_u32_e32 v104, vcc, s35, v130
	s_nop 1
	v_addc_co_u32_e32 v105, vcc, 0, v131, vcc
	global_store_short v[104:105], v0, off offset:3072
	v_mul_f32_e32 v106, 0xbfb8aa3b, v92
	v_exp_f32_e32 v106, v106
	v_rcp_f32_e32 v0, v90
	s_nop 0
	v_mul_f32_e32 v0, v91, v0
	v_add_f32_e32 v106, 1.0, v106
	v_mul_f32_e32 v0, v107, v0
	s_nop 0
	v_cvt_pk_bf16_f32 v0, v0, s0
	v_lshl_add_u64 v[90:91], v[132:133], 0, v[184:185]
	global_store_short v[90:91], v0, off
	v_rcp_f32_e32 v0, v106
	v_mul_f32_e32 v106, 0xbfb8aa3b, v93
	v_exp_f32_e32 v106, v106
	v_mul_f32_e32 v0, v92, v0
	v_mul_f32_e32 v0, v108, v0
	v_cvt_pk_bf16_f32 v0, v0, s0
	v_add_f32_e32 v92, 1.0, v106
	v_add_co_u32_e32 v106, vcc, s11, v130
	s_nop 1
	v_addc_co_u32_e32 v107, vcc, 0, v131, vcc
	global_store_short v[106:107], v0, off
	v_rcp_f32_e32 v0, v92
	v_mul_f32_e32 v92, 0xbfb8aa3b, v94
	v_exp_f32_e32 v92, v92
	v_mul_f32_e32 v0, v93, v0
	v_mul_f32_e32 v0, v109, v0
	v_cvt_pk_bf16_f32 v0, v0, s0
	v_add_f32_e32 v108, 1.0, v92
	v_add_co_u32_e32 v92, vcc, s12, v130
	s_nop 1
	v_addc_co_u32_e32 v93, vcc, 0, v131, vcc
	global_store_short v[92:93], v0, off offset:1536
	v_rcp_f32_e32 v0, v108
	v_mul_f32_e32 v108, 0xbfb8aa3b, v95
	v_exp_f32_e32 v108, v108
	v_mul_f32_e32 v0, v94, v0
	v_mul_f32_e32 v0, v110, v0
	v_cvt_pk_bf16_f32 v0, v0, s0
	v_add_f32_e32 v94, 1.0, v108
	v_add_co_u32_e32 v108, vcc, s13, v130
	s_nop 1
	v_addc_co_u32_e32 v109, vcc, 0, v131, vcc
	global_store_short v[108:109], v0, off offset:3072
	v_mul_f32_e32 v110, 0xbfb8aa3b, v64
	v_exp_f32_e32 v110, v110
	v_rcp_f32_e32 v0, v94
	s_nop 0
	v_mul_f32_e32 v0, v95, v0
	v_add_f32_e32 v110, 1.0, v110
	v_mul_f32_e32 v0, v111, v0
	s_nop 0
	v_cvt_pk_bf16_f32 v0, v0, s0
	v_lshl_add_u64 v[94:95], v[132:133], 0, v[186:187]
	global_store_short v[94:95], v0, off
	v_mul_f32_e32 v111, 0xbfb8aa3b, v65
	v_exp_f32_e32 v111, v111
	v_rcp_f32_e32 v0, v110
	s_nop 0
	v_mul_f32_e32 v0, v64, v0
	v_add_f32_e32 v64, 1.0, v111
	v_mul_f32_e32 v0, v48, v0
	v_cvt_pk_bf16_f32 v0, v0, s0
	global_store_short v[2:3], v0, off offset:64
	v_mul_f32_e32 v3, 0xbfb8aa3b, v66
	v_exp_f32_e32 v3, v3
	v_rcp_f32_e32 v0, v64
	v_add_f32_e32 v2, 1.0, v3
	v_mul_f32_e32 v0, v65, v0
	v_mul_f32_e32 v0, v49, v0
	v_cvt_pk_bf16_f32 v0, v0, s0
	global_store_short v[4:5], v0, off offset:1600
	v_mul_f32_e32 v3, 0xbfb8aa3b, v67
	v_exp_f32_e32 v3, v3
	v_rcp_f32_e32 v0, v2
	s_nop 0
	v_mul_f32_e32 v0, v66, v0
	v_add_f32_e32 v2, 1.0, v3
	v_mul_f32_e32 v0, v50, v0
	v_cvt_pk_bf16_f32 v0, v0, s0
	global_store_short v[6:7], v0, off offset:3136
	v_mul_f32_e32 v3, 0xbfb8aa3b, v68
	v_exp_f32_e32 v3, v3
	v_rcp_f32_e32 v0, v2
	s_nop 0
	v_mul_f32_e32 v0, v67, v0
	v_add_f32_e32 v2, 1.0, v3
	v_mul_f32_e32 v0, v51, v0
	v_cvt_pk_bf16_f32 v0, v0, s0
	global_store_short v[8:9], v0, off offset:64
	v_mul_f32_e32 v3, 0xbfb8aa3b, v69
	v_exp_f32_e32 v3, v3
	v_rcp_f32_e32 v0, v2
	s_nop 0
	v_mul_f32_e32 v0, v68, v0
	v_add_f32_e32 v2, 1.0, v3
	v_mul_f32_e32 v0, v52, v0
	v_cvt_pk_bf16_f32 v0, v0, s0
	global_store_short v[10:11], v0, off offset:64
	v_mul_f32_e32 v3, 0xbfb8aa3b, v70
	v_exp_f32_e32 v3, v3
	v_rcp_f32_e32 v0, v2
	s_nop 0
	v_mul_f32_e32 v0, v69, v0
	v_add_f32_e32 v2, 1.0, v3
	v_mul_f32_e32 v0, v53, v0
	v_cvt_pk_bf16_f32 v0, v0, s0
	global_store_short v[12:13], v0, off offset:1600
	v_mul_f32_e32 v3, 0xbfb8aa3b, v71
	v_exp_f32_e32 v3, v3
	v_rcp_f32_e32 v0, v2
	s_nop 0
	v_mul_f32_e32 v0, v70, v0
	v_add_f32_e32 v2, 1.0, v3
	v_mul_f32_e32 v0, v54, v0
	v_cvt_pk_bf16_f32 v0, v0, s0
	global_store_short v[14:15], v0, off offset:3136
	v_mul_f32_e32 v3, 0xbfb8aa3b, v72
	v_exp_f32_e32 v3, v3
	v_rcp_f32_e32 v0, v2
	s_nop 0
	v_mul_f32_e32 v0, v71, v0
	v_add_f32_e32 v2, 1.0, v3
	v_mul_f32_e32 v0, v55, v0
	v_cvt_pk_bf16_f32 v0, v0, s0
	global_store_short v[112:113], v0, off offset:64
	v_mul_f32_e32 v3, 0xbfb8aa3b, v73
	v_exp_f32_e32 v3, v3
	v_rcp_f32_e32 v0, v2
	s_nop 0
	v_mul_f32_e32 v0, v72, v0
	v_add_f32_e32 v2, 1.0, v3
	v_mul_f32_e32 v0, v56, v0
	v_cvt_pk_bf16_f32 v0, v0, s0
	global_store_short v[114:115], v0, off offset:64
	v_mul_f32_e32 v3, 0xbfb8aa3b, v74
	v_exp_f32_e32 v3, v3
	v_rcp_f32_e32 v0, v2
	s_nop 0
	v_mul_f32_e32 v0, v73, v0
	v_add_f32_e32 v2, 1.0, v3
	v_mul_f32_e32 v0, v57, v0
	v_cvt_pk_bf16_f32 v0, v0, s0
	global_store_short v[116:117], v0, off offset:1600
	v_mul_f32_e32 v3, 0xbfb8aa3b, v75
	v_exp_f32_e32 v3, v3
	v_rcp_f32_e32 v0, v2
	s_nop 0
	v_mul_f32_e32 v0, v74, v0
	v_add_f32_e32 v2, 1.0, v3
	v_mul_f32_e32 v0, v58, v0
	v_cvt_pk_bf16_f32 v0, v0, s0
	global_store_short v[118:119], v0, off offset:3136
	v_mul_f32_e32 v3, 0xbfb8aa3b, v76
	v_exp_f32_e32 v3, v3
	v_rcp_f32_e32 v0, v2
	s_nop 0
	v_mul_f32_e32 v0, v75, v0
	v_add_f32_e32 v2, 1.0, v3
	v_mul_f32_e32 v0, v59, v0
	v_cvt_pk_bf16_f32 v0, v0, s0
	global_store_short v[120:121], v0, off offset:64
	v_mul_f32_e32 v3, 0xbfb8aa3b, v77
	v_exp_f32_e32 v3, v3
	v_rcp_f32_e32 v0, v2
	s_nop 0
	v_mul_f32_e32 v0, v76, v0
	v_add_f32_e32 v2, 1.0, v3
	v_mul_f32_e32 v0, v60, v0
	v_cvt_pk_bf16_f32 v0, v0, s0
	global_store_short v[122:123], v0, off offset:64
	v_mul_f32_e32 v3, 0xbfb8aa3b, v78
	v_exp_f32_e32 v3, v3
	v_rcp_f32_e32 v0, v2
	s_nop 0
	v_mul_f32_e32 v0, v77, v0
	v_add_f32_e32 v2, 1.0, v3
	v_mul_f32_e32 v0, v61, v0
	v_cvt_pk_bf16_f32 v0, v0, s0
	global_store_short v[124:125], v0, off offset:1600
	v_mul_f32_e32 v3, 0xbfb8aa3b, v79
	v_exp_f32_e32 v3, v3
	v_rcp_f32_e32 v0, v2
	s_nop 0
	v_mul_f32_e32 v0, v78, v0
	v_add_f32_e32 v2, 1.0, v3
	v_mul_f32_e32 v0, v62, v0
	v_cvt_pk_bf16_f32 v0, v0, s0
	global_store_short v[128:129], v0, off offset:3136
	v_mul_f32_e32 v3, 0xbfb8aa3b, v16
	v_exp_f32_e32 v3, v3
	v_rcp_f32_e32 v0, v2
	s_nop 0
	v_mul_f32_e32 v0, v79, v0
	v_add_f32_e32 v2, 1.0, v3
	v_mul_f32_e32 v0, v63, v0
	v_cvt_pk_bf16_f32 v0, v0, s0
	global_store_short v[126:127], v0, off offset:64
	v_mul_f32_e32 v3, 0xbfb8aa3b, v17
	v_exp_f32_e32 v3, v3
	v_rcp_f32_e32 v0, v2
	s_nop 0
	v_mul_f32_e32 v0, v16, v0
	v_add_f32_e32 v2, 1.0, v3
	v_mul_f32_e32 v0, v32, v0
	v_cvt_pk_bf16_f32 v0, v0, s0
	global_store_short v[130:131], v0, off offset:64
	v_mul_f32_e32 v3, 0xbfb8aa3b, v18
	v_exp_f32_e32 v3, v3
	v_rcp_f32_e32 v0, v2
	s_nop 0
	v_mul_f32_e32 v0, v17, v0
	v_add_f32_e32 v2, 1.0, v3
	v_mul_f32_e32 v0, v33, v0
	v_cvt_pk_bf16_f32 v0, v0, s0
	global_store_short v[80:81], v0, off offset:1600
	v_mul_f32_e32 v3, 0xbfb8aa3b, v19
	v_exp_f32_e32 v3, v3
	v_rcp_f32_e32 v0, v2
	s_nop 0
	v_mul_f32_e32 v0, v18, v0
	v_add_f32_e32 v2, 1.0, v3
	v_mul_f32_e32 v0, v34, v0
	v_cvt_pk_bf16_f32 v0, v0, s0
	global_store_short v[96:97], v0, off offset:3136
	v_mul_f32_e32 v3, 0xbfb8aa3b, v20
	v_exp_f32_e32 v3, v3
	v_rcp_f32_e32 v0, v2
	s_nop 0
	v_mul_f32_e32 v0, v19, v0
	v_add_f32_e32 v2, 1.0, v3
	v_mul_f32_e32 v0, v35, v0
	v_cvt_pk_bf16_f32 v0, v0, s0
	global_store_short v[82:83], v0, off offset:64
	v_mul_f32_e32 v3, 0xbfb8aa3b, v21
	v_exp_f32_e32 v3, v3
	v_rcp_f32_e32 v0, v2
	s_nop 0
	v_mul_f32_e32 v0, v20, v0
	v_add_f32_e32 v2, 1.0, v3
	v_mul_f32_e32 v0, v36, v0
	v_cvt_pk_bf16_f32 v0, v0, s0
	global_store_short v[98:99], v0, off offset:64
	v_mul_f32_e32 v3, 0xbfb8aa3b, v22
	v_exp_f32_e32 v3, v3
	v_rcp_f32_e32 v0, v2
	s_nop 0
	v_mul_f32_e32 v0, v21, v0
	v_add_f32_e32 v2, 1.0, v3
	v_mul_f32_e32 v0, v37, v0
	v_cvt_pk_bf16_f32 v0, v0, s0
	global_store_short v[84:85], v0, off offset:1600
	v_mul_f32_e32 v3, 0xbfb8aa3b, v23
	v_exp_f32_e32 v3, v3
	v_rcp_f32_e32 v0, v2
	s_nop 0
	v_mul_f32_e32 v0, v22, v0
	v_add_f32_e32 v2, 1.0, v3
	v_mul_f32_e32 v0, v38, v0
	v_cvt_pk_bf16_f32 v0, v0, s0
	global_store_short v[100:101], v0, off offset:3136
	v_mul_f32_e32 v3, 0xbfb8aa3b, v24
	v_exp_f32_e32 v3, v3
	v_rcp_f32_e32 v0, v2
	s_nop 0
	v_mul_f32_e32 v0, v23, v0
	v_add_f32_e32 v2, 1.0, v3
	v_mul_f32_e32 v0, v39, v0
	v_cvt_pk_bf16_f32 v0, v0, s0
	global_store_short v[86:87], v0, off offset:64
	v_mul_f32_e32 v3, 0xbfb8aa3b, v25
	v_exp_f32_e32 v3, v3
	v_rcp_f32_e32 v0, v2
	s_nop 0
	v_mul_f32_e32 v0, v24, v0
	v_add_f32_e32 v2, 1.0, v3
	v_mul_f32_e32 v0, v40, v0
	v_cvt_pk_bf16_f32 v0, v0, s0
	global_store_short v[102:103], v0, off offset:64
	v_mul_f32_e32 v3, 0xbfb8aa3b, v26
	v_exp_f32_e32 v3, v3
	v_rcp_f32_e32 v0, v2
	s_nop 0
	v_mul_f32_e32 v0, v25, v0
	v_add_f32_e32 v2, 1.0, v3
	v_mul_f32_e32 v0, v41, v0
	v_cvt_pk_bf16_f32 v0, v0, s0
	global_store_short v[88:89], v0, off offset:1600
	v_mul_f32_e32 v3, 0xbfb8aa3b, v27
	v_exp_f32_e32 v3, v3
	v_rcp_f32_e32 v0, v2
	s_nop 0
	v_mul_f32_e32 v0, v26, v0
	v_add_f32_e32 v2, 1.0, v3
	v_mul_f32_e32 v0, v42, v0
	v_cvt_pk_bf16_f32 v0, v0, s0
	global_store_short v[104:105], v0, off offset:3136
	v_mul_f32_e32 v3, 0xbfb8aa3b, v28
	v_exp_f32_e32 v3, v3
	v_rcp_f32_e32 v0, v2
	s_nop 0
	v_mul_f32_e32 v0, v27, v0
	v_add_f32_e32 v2, 1.0, v3
	v_mul_f32_e32 v0, v43, v0
	v_cvt_pk_bf16_f32 v0, v0, s0
	global_store_short v[90:91], v0, off offset:64
	v_mul_f32_e32 v3, 0xbfb8aa3b, v29
	v_exp_f32_e32 v3, v3
	v_rcp_f32_e32 v0, v2
	s_nop 0
	v_mul_f32_e32 v0, v28, v0
	v_add_f32_e32 v2, 1.0, v3
	v_mul_f32_e32 v0, v44, v0
	v_cvt_pk_bf16_f32 v0, v0, s0
	global_store_short v[106:107], v0, off offset:64
	v_mul_f32_e32 v3, 0xbfb8aa3b, v30
	v_exp_f32_e32 v3, v3
	v_rcp_f32_e32 v0, v2
	s_nop 0
	v_mul_f32_e32 v0, v29, v0
	v_add_f32_e32 v2, 1.0, v3
	v_mul_f32_e32 v0, v45, v0
	v_cvt_pk_bf16_f32 v0, v0, s0
	global_store_short v[92:93], v0, off offset:1600
	v_mul_f32_e32 v3, 0xbfb8aa3b, v31
	v_exp_f32_e32 v3, v3
	v_rcp_f32_e32 v0, v2
	s_nop 0
	v_mul_f32_e32 v0, v30, v0
	v_add_f32_e32 v2, 1.0, v3
	v_mul_f32_e32 v0, v46, v0
	v_cvt_pk_bf16_f32 v0, v0, s0
	global_store_short v[108:109], v0, off offset:3136
	v_rcp_f32_e32 v0, v2
	s_nop 0
	v_mul_f32_e32 v0, v31, v0
	v_mul_f32_e32 v0, v47, v0
	v_cvt_pk_bf16_f32 v0, v0, s0
	global_store_short v[94:95], v0, off offset:64
	s_cbranch_scc0 .LBB0_941

.LBB0_954:
	s_ashr_i32 s0, s23, 31
	s_lshr_b32 s0, s0, 27
	s_add_i32 s20, s23, s0
	s_and_b32 s0, s20, 0xffffffe0
	s_sub_i32 s26, s23, s0
	s_mul_i32 s0, s26, 0xb0000
	s_ashr_i32 s1, s0, 31
	s_lshl_b32 s20, s20, 2
	s_and_b32 s27, s20, 0xffffff80
	s_lshl_b64 s[0:1], s[0:1], 1
	v_readlane_b32 s4, v254, 21
	v_readlane_b32 s5, v254, 22
	s_add_u32 s0, s4, s0
	s_addc_u32 s1, s5, s1
	s_mul_i32 s20, s27, 0x1600
	s_mul_hi_i32 s21, s27, 0x1600
	s_add_u32 s20, s24, s20
	s_addc_u32 s21, s25, s21
	s_waitcnt lgkmcnt(0)
	v_lshlrev_b32_e32 v142, 1, v133
	v_lshrrev_b32_e32 v140, 3, v196
	v_lshrrev_b32_e32 v141, 4, v196
	v_xor_b32_e32 v141, v141, v196
	v_and_b32_e32 v141, 7, v141
	v_lshlrev_b32_e32 v141, 4, v141
	v_mul_u32_u24_e32 v140, 0x1600, v140
	v_add_u32_e32 v82, v140, v141
	v_add_u32_e32 v83, 0x58000, v82
	v_add_u32_e32 v84, 0xb0000, v82
	v_add_u32_e32 v85, 0x108000, v82
	v_add_u32_e32 v140, 0, v130
	v_xor_b32_e32 v140, v140, v131
	v_lshlrev_b32_e32 v140, 4, v140
	v_add3_u32 v86, v134, v140, 16
	v_add3_u32 v136, v142, v140, 16
	v_add_u32_e32 v140, 2, v130
	v_xor_b32_e32 v140, v140, v131
	v_lshlrev_b32_e32 v140, 4, v140
	v_add3_u32 v87, v134, v140, 16
	v_add3_u32 v137, v142, v140, 16
	v_add_u32_e32 v140, 4, v130
	v_xor_b32_e32 v140, v140, v131
	v_lshlrev_b32_e32 v140, 4, v140
	v_add3_u32 v88, v134, v140, 16
	v_add3_u32 v138, v142, v140, 16
	v_add_u32_e32 v140, 6, v130
	v_xor_b32_e32 v140, v140, v131
	v_lshlrev_b32_e32 v140, 4, v140
	v_add3_u32 v89, v134, v140, 16
	v_add3_u32 v139, v142, v140, 16
	v_lshrrev_b32_e32 v140, 6, v196
	v_mov_b64_e32 v[2:3], 0
	v_mov_b64_e32 v[4:5], 0
	v_mov_b64_e32 v[6:7], 0
	v_mov_b64_e32 v[8:9], 0
	v_mov_b64_e32 v[10:11], 0
	v_mov_b64_e32 v[12:13], 0
	v_mov_b64_e32 v[14:15], 0
	v_mov_b64_e32 v[16:17], 0
	v_mov_b64_e32 v[18:19], 0
	v_mov_b64_e32 v[20:21], 0
	v_mov_b64_e32 v[22:23], 0
	v_mov_b64_e32 v[24:25], 0
	v_mov_b64_e32 v[26:27], 0
	v_mov_b64_e32 v[28:29], 0
	v_mov_b64_e32 v[30:31], 0
	v_mov_b64_e32 v[32:33], 0
	v_mov_b64_e32 v[34:35], 0
	v_mov_b64_e32 v[36:37], 0
	v_mov_b64_e32 v[38:39], 0
	v_mov_b64_e32 v[40:41], 0
	v_mov_b64_e32 v[42:43], 0
	v_mov_b64_e32 v[44:45], 0
	v_mov_b64_e32 v[46:47], 0
	v_mov_b64_e32 v[48:49], 0
	v_mov_b64_e32 v[50:51], 0
	v_mov_b64_e32 v[52:53], 0
	v_mov_b64_e32 v[54:55], 0
	v_mov_b64_e32 v[56:57], 0
	v_mov_b64_e32 v[58:59], 0
	v_mov_b64_e32 v[60:61], 0
	v_mov_b64_e32 v[62:63], 0
	v_mov_b64_e32 v[64:65], 0
	v_readfirstlane_b32 s43, v140
	s_lshl_b32 s43, s43, 10
	s_add_i32 s43, s43, 16
	s_add_i32 vcc_hi, s43, 0xc000
	s_mov_b32 m0, s43
	s_nop 0
	global_load_lds_dwordx4 v82, s[0:1]
	s_add_u32 m0, m0, 0x2000
	s_nop 0
	global_load_lds_dwordx4 v83, s[0:1]
	s_add_u32 m0, m0, 0x2000
	s_nop 0
	global_load_lds_dwordx4 v84, s[0:1]
	s_add_u32 m0, m0, 0x2000
	s_nop 0
	global_load_lds_dwordx4 v85, s[0:1]
	s_add_u32 m0, m0, 0x2000
	s_nop 0
	global_load_lds_dwordx4 v82, s[20:21]
	s_add_u32 m0, m0, 0x2000
	s_nop 0
	global_load_lds_dwordx4 v83, s[20:21]
	s_add_u32 s0, s0, 0x80
	s_addc_u32 s1, s1, 0
	s_add_u32 s20, s20, 0x80
	s_addc_u32 s21, s21, 0
	s_mov_b32 m0, vcc_hi
	s_nop 0
	global_load_lds_dwordx4 v82, s[0:1]
	s_add_u32 m0, m0, 0x2000
	s_nop 0
	global_load_lds_dwordx4 v83, s[0:1]
	s_add_u32 m0, m0, 0x2000
	s_nop 0
	global_load_lds_dwordx4 v84, s[0:1]
	s_add_u32 m0, m0, 0x2000
	s_nop 0
	global_load_lds_dwordx4 v85, s[0:1]
	s_add_u32 m0, m0, 0x2000
	s_nop 0
	global_load_lds_dwordx4 v82, s[20:21]
	s_add_u32 m0, m0, 0x2000
	s_nop 0
	global_load_lds_dwordx4 v83, s[20:21]
	s_add_u32 s0, s0, 0x80
	s_addc_u32 s1, s1, 0
	s_add_u32 s20, s20, 0x80
	s_addc_u32 s21, s21, 0
	s_mov_b32 s41, 0
	s_movk_i32 s40, 43
.Lw2_loop:
	s_waitcnt vmcnt(6)
	s_barrier
	ds_read_b128 v[144:147], v86
	ds_read_b128 v[148:151], v86 offset:4096
	ds_read_b128 v[152:155], v136 offset:32768
	ds_read_b128 v[156:159], v136 offset:36864
	s_cmp_lt_u32 s40, 2
	s_cbranch_scc1 .Lw2_skipdma
	s_add_i32 vcc_hi, s41, 2
	s_cmp_ge_u32 vcc_hi, 3
	s_cselect_b32 vcc_lo, 3, 0
	s_sub_i32 vcc_hi, vcc_hi, vcc_lo
	s_mul_i32 vcc_hi, vcc_hi, 0xc000
	s_add_i32 vcc_hi, vcc_hi, s43
	s_mov_b32 m0, vcc_hi
	s_nop 0
	global_load_lds_dwordx4 v82, s[0:1]
	s_add_u32 m0, m0, 0x2000
	s_nop 0
	global_load_lds_dwordx4 v83, s[0:1]
	s_add_u32 m0, m0, 0x2000
	s_nop 0
	global_load_lds_dwordx4 v84, s[0:1]
	s_add_u32 m0, m0, 0x2000
	s_nop 0
	global_load_lds_dwordx4 v85, s[0:1]
	s_add_u32 m0, m0, 0x2000
	s_nop 0
	global_load_lds_dwordx4 v82, s[20:21]
	s_add_u32 m0, m0, 0x2000
	s_nop 0
	global_load_lds_dwordx4 v83, s[20:21]
	s_add_u32 s0, s0, 0x80
	s_addc_u32 s1, s1, 0
	s_add_u32 s20, s20, 0x80
	s_addc_u32 s21, s21, 0
.Lw2_skipdma:
	ds_read_b128 v[66:69], v87
	ds_read_b128 v[70:73], v87 offset:4096
	ds_read_b128 v[74:77], v137 offset:32768
	ds_read_b128 v[78:81], v137 offset:36864
	s_waitcnt lgkmcnt(4)
	s_setprio 1
	v_mfma_f32_32x32x16_bf16 v[50:65], v[144:147], v[152:155], v[50:65]
	v_mfma_f32_32x32x16_bf16 v[18:33], v[148:151], v[152:155], v[18:33]
	v_mfma_f32_32x32x16_bf16 v[34:49], v[144:147], v[156:159], v[34:49]
	v_mfma_f32_32x32x16_bf16 v[2:17], v[148:151], v[156:159], v[2:17]
	s_setprio 0
	ds_read_b128 v[144:147], v88
	ds_read_b128 v[148:151], v88 offset:4096
	ds_read_b128 v[152:155], v138 offset:32768
	ds_read_b128 v[156:159], v138 offset:36864
	s_waitcnt lgkmcnt(4)
	s_setprio 1
	v_mfma_f32_32x32x16_bf16 v[50:65], v[66:69], v[74:77], v[50:65]
	v_mfma_f32_32x32x16_bf16 v[18:33], v[70:73], v[74:77], v[18:33]
	v_mfma_f32_32x32x16_bf16 v[34:49], v[66:69], v[78:81], v[34:49]
	v_mfma_f32_32x32x16_bf16 v[2:17], v[70:73], v[78:81], v[2:17]
	s_setprio 0
	ds_read_b128 v[66:69], v89
	ds_read_b128 v[70:73], v89 offset:4096
	ds_read_b128 v[74:77], v139 offset:32768
	ds_read_b128 v[78:81], v139 offset:36864
	s_waitcnt lgkmcnt(4)
	s_setprio 1
	v_mfma_f32_32x32x16_bf16 v[50:65], v[144:147], v[152:155], v[50:65]
	v_mfma_f32_32x32x16_bf16 v[18:33], v[148:151], v[152:155], v[18:33]
	v_mfma_f32_32x32x16_bf16 v[34:49], v[144:147], v[156:159], v[34:49]
	v_mfma_f32_32x32x16_bf16 v[2:17], v[148:151], v[156:159], v[2:17]
	s_setprio 0
	s_waitcnt lgkmcnt(0)
	s_setprio 1
	v_mfma_f32_32x32x16_bf16 v[50:65], v[66:69], v[74:77], v[50:65]
	v_mfma_f32_32x32x16_bf16 v[18:33], v[70:73], v[74:77], v[18:33]
	v_mfma_f32_32x32x16_bf16 v[34:49], v[66:69], v[78:81], v[34:49]
	v_mfma_f32_32x32x16_bf16 v[2:17], v[70:73], v[78:81], v[2:17]
	s_setprio 0
	s_add_i32 s41, s41, 1
	s_cmp_eq_u32 s41, 3
	s_cselect_b32 vcc_lo, 0xfffdc000, 0
	s_cselect_b32 s41, 0, s41
	s_add_i32 vcc_lo, vcc_lo, 0xc000
	v_add_u32_e32 v86, vcc_lo, v86
	v_add_u32_e32 v136, vcc_lo, v136
	v_add_u32_e32 v87, vcc_lo, v87
	v_add_u32_e32 v137, vcc_lo, v137
	v_add_u32_e32 v88, vcc_lo, v88
	v_add_u32_e32 v138, vcc_lo, v138
	v_add_u32_e32 v89, vcc_lo, v89
	v_add_u32_e32 v139, vcc_lo, v139
	s_add_i32 s40, s40, -1
	s_cmp_lg_u32 s40, 0
	s_cbranch_scc1 .Lw2_loop
	s_waitcnt vmcnt(0)
	s_barrier
	ds_read_b128 v[144:147], v86
	ds_read_b128 v[148:151], v86 offset:4096
	ds_read_b128 v[152:155], v136 offset:32768
	ds_read_b128 v[156:159], v136 offset:36864
	ds_read_b128 v[66:69], v87
	ds_read_b128 v[70:73], v87 offset:4096
	ds_read_b128 v[74:77], v137 offset:32768
	ds_read_b128 v[78:81], v137 offset:36864
	s_waitcnt lgkmcnt(4)
	s_setprio 1
	v_mfma_f32_32x32x16_bf16 v[50:65], v[144:147], v[152:155], v[50:65]
	v_mfma_f32_32x32x16_bf16 v[18:33], v[148:151], v[152:155], v[18:33]
	v_mfma_f32_32x32x16_bf16 v[34:49], v[144:147], v[156:159], v[34:49]
	v_mfma_f32_32x32x16_bf16 v[2:17], v[148:151], v[156:159], v[2:17]
	s_setprio 0
	ds_read_b128 v[144:147], v88
	ds_read_b128 v[148:151], v88 offset:4096
	ds_read_b128 v[152:155], v138 offset:32768
	ds_read_b128 v[156:159], v138 offset:36864
	s_waitcnt lgkmcnt(4)
	s_setprio 1
	v_mfma_f32_32x32x16_bf16 v[50:65], v[66:69], v[74:77], v[50:65]
	v_mfma_f32_32x32x16_bf16 v[18:33], v[70:73], v[74:77], v[18:33]
	v_mfma_f32_32x32x16_bf16 v[34:49], v[66:69], v[78:81], v[34:49]
	v_mfma_f32_32x32x16_bf16 v[2:17], v[70:73], v[78:81], v[2:17]
	s_setprio 0
	ds_read_b128 v[66:69], v89
	ds_read_b128 v[70:73], v89 offset:4096
	ds_read_b128 v[74:77], v139 offset:32768
	ds_read_b128 v[78:81], v139 offset:36864
	s_waitcnt lgkmcnt(4)
	s_setprio 1
	v_mfma_f32_32x32x16_bf16 v[50:65], v[144:147], v[152:155], v[50:65]
	v_mfma_f32_32x32x16_bf16 v[18:33], v[148:151], v[152:155], v[18:33]
	v_mfma_f32_32x32x16_bf16 v[34:49], v[144:147], v[156:159], v[34:49]
	v_mfma_f32_32x32x16_bf16 v[2:17], v[148:151], v[156:159], v[2:17]
	s_setprio 0
	s_waitcnt lgkmcnt(0)
	s_setprio 1
	v_mfma_f32_32x32x16_bf16 v[50:65], v[66:69], v[74:77], v[50:65]
	v_mfma_f32_32x32x16_bf16 v[18:33], v[70:73], v[74:77], v[18:33]
	v_mfma_f32_32x32x16_bf16 v[34:49], v[66:69], v[78:81], v[34:49]
	v_mfma_f32_32x32x16_bf16 v[2:17], v[70:73], v[78:81], v[2:17]
	s_setprio 0
	s_barrier
	v_mov_b32_e32 v0, v1
	s_nop 7
	s_waitcnt vmcnt(5)
	v_lshl_add_u32 v68, s26, 8, v132
	v_add_u32_e32 v0, 0xfffff000, v68
	v_lshrrev_b32_e32 v0, 11, v0
	s_movk_i32 s0, 0x1800
	v_mad_u32_u24 v0, v0, s0, s0
	v_cmp_lt_i32_e32 vcc, s50, v68
	v_ashrrev_i32_e32 v69, 31, v68
	v_readlane_b32 s4, v254, 0
	v_or_b32_e32 v66, s27, v135
	v_cndmask_b32_e32 v160, 0, v0, vcc
	s_waitcnt vmcnt(4)
	v_lshlrev_b64 v[70:71], 12, v[68:69]
	v_readlane_b32 s5, v254, 1
	v_ashrrev_i32_e32 v67, 31, v66
	v_mov_b32_e32 v95, v1
	v_lshl_add_u64 v[72:73], s[4:5], 0, v[70:71]
	v_add_u32_e32 v70, v160, v66
	v_ashrrev_i32_e32 v71, 31, v70
	v_lshl_add_u64 v[70:71], v[70:71], 2, s[28:29]
	global_load_dword v69, v[70:71], off
	v_lshlrev_b64 v[70:71], 2, v[66:67]
	s_waitcnt vmcnt(4)
	v_lshl_add_u64 v[74:75], v[72:73], 0, v[70:71]
	v_mov_b32_e32 v109, v1
	v_mov_b32_e32 v111, v1
	v_lshl_add_u64 v[72:73], v[74:75], 0, v[94:95]
	v_mov_b32_e32 v97, v1
	v_mov_b32_e32 v99, v1
	v_mov_b32_e32 v101, v1
	v_mov_b32_e32 v103, v1
	v_mov_b32_e32 v105, v1
	v_mov_b32_e32 v107, v1
	s_waitcnt vmcnt(1)
	v_lshl_add_u64 v[88:89], v[74:75], 0, v[108:109]
	v_lshl_add_u64 v[144:145], v[74:75], 0, v[110:111]
	v_mov_b32_e32 v113, v1
	v_lshl_add_u64 v[76:77], v[74:75], 0, v[96:97]
	v_lshl_add_u64 v[78:79], v[74:75], 0, v[98:99]
	v_lshl_add_u64 v[80:81], v[74:75], 0, v[100:101]
	v_lshl_add_u64 v[82:83], v[74:75], 0, v[102:103]
	v_lshl_add_u64 v[84:85], v[74:75], 0, v[104:105]
	v_lshl_add_u64 v[86:87], v[74:75], 0, v[106:107]
	global_load_dword v67, v[72:73], off
	global_load_dword v161, v[76:77], off
	global_load_dword v162, v[78:79], off
	global_load_dword v163, v[80:81], off
	global_load_dword v164, v[82:83], off
	global_load_dword v165, v[84:85], off
	global_load_dword v166, v[86:87], off
	global_load_dword v167, v[88:89], off
	global_load_dword v168, v[144:145], off
	v_lshl_add_u64 v[146:147], v[74:75], 0, v[112:113]
	v_mov_b32_e32 v115, v1
	global_load_dword v169, v[146:147], off
	v_lshl_add_u64 v[148:149], v[74:75], 0, v[114:115]
	v_mov_b32_e32 v117, v1
	global_load_dword v170, v[148:149], off
	v_lshl_add_u64 v[150:151], v[74:75], 0, v[116:117]
	v_mov_b32_e32 v119, v1
	global_load_dword v171, v[150:151], off
	v_lshl_add_u64 v[152:153], v[74:75], 0, v[118:119]
	v_mov_b32_e32 v121, v1
	global_load_dword v172, v[152:153], off
	v_lshl_add_u64 v[154:155], v[74:75], 0, v[120:121]
	v_mov_b32_e32 v123, v1
	global_load_dword v173, v[154:155], off
	global_load_dword v177, v[72:73], off offset:128
	v_lshl_add_u64 v[156:157], v[74:75], 0, v[122:123]
	v_mov_b32_e32 v125, v1
	global_load_dword v174, v[156:157], off
	v_lshl_add_u64 v[158:159], v[74:75], 0, v[124:125]
	global_load_dword v175, v[158:159], off
	v_add_f32_e32 v50, 0, v50
	v_add_f32_e32 v51, 0, v51
	v_add_f32_e32 v52, 0, v52
	v_add_f32_e32 v53, 0, v53
	v_add_f32_e32 v54, 0, v54
	v_add_f32_e32 v55, 0, v55
	v_add_f32_e32 v56, 0, v56
	v_add_f32_e32 v57, 0, v57
	v_or_b32_e32 v176, 32, v66
	s_mov_b64 s[0:1], 0x80
	v_add_f32_e32 v34, 0, v34
	v_add_f32_e32 v35, 0, v35
	v_add_f32_e32 v36, 0, v36
	v_add_f32_e32 v37, 0, v37
	v_add_f32_e32 v41, 0, v41
	v_add_f32_e32 v38, 0, v38
	v_add_f32_e32 v39, 0, v39
	v_add_f32_e32 v40, 0, v40
	v_add_f32_e32 v18, 0, v18
	v_add_f32_e32 v19, 0, v19
	v_add_f32_e32 v20, 0, v20
	v_add_f32_e32 v21, 0, v21
	v_add_f32_e32 v2, 0, v2
	s_add_i32 s23, s23, s22
	v_add_f32_e32 v3, 0, v3
	v_add_f32_e32 v4, 0, v4
	v_add_f32_e32 v5, 0, v5
	s_cmpk_gt_i32 s23, 0xff
	v_readlane_b32 s6, v254, 2
	v_readlane_b32 s7, v254, 3
	v_readlane_b32 s8, v254, 4
	v_readlane_b32 s9, v254, 5
	v_readlane_b32 s10, v254, 6
	v_readlane_b32 s11, v254, 7
	v_readlane_b32 s12, v254, 8
	v_readlane_b32 s13, v254, 9
	v_readlane_b32 s14, v254, 10
	v_readlane_b32 s15, v254, 11
	v_readlane_b32 s16, v254, 12
	v_readlane_b32 s17, v254, 13
	v_readlane_b32 s18, v254, 14
	v_readlane_b32 s19, v254, 15
	s_waitcnt vmcnt(16)
	v_fmac_f32_e32 v67, v50, v69
	v_add_f32_e32 v50, 0, v58
	s_waitcnt vmcnt(15)
	v_fmac_f32_e32 v161, v51, v69
	s_waitcnt vmcnt(14)
	v_fmac_f32_e32 v162, v52, v69
	s_waitcnt vmcnt(13)
	v_fmac_f32_e32 v163, v53, v69
	s_waitcnt vmcnt(12)
	v_fmac_f32_e32 v164, v54, v69
	s_waitcnt vmcnt(11)
	v_fmac_f32_e32 v165, v55, v69
	s_waitcnt vmcnt(10)
	v_fmac_f32_e32 v166, v56, v69
	s_waitcnt vmcnt(8)
	v_fmac_f32_e32 v168, v50, v69
	v_add_f32_e32 v50, 0, v59
	v_fmac_f32_e32 v167, v57, v69
	s_waitcnt vmcnt(7)
	v_fmac_f32_e32 v169, v50, v69
	v_add_f32_e32 v50, 0, v60
	global_store_dword v[72:73], v67, off
	global_store_dword v[76:77], v161, off
	global_store_dword v[78:79], v162, off
	global_store_dword v[80:81], v163, off
	global_store_dword v[82:83], v164, off
	global_store_dword v[84:85], v165, off
	global_store_dword v[86:87], v166, off
	global_store_dword v[88:89], v167, off
	s_waitcnt vmcnt(14)
	v_fmac_f32_e32 v170, v50, v69
	v_add_f32_e32 v50, 0, v61
	v_add_f32_e32 v67, 0, v65
	s_waitcnt vmcnt(13)
	v_fmac_f32_e32 v171, v50, v69
	v_add_f32_e32 v50, 0, v62
	global_store_dword v[144:145], v168, off
	s_waitcnt vmcnt(13)
	v_fmac_f32_e32 v172, v50, v69
	v_add_f32_e32 v50, 0, v63
	global_store_dword v[146:147], v169, off
	s_waitcnt vmcnt(13)
	v_fmac_f32_e32 v173, v50, v69
	v_add_f32_e32 v50, 0, v64
	global_store_dword v[148:149], v170, off
	global_store_dword v[150:151], v171, off
	s_waitcnt vmcnt(13)
	v_fmac_f32_e32 v174, v50, v69
	v_lshl_add_u64 v[50:51], v[74:75], 0, s[0:1]
	v_add_u32_e32 v74, v160, v176
	global_store_dword v[152:153], v172, off
	global_store_dword v[154:155], v173, off
	global_store_dword v[156:157], v174, off
	v_lshl_add_u64 v[52:53], v[50:51], 0, v[96:97]
	s_waitcnt vmcnt(15)
	v_fmac_f32_e32 v175, v67, v69
	v_ashrrev_i32_e32 v75, 31, v74
	v_lshl_add_u64 v[54:55], v[50:51], 0, v[98:99]
	v_lshl_add_u64 v[56:57], v[50:51], 0, v[100:101]
	v_lshl_add_u64 v[58:59], v[50:51], 0, v[102:103]
	v_lshl_add_u64 v[60:61], v[50:51], 0, v[104:105]
	v_lshl_add_u64 v[62:63], v[50:51], 0, v[106:107]
	v_lshl_add_u64 v[64:65], v[50:51], 0, v[108:109]
	global_load_dword v88, v[52:53], off
	global_load_dword v89, v[54:55], off
	global_load_dword v144, v[56:57], off
	global_load_dword v145, v[58:59], off
	global_load_dword v146, v[60:61], off
	global_load_dword v147, v[62:63], off
	global_load_dword v148, v[64:65], off
	v_lshl_add_u64 v[74:75], v[74:75], 2, s[28:29]
	global_store_dword v[158:159], v175, off
	global_load_dword v67, v[74:75], off
	v_lshl_add_u64 v[74:75], v[50:51], 0, v[110:111]
	global_load_dword v69, v[74:75], off
	v_lshl_add_u64 v[76:77], v[50:51], 0, v[112:113]
	global_load_dword v149, v[76:77], off
	v_lshl_add_u64 v[78:79], v[50:51], 0, v[114:115]
	global_load_dword v150, v[78:79], off
	v_lshl_add_u64 v[80:81], v[50:51], 0, v[116:117]
	global_load_dword v151, v[80:81], off
	v_lshl_add_u64 v[82:83], v[50:51], 0, v[118:119]
	global_load_dword v152, v[82:83], off
	v_lshl_add_u64 v[84:85], v[50:51], 0, v[120:121]
	global_load_dword v153, v[84:85], off
	v_lshl_add_u64 v[86:87], v[50:51], 0, v[122:123]
	global_load_dword v154, v[86:87], off
	v_lshl_add_u64 v[50:51], v[50:51], 0, v[124:125]
	global_load_dword v155, v[50:51], off
	s_waitcnt vmcnt(8)
	v_fmac_f32_e32 v177, v34, v67
	v_add_f32_e32 v34, 0, v42
	s_waitcnt vmcnt(7)
	v_fmac_f32_e32 v69, v34, v67
	v_add_f32_e32 v34, 0, v43
	s_waitcnt vmcnt(6)
	v_fmac_f32_e32 v149, v34, v67
	v_add_f32_e32 v34, 0, v44
	s_waitcnt vmcnt(5)
	v_fmac_f32_e32 v150, v34, v67
	v_add_f32_e32 v34, 0, v45
	s_waitcnt vmcnt(4)
	v_fmac_f32_e32 v151, v34, v67
	v_add_f32_e32 v34, 0, v46
	s_waitcnt vmcnt(3)
	v_fmac_f32_e32 v152, v34, v67
	v_add_f32_e32 v34, 0, v47
	s_waitcnt vmcnt(2)
	v_fmac_f32_e32 v153, v34, v67
	v_add_f32_e32 v34, 0, v48
	s_waitcnt vmcnt(1)
	v_fmac_f32_e32 v154, v34, v67
	v_add_f32_e32 v34, 0, v49
	s_waitcnt vmcnt(0)
	v_fmac_f32_e32 v155, v34, v67
	v_or_b32_e32 v34, 32, v68
	v_cmp_lt_i32_e32 vcc, s50, v34
	v_fmac_f32_e32 v88, v35, v67
	v_ashrrev_i32_e32 v35, 31, v34
	v_cndmask_b32_e32 v0, 0, v0, vcc
	v_fmac_f32_e32 v89, v36, v67
	v_lshlrev_b64 v[34:35], 12, v[34:35]
	v_add_u32_e32 v36, v0, v66
	v_fmac_f32_e32 v144, v37, v67
	v_fmac_f32_e32 v148, v41, v67
	v_lshl_add_u64 v[34:35], s[4:5], 0, v[34:35]
	v_ashrrev_i32_e32 v37, 31, v36
	v_fmac_f32_e32 v145, v38, v67
	v_fmac_f32_e32 v146, v39, v67
	v_fmac_f32_e32 v147, v40, v67
	global_store_dword v[72:73], v177, off offset:128
	global_store_dword v[52:53], v88, off
	global_store_dword v[54:55], v89, off
	global_store_dword v[56:57], v144, off
	global_store_dword v[58:59], v145, off
	global_store_dword v[60:61], v146, off
	global_store_dword v[62:63], v147, off
	global_store_dword v[64:65], v148, off
	global_store_dword v[74:75], v69, off
	global_store_dword v[76:77], v149, off
	global_store_dword v[78:79], v150, off
	global_store_dword v[80:81], v151, off
	global_store_dword v[82:83], v152, off
	global_store_dword v[84:85], v153, off
	global_store_dword v[86:87], v154, off
	global_store_dword v[50:51], v155, off
	v_lshl_add_u64 v[36:37], v[36:37], 2, s[28:29]
	v_lshl_add_u64 v[34:35], v[34:35], 0, v[70:71]
	global_load_dword v68, v[36:37], off
	v_lshl_add_u64 v[36:37], v[34:35], 0, v[94:95]
	v_lshl_add_u64 v[44:45], v[34:35], 0, v[102:103]
	v_lshl_add_u64 v[38:39], v[34:35], 0, v[96:97]
	v_lshl_add_u64 v[40:41], v[34:35], 0, v[98:99]
	v_lshl_add_u64 v[42:43], v[34:35], 0, v[100:101]
	global_load_dword v69, v[36:37], off
	global_load_dword v70, v[38:39], off
	global_load_dword v71, v[40:41], off
	global_load_dword v72, v[42:43], off
	global_load_dword v73, v[44:45], off
	v_lshl_add_u64 v[46:47], v[34:35], 0, v[104:105]
	global_load_dword v74, v[46:47], off
	v_lshl_add_u64 v[48:49], v[34:35], 0, v[106:107]
	global_load_dword v75, v[48:49], off
	v_lshl_add_u64 v[50:51], v[34:35], 0, v[108:109]
	global_load_dword v76, v[50:51], off
	v_lshl_add_u64 v[52:53], v[34:35], 0, v[110:111]
	global_load_dword v77, v[52:53], off
	v_lshl_add_u64 v[54:55], v[34:35], 0, v[112:113]
	global_load_dword v78, v[54:55], off
	v_lshl_add_u64 v[56:57], v[34:35], 0, v[114:115]
	global_load_dword v79, v[56:57], off
	global_load_dword v85, v[36:37], off offset:128
	v_lshl_add_u64 v[58:59], v[34:35], 0, v[116:117]
	global_load_dword v80, v[58:59], off
	v_lshl_add_u64 v[60:61], v[34:35], 0, v[118:119]
	global_load_dword v81, v[60:61], off
	v_lshl_add_u64 v[62:63], v[34:35], 0, v[120:121]
	global_load_dword v82, v[62:63], off
	v_lshl_add_u64 v[64:65], v[34:35], 0, v[122:123]
	global_load_dword v83, v[64:65], off
	v_lshl_add_u64 v[66:67], v[34:35], 0, v[124:125]
	global_load_dword v84, v[66:67], off
	s_waitcnt vmcnt(16)
	v_fmac_f32_e32 v69, v18, v68
	v_add_f32_e32 v18, 0, v22
	s_waitcnt vmcnt(15)
	v_fmac_f32_e32 v70, v19, v68
	s_waitcnt vmcnt(14)
	v_fmac_f32_e32 v71, v20, v68
	s_waitcnt vmcnt(12)
	v_fmac_f32_e32 v73, v18, v68
	v_add_f32_e32 v18, 0, v23
	s_waitcnt vmcnt(11)
	v_fmac_f32_e32 v74, v18, v68
	v_add_f32_e32 v18, 0, v24
	s_waitcnt vmcnt(10)
	v_fmac_f32_e32 v75, v18, v68
	v_add_f32_e32 v18, 0, v25
	s_waitcnt vmcnt(9)
	v_fmac_f32_e32 v76, v18, v68
	v_add_f32_e32 v18, 0, v26
	s_waitcnt vmcnt(8)
	v_fmac_f32_e32 v77, v18, v68
	v_add_f32_e32 v18, 0, v27
	s_waitcnt vmcnt(7)
	v_fmac_f32_e32 v78, v18, v68
	v_add_f32_e32 v18, 0, v28
	s_waitcnt vmcnt(6)
	v_fmac_f32_e32 v79, v18, v68
	v_add_f32_e32 v18, 0, v29
	v_fmac_f32_e32 v72, v21, v68
	s_waitcnt vmcnt(4)
	v_fmac_f32_e32 v80, v18, v68
	v_add_f32_e32 v18, 0, v30
	s_waitcnt vmcnt(3)
	v_fmac_f32_e32 v81, v18, v68
	v_add_f32_e32 v18, 0, v31
	s_waitcnt vmcnt(2)
	v_fmac_f32_e32 v82, v18, v68
	v_add_f32_e32 v18, 0, v32
	global_store_dword v[36:37], v69, off
	global_store_dword v[38:39], v70, off
	global_store_dword v[40:41], v71, off
	global_store_dword v[42:43], v72, off
	s_waitcnt vmcnt(5)
	v_fmac_f32_e32 v83, v18, v68
	v_add_f32_e32 v38, 0, v33
	v_lshl_add_u64 v[18:19], v[34:35], 0, s[0:1]
	v_add_u32_e32 v34, v0, v176
	global_store_dword v[44:45], v73, off
	global_store_dword v[46:47], v74, off
	global_store_dword v[48:49], v75, off
	global_store_dword v[50:51], v76, off
	global_store_dword v[52:53], v77, off
	global_store_dword v[54:55], v78, off
	global_store_dword v[56:57], v79, off
	global_store_dword v[58:59], v80, off
	global_store_dword v[60:61], v81, off
	global_store_dword v[62:63], v82, off
	global_store_dword v[64:65], v83, off
	v_lshl_add_u64 v[20:21], v[18:19], 0, v[96:97]
	s_waitcnt vmcnt(15)
	v_fmac_f32_e32 v84, v38, v68
	v_ashrrev_i32_e32 v35, 31, v34
	v_lshl_add_u64 v[22:23], v[18:19], 0, v[98:99]
	v_lshl_add_u64 v[24:25], v[18:19], 0, v[100:101]
	v_lshl_add_u64 v[26:27], v[18:19], 0, v[102:103]
	v_lshl_add_u64 v[28:29], v[18:19], 0, v[104:105]
	v_lshl_add_u64 v[30:31], v[18:19], 0, v[106:107]
	v_lshl_add_u64 v[32:33], v[18:19], 0, v[108:109]
	global_load_dword v50, v[20:21], off
	global_load_dword v51, v[22:23], off
	global_load_dword v52, v[24:25], off
	global_load_dword v53, v[26:27], off
	global_load_dword v54, v[28:29], off
	global_load_dword v55, v[30:31], off
	global_load_dword v56, v[32:33], off
	v_lshl_add_u64 v[34:35], v[34:35], 2, s[28:29]
	global_store_dword v[66:67], v84, off
	global_load_dword v0, v[34:35], off
	v_lshl_add_u64 v[34:35], v[18:19], 0, v[110:111]
	global_load_dword v57, v[34:35], off
	v_lshl_add_u64 v[38:39], v[18:19], 0, v[112:113]
	global_load_dword v58, v[38:39], off
	v_lshl_add_u64 v[40:41], v[18:19], 0, v[114:115]
	global_load_dword v59, v[40:41], off
	v_lshl_add_u64 v[42:43], v[18:19], 0, v[116:117]
	global_load_dword v60, v[42:43], off
	v_lshl_add_u64 v[44:45], v[18:19], 0, v[118:119]
	global_load_dword v61, v[44:45], off
	v_lshl_add_u64 v[46:47], v[18:19], 0, v[120:121]
	global_load_dword v62, v[46:47], off
	v_lshl_add_u64 v[48:49], v[18:19], 0, v[122:123]
	global_load_dword v63, v[48:49], off
	v_lshl_add_u64 v[18:19], v[18:19], 0, v[124:125]
	global_load_dword v64, v[18:19], off
	s_waitcnt vmcnt(8)
	v_fmac_f32_e32 v85, v2, v0
	v_add_f32_e32 v2, 0, v6
	v_fmac_f32_e32 v53, v2, v0
	v_add_f32_e32 v2, 0, v7
	v_fmac_f32_e32 v54, v2, v0
	v_add_f32_e32 v2, 0, v8
	v_fmac_f32_e32 v55, v2, v0
	v_add_f32_e32 v2, 0, v9
	v_fmac_f32_e32 v56, v2, v0
	v_add_f32_e32 v2, 0, v10
	s_waitcnt vmcnt(7)
	v_fmac_f32_e32 v57, v2, v0
	v_add_f32_e32 v2, 0, v11
	s_waitcnt vmcnt(6)
	v_fmac_f32_e32 v58, v2, v0
	v_add_f32_e32 v2, 0, v12
	s_waitcnt vmcnt(5)
	v_fmac_f32_e32 v59, v2, v0
	v_add_f32_e32 v2, 0, v13
	s_waitcnt vmcnt(4)
	v_fmac_f32_e32 v60, v2, v0
	v_add_f32_e32 v2, 0, v14
	s_waitcnt vmcnt(3)
	v_fmac_f32_e32 v61, v2, v0
	v_add_f32_e32 v2, 0, v15
	s_waitcnt vmcnt(2)
	v_fmac_f32_e32 v62, v2, v0
	v_add_f32_e32 v2, 0, v16
	s_waitcnt vmcnt(1)
	v_fmac_f32_e32 v63, v2, v0
	v_add_f32_e32 v2, 0, v17
	s_waitcnt vmcnt(0)
	v_fmac_f32_e32 v64, v2, v0
	v_fmac_f32_e32 v50, v3, v0
	v_fmac_f32_e32 v51, v4, v0
	v_fmac_f32_e32 v52, v5, v0
	global_store_dword v[36:37], v85, off offset:128
	global_store_dword v[20:21], v50, off
	global_store_dword v[22:23], v51, off
	global_store_dword v[24:25], v52, off
	global_store_dword v[26:27], v53, off
	global_store_dword v[28:29], v54, off
	global_store_dword v[30:31], v55, off
	global_store_dword v[32:33], v56, off
	global_store_dword v[34:35], v57, off
	global_store_dword v[38:39], v58, off
	global_store_dword v[40:41], v59, off
	global_store_dword v[42:43], v60, off
	global_store_dword v[44:45], v61, off
	global_store_dword v[46:47], v62, off
	global_store_dword v[48:49], v63, off
	global_store_dword v[18:19], v64, off
	s_cbranch_scc0 .LBB0_954
